# attention row-max trees: canonicalising self-max copies removed (readers take the MFMA result directly), hazard pads re-derived
# speedup vs baseline: 1.0390x; 1.0071x over previous
.LBB0_839:
	s_or_b64 exec, exec, s[0:1]
	v_mad_u32_u24 v37, v116, s11, 0
	v_add_u32_e32 v163, v37, v48
	ds_read_b128 v[0:3], v163
	ds_read_b128 v[16:19], v163 offset:0x1a00
	ds_read_b128 v[38:41], v163 offset:32
	ds_read_b128 v[42:45], v163 offset:0x1a20
	ds_read_b128 v[50:53], v163 offset:64
	ds_read_b128 v[54:57], v163 offset:0x1a40
	ds_read_b128 v[58:61], v163 offset:96
	ds_read_b128 v[62:65], v163 offset:0x1a60
	ds_read_b128 v[68:71], v163 offset:128
	ds_read_b128 v[72:75], v163 offset:0x1a80
	ds_read_b128 v[118:121], v163 offset:160
	ds_read_b128 v[122:125], v163 offset:0x1aa0
	s_waitcnt lgkmcnt(0)
	s_movk_i32 s0, 0xffb8
	v_mfma_f32_32x32x16_bf16 v[0:15], v[0:3], v[100:103], 0
	v_lshlrev_b32_e32 v117, 3, v36
	v_mad_i32_i24 v49, v116, s0, v37
	v_add3_u32 v162, v49, v117, s87
	v_mfma_f32_32x32x16_bf16 v[16:31], v[16:19], v[100:103], 0
	v_mfma_f32_32x32x16_bf16 v[0:15], v[38:41], v[96:99], v[0:15]
	v_mfma_f32_32x32x16_bf16 v[16:31], v[42:45], v[96:99], v[16:31]
	v_mfma_f32_32x32x16_bf16 v[0:15], v[50:53], v[92:95], v[0:15]
	v_mfma_f32_32x32x16_bf16 v[16:31], v[54:57], v[92:95], v[16:31]
	v_mfma_f32_32x32x16_bf16 v[0:15], v[58:61], v[88:91], v[0:15]
	v_mfma_f32_32x32x16_bf16 v[16:31], v[62:65], v[88:91], v[16:31]
	v_mfma_f32_32x32x16_bf16 v[0:15], v[68:71], v[84:87], v[0:15]
	v_mfma_f32_32x32x16_bf16 v[16:31], v[72:75], v[84:87], v[16:31]
	v_mfma_f32_32x32x16_bf16 v[16:31], v[122:125], v[80:83], v[16:31]
	ds_read_b64 v[68:69], v162
	ds_read_b64 v[70:71], v162 offset:16
	ds_read_b64 v[72:73], v162 offset:32
	ds_read_b64 v[74:75], v162 offset:48
	ds_read_b64 v[144:145], v162 offset:64
	ds_read_b64 v[146:147], v162 offset:80
	ds_read_b64 v[134:135], v162 offset:96
	ds_read_b64 v[136:137], v162 offset:112
	ds_read_b64 v[130:131], v162 offset:0x1100
	ds_read_b64 v[132:133], v162 offset:0x1110
	ds_read_b64 v[126:127], v162 offset:0x1120
	ds_read_b64 v[128:129], v162 offset:0x1130
	ds_read_b64 v[122:123], v162 offset:0x1140
	ds_read_b64 v[124:125], v162 offset:0x1150
	ds_read_b64 v[36:37], v162 offset:0x1160
	ds_read_b64 v[38:39], v162 offset:0x1170
	s_nop 0
	s_waitcnt lgkmcnt(0)
	s_waitcnt vmcnt(0)
	ds_write_b128 v158, v[32:35] offset:32768
	v_mfma_f32_32x32x16_bf16 v[0:15], v[118:121], v[80:83], v[0:15]
	s_nop 8
	s_nop 2
	v_max_f32_e32 v40, v0, v16
	v_max_f32_e32 v41, v1, v17
	v_max_f32_e32 v42, v3, v19
	v_max3_f32 v42, v2, v18, v42
	v_max3_f32 v40, v40, v41, v42
	v_max_f32_e32 v41, v5, v21
	v_max_f32_e32 v42, v7, v23
	v_max3_f32 v41, v4, v20, v41
	v_max3_f32 v42, v6, v22, v42
	v_max3_f32 v40, v40, v41, v42
	v_max_f32_e32 v41, v9, v25
	v_max_f32_e32 v42, v11, v27
	v_max3_f32 v41, v8, v24, v41
	v_max3_f32 v42, v10, v26, v42
	v_max3_f32 v40, v40, v41, v42
	v_max_f32_e32 v41, v13, v29
	v_max_f32_e32 v42, v15, v31
	v_max3_f32 v41, v12, v28, v41
	v_max3_f32 v42, v14, v30, v42
	v_max3_f32 v40, v40, v41, v42
	v_mov_b32_e32 v41, v40
	s_nop 1
	v_permlane32_swap_b32_e32 v40, v41
	v_max_f32_e32 v118, v40, v41
	v_sub_f32_e32 v0, v0, v118
	v_sub_f32_e32 v1, v1, v118
	v_sub_f32_e32 v2, v2, v118
	v_sub_f32_e32 v3, v3, v118
	v_sub_f32_e32 v4, v4, v118
	v_sub_f32_e32 v5, v5, v118
	v_sub_f32_e32 v6, v6, v118
	v_sub_f32_e32 v7, v7, v118
	v_exp_f32_e32 v40, v0
	v_exp_f32_e32 v41, v1
	v_exp_f32_e32 v44, v2
	v_exp_f32_e32 v45, v3
	v_exp_f32_e32 v50, v4
	v_exp_f32_e32 v51, v5
	v_exp_f32_e32 v54, v6
	v_exp_f32_e32 v55, v7
	v_sub_f32_e32 v16, v16, v118
	v_sub_f32_e32 v17, v17, v118
	v_sub_f32_e32 v18, v18, v118
	v_sub_f32_e32 v19, v19, v118
	v_sub_f32_e32 v8, v8, v118
	v_sub_f32_e32 v9, v9, v118
	v_sub_f32_e32 v10, v10, v118
	v_sub_f32_e32 v11, v11, v118
	v_sub_f32_e32 v12, v12, v118
	v_exp_f32_e32 v42, v16
	v_exp_f32_e32 v43, v17
	v_exp_f32_e32 v46, v18
	v_exp_f32_e32 v47, v19
	v_cvt_pk_bf16_f32 v16, v40, v41
	v_cvt_pk_bf16_f32 v17, v44, v45
	v_cvt_pk_bf16_f32 v18, v50, v51
	v_cvt_pk_bf16_f32 v19, v54, v55
	v_sub_f32_e32 v65, v13, v118
	v_sub_f32_e32 v67, v14, v118
	v_sub_f32_e32 v76, v15, v118
	v_exp_f32_e32 v58, v8
	v_exp_f32_e32 v59, v9
	v_exp_f32_e32 v62, v10
	v_exp_f32_e32 v63, v11
	v_exp_f32_e32 v64, v12
	v_mfma_f32_32x32x16_bf16 v[0:15], v[68:71], v[16:19], 0
	v_exp_f32_e32 v65, v65
	v_exp_f32_e32 v70, v67
	v_exp_f32_e32 v71, v76
	v_sub_f32_e32 v20, v20, v118
	v_sub_f32_e32 v21, v21, v118
	v_sub_f32_e32 v22, v22, v118
	v_sub_f32_e32 v23, v23, v118
	v_sub_f32_e32 v24, v24, v118
	v_sub_f32_e32 v25, v25, v118
	v_sub_f32_e32 v26, v26, v118
	v_sub_f32_e32 v27, v27, v118
	v_sub_f32_e32 v28, v28, v118
	v_sub_f32_e32 v29, v29, v118
	v_sub_f32_e32 v30, v30, v118
	v_sub_f32_e32 v31, v31, v118
	v_cvt_pk_bf16_f32 v148, v58, v59
	v_cvt_pk_bf16_f32 v149, v62, v63
	v_cvt_pk_bf16_f32 v150, v64, v65
	v_cvt_pk_bf16_f32 v151, v70, v71
	v_exp_f32_e32 v52, v20
	v_exp_f32_e32 v53, v21
	v_exp_f32_e32 v56, v22
	v_exp_f32_e32 v57, v23
	v_exp_f32_e32 v60, v24
	v_exp_f32_e32 v61, v25
	v_mfma_f32_32x32x16_bf16 v[0:15], v[72:75], v[148:151], v[0:15]
	v_exp_f32_e32 v74, v26
	v_exp_f32_e32 v75, v27
	v_exp_f32_e32 v72, v28
	v_exp_f32_e32 v73, v29
	v_exp_f32_e32 v76, v30
	v_exp_f32_e32 v77, v31
	v_cvt_pk_bf16_f32 v152, v42, v43
	v_mfma_f32_32x32x16_bf16 v[16:31], v[130:133], v[16:19], 0
	v_cvt_pk_bf16_f32 v153, v46, v47
	v_cvt_pk_bf16_f32 v154, v52, v53
	v_cvt_pk_bf16_f32 v155, v56, v57
	v_mfma_f32_32x32x16_bf16 v[16:31], v[126:129], v[148:151], v[16:31]
	s_nop 0
	v_mfma_f32_32x32x16_bf16 v[0:15], v[144:147], v[152:155], v[0:15]
	v_cvt_pk_bf16_f32 v144, v60, v61
	v_cvt_pk_bf16_f32 v145, v74, v75
	v_cvt_pk_bf16_f32 v146, v72, v73
	v_cvt_pk_bf16_f32 v147, v76, v77
	v_mfma_f32_32x32x16_bf16 v[16:31], v[122:125], v[152:155], v[16:31]
	s_nop 0
	v_mfma_f32_32x32x16_bf16 v[0:15], v[134:137], v[144:147], v[0:15]
	v_mfma_f32_32x32x16_bf16 v[16:31], v[36:39], v[144:147], v[16:31]
	s_and_saveexec_b64 s[0:1], s[2:3]
	ds_write_b128 v157, v[108:111] offset:32768
	s_or_b64 exec, exec, s[0:1]
	v_add_u32_e32 v160, 0xb400, v66
	s_and_saveexec_b64 s[0:1], s[4:5]
	s_cbranch_execz .LBB0_843
	v_perm_b32 v32, v104, v112, s85
	v_perm_b32 v33, v104, v112, s86
	ds_write2_b32 v160, v32, v33 offset1:34
	v_perm_b32 v32, v105, v113, s85
	v_perm_b32 v33, v105, v113, s86
	ds_write2_b32 v160, v32, v33 offset0:68 offset1:102
	v_perm_b32 v32, v106, v114, s85
	v_perm_b32 v33, v106, v114, s86
	ds_write2_b32 v160, v32, v33 offset0:136 offset1:170
	v_perm_b32 v32, v107, v115, s85
	v_perm_b32 v33, v107, v115, s86
	ds_write2_b32 v160, v32, v33 offset0:204 offset1:238

.LBB0_847:
	s_or_b64 exec, exec, s[0:1]
	v_pk_add_f32 v[32:33], v[40:41], 0 op_sel_hi:[1,0]
	s_movk_i32 s0, 0x48
	v_pk_add_f32 v[32:33], v[42:43], v[32:33]
	v_mad_u32_u24 v138, v116, s0, v49
	v_pk_add_f32 v[32:33], v[44:45], v[32:33]
	s_mov_b32 s0, 0x8000
	v_pk_add_f32 v[32:33], v[46:47], v[32:33]
	v_add3_u32 v161, v138, v48, s0
	v_pk_add_f32 v[32:33], v[50:51], v[32:33]
	s_mov_b32 s0, 0xb400
	v_pk_add_f32 v[32:33], v[52:53], v[32:33]
	s_nop 0
	v_pk_add_f32 v[32:33], v[54:55], v[32:33]
	s_nop 0
	v_pk_add_f32 v[32:33], v[56:57], v[32:33]
	s_nop 0
	v_pk_add_f32 v[32:33], v[58:59], v[32:33]
	s_nop 0
	v_pk_add_f32 v[32:33], v[60:61], v[32:33]
	s_nop 0
	v_pk_add_f32 v[32:33], v[62:63], v[32:33]
	s_nop 0
	v_pk_add_f32 v[32:33], v[74:75], v[32:33]
	s_nop 0
	v_pk_add_f32 v[32:33], v[64:65], v[32:33]
	s_nop 0
	v_pk_add_f32 v[32:33], v[72:73], v[32:33]
	s_nop 0
	v_pk_add_f32 v[32:33], v[70:71], v[32:33]
	s_nop 0
	v_pk_add_f32 v[32:33], v[76:77], v[32:33]
	s_nop 0
	v_pk_add_f32 v[32:33], v[32:33], v[32:33] op_sel:[0,1] op_sel_hi:[1,0]
	s_nop 0
	v_mov_b32_e32 v33, v118
	v_pk_add_f32 v[152:153], v[32:33], 0 op_sel_hi:[1,0]
	ds_read_b128 v[70:73], v161
	ds_read_b128 v[74:77], v161 offset:0x1a00
	ds_read_b128 v[118:121], v161 offset:32
	ds_read_b128 v[122:125], v161 offset:0x1a20
	ds_read_b128 v[126:129], v161 offset:64
	ds_read_b128 v[130:133], v161 offset:0x1a40
	ds_read_b128 v[134:137], v161 offset:96
	ds_read_b128 v[144:147], v161 offset:0x1a60
	ds_read_b128 v[148:151], v161 offset:128
	ds_read_b128 v[166:169], v161 offset:0x1a80
	ds_read_b128 v[170:173], v161 offset:160
	ds_read_b128 v[174:177], v161 offset:0x1aa0
	s_waitcnt lgkmcnt(0)
	s_nop 0
	v_xor_b32_e32 v32, 0x80000000, v153
	v_mov_b32_e32 v33, v32
	v_mov_b32_e32 v34, v32
	v_mov_b32_e32 v35, v32
	v_mov_b32_e32 v36, v32
	v_mov_b32_e32 v37, v32
	v_mov_b32_e32 v38, v32
	v_mov_b32_e32 v39, v32
	v_mov_b32_e32 v40, v32
	v_mov_b32_e32 v41, v32
	v_mov_b32_e32 v42, v32
	v_mov_b32_e32 v43, v32
	v_mov_b32_e32 v44, v32
	v_mov_b32_e32 v45, v32
	v_mov_b32_e32 v46, v32
	v_mov_b32_e32 v47, v32
	s_nop 1
	v_mfma_f32_32x32x16_bf16 v[50:65], v[70:73], v[100:103], v[32:47]
	v_mov_b64_e32 v[48:49], v[46:47]
	s_nop 5
	v_mov_b64_e32 v[46:47], v[44:45]
	v_mov_b64_e32 v[44:45], v[42:43]
	v_mov_b64_e32 v[42:43], v[40:41]
	v_mov_b64_e32 v[40:41], v[38:39]
	v_mov_b64_e32 v[38:39], v[36:37]
	v_mov_b64_e32 v[36:37], v[34:35]
	v_mov_b64_e32 v[34:35], v[32:33]
	v_mfma_f32_32x32x16_bf16 v[50:65], v[118:121], v[96:99], v[50:65]
	v_mul_i32_i24_e32 v33, 0xffffffb8, v116
	v_add_u32_e32 v33, v138, v33
	v_add3_u32 v159, v33, v117, s0
	v_mfma_f32_32x32x16_bf16 v[34:49], v[74:77], v[100:103], v[34:49]
	v_mfma_f32_32x32x16_bf16 v[34:49], v[122:125], v[96:99], v[34:49]
	v_mfma_f32_32x32x16_bf16 v[50:65], v[126:129], v[92:95], v[50:65]
	v_mfma_f32_32x32x16_bf16 v[34:49], v[130:133], v[92:95], v[34:49]
	v_mfma_f32_32x32x16_bf16 v[50:65], v[134:137], v[88:91], v[50:65]
	ds_read_b64 v[136:137], v159
	ds_read_b64 v[138:139], v159 offset:16
	ds_read_b64 v[132:133], v159 offset:32
	ds_read_b64 v[134:135], v159 offset:48
	ds_read_b64 v[128:129], v159 offset:64
	ds_read_b64 v[130:131], v159 offset:80
	ds_read_b64 v[124:125], v159 offset:96
	ds_read_b64 v[126:127], v159 offset:112
	ds_read_b64 v[120:121], v159 offset:0x1100
	ds_read_b64 v[122:123], v159 offset:0x1110
	ds_read_b64 v[116:117], v159 offset:0x1120
	ds_read_b64 v[118:119], v159 offset:0x1130
	ds_read_b64 v[74:75], v159 offset:0x1140
	ds_read_b64 v[76:77], v159 offset:0x1150
	ds_read_b64 v[70:71], v159 offset:0x1160
	ds_read_b64 v[72:73], v159 offset:0x1170
	v_mfma_f32_32x32x16_bf16 v[34:49], v[144:147], v[88:91], v[34:49]
	v_mfma_f32_32x32x16_bf16 v[50:65], v[148:151], v[84:87], v[50:65]
	v_mfma_f32_32x32x16_bf16 v[34:49], v[166:169], v[84:87], v[34:49]
	v_mfma_f32_32x32x16_bf16 v[34:49], v[174:177], v[80:83], v[34:49]
	v_mfma_f32_32x32x16_bf16 v[50:65], v[170:173], v[80:83], v[50:65]
	s_nop 11
	v_max_f32_e32 v33, v50, v34
	v_max_f32_e32 v144, v51, v35
	v_max_f32_e32 v145, v53, v37
	v_max3_f32 v145, v52, v36, v145
	v_max3_f32 v33, v33, v144, v145
	v_max_f32_e32 v144, v55, v39
	v_max_f32_e32 v145, v57, v41
	v_max3_f32 v144, v54, v38, v144
	v_max3_f32 v145, v56, v40, v145
	v_max3_f32 v33, v33, v144, v145
	v_max_f32_e32 v144, v59, v43
	v_max_f32_e32 v145, v61, v45
	v_max3_f32 v144, v58, v42, v144
	v_max3_f32 v145, v60, v44, v145
	v_max3_f32 v33, v33, v144, v145
	v_max_f32_e32 v144, v63, v47
	v_max_f32_e32 v146, v65, v65
	v_max_f32_e32 v145, v146, v49
	v_max3_f32 v144, v62, v46, v144
	v_max3_f32 v145, v64, v48, v145
	v_max3_f32 v33, v33, v144, v145
	v_mov_b32_e32 v144, v33
	s_nop 1
	v_permlane32_swap_b32_e32 v33, v144
	v_max_f32_e32 v33, v33, v144
	v_cmp_lt_f32_e32 vcc, s80, v33
	s_cbranch_vccz .LBB0_849
	v_max_f32_e32 v144, 0, v33
	v_exp_f32_e64 v146, -v144
	v_add_f32_e32 v153, v153, v144
	v_xor_b32_e32 v32, 0x80000000, v153
	v_pk_add_f32 v[50:51], v[50:51], v[144:145] op_sel_hi:[1,0] neg_lo:[0,1] neg_hi:[0,1]
	v_pk_mul_f32 v[14:15], v[14:15], v[146:147] op_sel_hi:[1,0]
	v_pk_mul_f32 v[12:13], v[12:13], v[146:147] op_sel_hi:[1,0]
	v_pk_mul_f32 v[10:11], v[10:11], v[146:147] op_sel_hi:[1,0]
	v_pk_mul_f32 v[8:9], v[8:9], v[146:147] op_sel_hi:[1,0]
	v_pk_mul_f32 v[6:7], v[6:7], v[146:147] op_sel_hi:[1,0]
	v_pk_mul_f32 v[4:5], v[4:5], v[146:147] op_sel_hi:[1,0]
	v_pk_mul_f32 v[2:3], v[2:3], v[146:147] op_sel_hi:[1,0]
	v_pk_mul_f32 v[0:1], v[0:1], v[146:147] op_sel_hi:[1,0]
	v_pk_mul_f32 v[30:31], v[30:31], v[146:147] op_sel_hi:[1,0]
	v_pk_mul_f32 v[28:29], v[28:29], v[146:147] op_sel_hi:[1,0]
	v_pk_mul_f32 v[26:27], v[26:27], v[146:147] op_sel_hi:[1,0]
	v_pk_mul_f32 v[24:25], v[24:25], v[146:147] op_sel_hi:[1,0]
	v_pk_mul_f32 v[22:23], v[22:23], v[146:147] op_sel_hi:[1,0]
	v_pk_mul_f32 v[20:21], v[20:21], v[146:147] op_sel_hi:[1,0]
	v_pk_mul_f32 v[18:19], v[18:19], v[146:147] op_sel_hi:[1,0]
	v_pk_mul_f32 v[16:17], v[16:17], v[146:147] op_sel_hi:[1,0]
	v_pk_add_f32 v[34:35], v[34:35], v[144:145] op_sel_hi:[1,0] neg_lo:[0,1] neg_hi:[0,1]
	v_pk_add_f32 v[52:53], v[52:53], v[144:145] op_sel_hi:[1,0] neg_lo:[0,1] neg_hi:[0,1]
	v_pk_add_f32 v[36:37], v[36:37], v[144:145] op_sel_hi:[1,0] neg_lo:[0,1] neg_hi:[0,1]
	v_pk_add_f32 v[54:55], v[54:55], v[144:145] op_sel_hi:[1,0] neg_lo:[0,1] neg_hi:[0,1]
	v_pk_add_f32 v[38:39], v[38:39], v[144:145] op_sel_hi:[1,0] neg_lo:[0,1] neg_hi:[0,1]
	v_pk_add_f32 v[56:57], v[56:57], v[144:145] op_sel_hi:[1,0] neg_lo:[0,1] neg_hi:[0,1]
	v_pk_add_f32 v[40:41], v[40:41], v[144:145] op_sel_hi:[1,0] neg_lo:[0,1] neg_hi:[0,1]
	v_pk_add_f32 v[58:59], v[58:59], v[144:145] op_sel_hi:[1,0] neg_lo:[0,1] neg_hi:[0,1]
	v_pk_add_f32 v[42:43], v[42:43], v[144:145] op_sel_hi:[1,0] neg_lo:[0,1] neg_hi:[0,1]
	v_pk_add_f32 v[60:61], v[60:61], v[144:145] op_sel_hi:[1,0] neg_lo:[0,1] neg_hi:[0,1]
	v_pk_add_f32 v[44:45], v[44:45], v[144:145] op_sel_hi:[1,0] neg_lo:[0,1] neg_hi:[0,1]
	v_pk_add_f32 v[62:63], v[62:63], v[144:145] op_sel_hi:[1,0] neg_lo:[0,1] neg_hi:[0,1]
	v_pk_add_f32 v[46:47], v[46:47], v[144:145] op_sel_hi:[1,0] neg_lo:[0,1] neg_hi:[0,1]
	v_pk_add_f32 v[64:65], v[64:65], v[144:145] op_sel_hi:[1,0] neg_lo:[0,1] neg_hi:[0,1]
	v_pk_add_f32 v[48:49], v[48:49], v[144:145] op_sel_hi:[1,0] neg_lo:[0,1] neg_hi:[0,1]
	v_mul_f32_e32 v152, v152, v146

.LBB0_857:
	s_or_b64 exec, exec, s[0:1]
	v_pk_add_f32 v[50:51], v[50:51], 0 op_sel_hi:[1,0]
	v_mov_b32_e32 v33, v32
	v_pk_add_f32 v[50:51], v[144:145], v[50:51]
	v_mov_b32_e32 v34, v32
	v_pk_add_f32 v[50:51], v[52:53], v[50:51]
	v_mov_b32_e32 v35, v32
	v_pk_add_f32 v[50:51], v[146:147], v[50:51]
	v_mov_b32_e32 v36, v32
	v_pk_add_f32 v[50:51], v[54:55], v[50:51]
	v_mov_b32_e32 v37, v32
	v_pk_add_f32 v[50:51], v[148:149], v[50:51]
	v_mov_b32_e32 v38, v32
	v_pk_add_f32 v[50:51], v[56:57], v[50:51]
	v_mov_b32_e32 v39, v32
	v_pk_add_f32 v[50:51], v[150:151], v[50:51]
	v_mov_b32_e32 v40, v32
	v_pk_add_f32 v[50:51], v[58:59], v[50:51]
	v_mov_b32_e32 v41, v32
	v_pk_add_f32 v[50:51], v[154:155], v[50:51]
	v_mov_b32_e32 v42, v32
	v_pk_add_f32 v[50:51], v[60:61], v[50:51]
	v_mov_b32_e32 v43, v32
	v_pk_add_f32 v[50:51], v[134:135], v[50:51]
	v_mov_b32_e32 v44, v32
	v_pk_add_f32 v[50:51], v[62:63], v[50:51]
	v_mov_b32_e32 v45, v32
	v_pk_add_f32 v[50:51], v[132:133], v[50:51]
	v_mov_b32_e32 v46, v32
	v_pk_add_f32 v[50:51], v[64:65], v[50:51]
	v_mov_b32_e32 v47, v32
	v_pk_add_f32 v[48:49], v[48:49], v[50:51]
	s_nop 0
	v_add_f32_e32 v48, v48, v49
	v_add_f32_e32 v152, v152, v48
	ds_read_b128 v[48:51], v163
	ds_read_b128 v[120:123], v163 offset:0x1a00
	ds_read_b128 v[124:127], v163 offset:32
	ds_read_b128 v[128:131], v163 offset:0x1a20
	ds_read_b128 v[132:135], v163 offset:64
	ds_read_b128 v[136:139], v163 offset:0x1a40
	ds_read_b128 v[140:143], v163 offset:96
	ds_read_b128 v[144:147], v163 offset:0x1a60
	ds_read_b128 v[148:151], v163 offset:128
	ds_read_b128 v[164:167], v163 offset:0x1a80
	ds_read_b128 v[168:171], v163 offset:160
	ds_read_b128 v[172:175], v163 offset:0x1aa0
	s_waitcnt lgkmcnt(0)
	s_nop 0
	v_mfma_f32_32x32x16_bf16 v[64:79], v[48:51], v[100:103], v[32:47]
	v_mfma_f32_32x32x16_bf16 v[48:63], v[120:123], v[100:103], v[32:47]
	v_mfma_f32_32x32x16_bf16 v[64:79], v[124:127], v[96:99], v[64:79]
	v_mfma_f32_32x32x16_bf16 v[48:63], v[128:131], v[96:99], v[48:63]
	v_mfma_f32_32x32x16_bf16 v[64:79], v[132:135], v[92:95], v[64:79]
	v_mfma_f32_32x32x16_bf16 v[48:63], v[136:139], v[92:95], v[48:63]
	v_mfma_f32_32x32x16_bf16 v[64:79], v[140:143], v[88:91], v[64:79]
	v_mfma_f32_32x32x16_bf16 v[48:63], v[144:147], v[88:91], v[48:63]
	v_mfma_f32_32x32x16_bf16 v[64:79], v[148:151], v[84:87], v[64:79]
	ds_read_b64 v[148:149], v162
	ds_read_b64 v[150:151], v162 offset:16
	ds_read_b64 v[144:145], v162 offset:32
	ds_read_b64 v[146:147], v162 offset:48
	ds_read_b64 v[140:141], v162 offset:64
	ds_read_b64 v[142:143], v162 offset:80
	ds_read_b64 v[136:137], v162 offset:96
	ds_read_b64 v[138:139], v162 offset:112
	ds_read_b64 v[132:133], v162 offset:0x1100
	ds_read_b64 v[134:135], v162 offset:0x1110
	ds_read_b64 v[128:129], v162 offset:0x1120
	ds_read_b64 v[130:131], v162 offset:0x1130
	ds_read_b64 v[124:125], v162 offset:0x1140
	ds_read_b64 v[126:127], v162 offset:0x1150
	ds_read_b64 v[120:121], v162 offset:0x1160
	ds_read_b64 v[122:123], v162 offset:0x1170
	v_mfma_f32_32x32x16_bf16 v[48:63], v[164:167], v[84:87], v[48:63]
	v_mfma_f32_32x32x16_bf16 v[64:79], v[168:171], v[80:83], v[64:79]
	v_mfma_f32_32x32x16_bf16 v[48:63], v[172:175], v[80:83], v[48:63]
	s_nop 11
	v_max_f32_e32 v154, v64, v48
	v_max_f32_e32 v155, v65, v49
	v_max_f32_e32 v162, v67, v51
	v_max3_f32 v162, v66, v50, v162
	v_max3_f32 v154, v154, v155, v162
	v_max_f32_e32 v155, v69, v53
	v_max_f32_e32 v162, v71, v55
	v_max3_f32 v155, v68, v52, v155
	v_max3_f32 v162, v70, v54, v162
	v_max3_f32 v154, v154, v155, v162
	v_max_f32_e32 v155, v73, v57
	v_max_f32_e32 v162, v75, v59
	v_max3_f32 v155, v72, v56, v155
	v_max3_f32 v162, v74, v58, v162
	v_max3_f32 v154, v154, v155, v162
	v_max_f32_e32 v155, v77, v61
	v_max_f32_e32 v163, v79, v79
	v_max_f32_e32 v162, v163, v63
	v_max3_f32 v155, v76, v60, v155
	v_max3_f32 v162, v78, v62, v162
	v_max3_f32 v154, v154, v155, v162
	v_mov_b32_e32 v155, v154
	s_nop 1
	v_permlane32_swap_b32_e32 v154, v155
	v_max_f32_e32 v154, v154, v155
	v_cmp_lt_f32_e32 vcc, s80, v154
	s_cbranch_vccz .LBB0_859
	v_max_f32_e32 v34, 0, v154
	v_exp_f32_e64 v32, -v34
	v_pk_add_f32 v[64:65], v[64:65], v[34:35] op_sel_hi:[1,0] neg_lo:[0,1] neg_hi:[0,1]
	v_pk_add_f32 v[48:49], v[48:49], v[34:35] op_sel_hi:[1,0] neg_lo:[0,1] neg_hi:[0,1]
	v_pk_add_f32 v[66:67], v[66:67], v[34:35] op_sel_hi:[1,0] neg_lo:[0,1] neg_hi:[0,1]
	v_pk_mul_f32 v[14:15], v[14:15], v[32:33] op_sel_hi:[1,0]
	v_pk_mul_f32 v[12:13], v[12:13], v[32:33] op_sel_hi:[1,0]
	v_pk_mul_f32 v[10:11], v[10:11], v[32:33] op_sel_hi:[1,0]
	v_pk_mul_f32 v[8:9], v[8:9], v[32:33] op_sel_hi:[1,0]
	v_pk_mul_f32 v[6:7], v[6:7], v[32:33] op_sel_hi:[1,0]
	v_pk_mul_f32 v[4:5], v[4:5], v[32:33] op_sel_hi:[1,0]
	v_pk_mul_f32 v[2:3], v[2:3], v[32:33] op_sel_hi:[1,0]
	v_pk_mul_f32 v[0:1], v[0:1], v[32:33] op_sel_hi:[1,0]
	v_pk_mul_f32 v[30:31], v[30:31], v[32:33] op_sel_hi:[1,0]
	v_pk_mul_f32 v[28:29], v[28:29], v[32:33] op_sel_hi:[1,0]
	v_pk_mul_f32 v[26:27], v[26:27], v[32:33] op_sel_hi:[1,0]
	v_pk_mul_f32 v[24:25], v[24:25], v[32:33] op_sel_hi:[1,0]
	v_pk_mul_f32 v[22:23], v[22:23], v[32:33] op_sel_hi:[1,0]
	v_pk_mul_f32 v[20:21], v[20:21], v[32:33] op_sel_hi:[1,0]
	v_pk_mul_f32 v[18:19], v[18:19], v[32:33] op_sel_hi:[1,0]
	v_pk_mul_f32 v[16:17], v[16:17], v[32:33] op_sel_hi:[1,0]
	v_mul_f32_e32 v152, v152, v32
	v_add_f32_e32 v32, v153, v34
	v_xor_b32_e32 v32, 0x80000000, v32
	v_pk_add_f32 v[50:51], v[50:51], v[34:35] op_sel_hi:[1,0] neg_lo:[0,1] neg_hi:[0,1]
	v_pk_add_f32 v[68:69], v[68:69], v[34:35] op_sel_hi:[1,0] neg_lo:[0,1] neg_hi:[0,1]
	v_pk_add_f32 v[52:53], v[52:53], v[34:35] op_sel_hi:[1,0] neg_lo:[0,1] neg_hi:[0,1]
	v_pk_add_f32 v[70:71], v[70:71], v[34:35] op_sel_hi:[1,0] neg_lo:[0,1] neg_hi:[0,1]
	v_pk_add_f32 v[54:55], v[54:55], v[34:35] op_sel_hi:[1,0] neg_lo:[0,1] neg_hi:[0,1]
	v_pk_add_f32 v[72:73], v[72:73], v[34:35] op_sel_hi:[1,0] neg_lo:[0,1] neg_hi:[0,1]
	v_pk_add_f32 v[56:57], v[56:57], v[34:35] op_sel_hi:[1,0] neg_lo:[0,1] neg_hi:[0,1]
	v_pk_add_f32 v[74:75], v[74:75], v[34:35] op_sel_hi:[1,0] neg_lo:[0,1] neg_hi:[0,1]
	v_pk_add_f32 v[58:59], v[58:59], v[34:35] op_sel_hi:[1,0] neg_lo:[0,1] neg_hi:[0,1]
	v_pk_add_f32 v[76:77], v[76:77], v[34:35] op_sel_hi:[1,0] neg_lo:[0,1] neg_hi:[0,1]
	v_pk_add_f32 v[60:61], v[60:61], v[34:35] op_sel_hi:[1,0] neg_lo:[0,1] neg_hi:[0,1]
	v_pk_add_f32 v[78:79], v[78:79], v[34:35] op_sel_hi:[1,0] neg_lo:[0,1] neg_hi:[0,1]
	v_pk_add_f32 v[62:63], v[62:63], v[34:35] op_sel_hi:[1,0] neg_lo:[0,1] neg_hi:[0,1]
	v_mov_b32_e32 v33, v32
	v_mov_b32_e32 v34, v32
	v_mov_b32_e32 v35, v32
	v_mov_b32_e32 v36, v32
	v_mov_b32_e32 v37, v32
	v_mov_b32_e32 v38, v32
	v_mov_b32_e32 v39, v32
	v_mov_b32_e32 v40, v32
	v_mov_b32_e32 v41, v32
	v_mov_b32_e32 v42, v32
	v_mov_b32_e32 v43, v32
	v_mov_b32_e32 v44, v32
	v_mov_b32_e32 v45, v32
	v_mov_b32_e32 v46, v32
	v_mov_b32_e32 v47, v32

.LBB0_863:
	s_or_b64 exec, exec, s[0:1]
	v_pk_add_f32 v[62:63], v[64:65], 0 op_sel_hi:[1,0]
	s_waitcnt lgkmcnt(0)
	v_pk_add_f32 v[48:49], v[48:49], v[62:63]
	s_barrier
	v_pk_add_f32 v[48:49], v[66:67], v[48:49]
	s_nop 0
	v_pk_add_f32 v[48:49], v[50:51], v[48:49]
	s_nop 0
	v_pk_add_f32 v[48:49], v[68:69], v[48:49]
	s_nop 0
	v_pk_add_f32 v[48:49], v[52:53], v[48:49]
	s_nop 0
	v_pk_add_f32 v[48:49], v[70:71], v[48:49]
	s_nop 0
	v_pk_add_f32 v[48:49], v[54:55], v[48:49]
	s_nop 0
	v_pk_add_f32 v[48:49], v[72:73], v[48:49]
	s_nop 0
	v_pk_add_f32 v[48:49], v[56:57], v[48:49]
	s_nop 0
	v_pk_add_f32 v[48:49], v[74:75], v[48:49]
	s_nop 0
	v_pk_add_f32 v[48:49], v[144:145], v[48:49]
	s_nop 0
	v_pk_add_f32 v[48:49], v[76:77], v[48:49]
	s_nop 0
	v_pk_add_f32 v[48:49], v[58:59], v[48:49]
	s_nop 0
	v_pk_add_f32 v[48:49], v[78:79], v[48:49]
	ds_read_b128 v[64:67], v161
	ds_read_b128 v[68:71], v161 offset:0x1a00
	ds_read_b128 v[72:75], v161 offset:32
	ds_read_b128 v[76:79], v161 offset:0x1a20
	ds_read_b128 v[106:109], v161 offset:64
	ds_read_b128 v[110:113], v161 offset:0x1a40
	ds_read_b128 v[114:117], v161 offset:96
	ds_read_b128 v[118:121], v161 offset:0x1a60
	ds_read_b128 v[122:125], v161 offset:128
	ds_read_b128 v[126:129], v161 offset:0x1a80
	ds_read_b128 v[130:133], v161 offset:160
	ds_read_b128 v[134:137], v161 offset:0x1aa0
	s_waitcnt lgkmcnt(0)
	s_nop 0
	v_pk_add_f32 v[48:49], v[60:61], v[48:49]
	s_nop 0
	v_add_f32_e32 v48, v48, v49
	v_add_f32_e32 v104, v152, v48
	v_mfma_f32_32x32x16_bf16 v[48:63], v[64:67], v[100:103], v[32:47]
	v_mfma_f32_32x32x16_bf16 v[32:47], v[68:71], v[100:103], v[32:47]
	v_mfma_f32_32x32x16_bf16 v[48:63], v[72:75], v[96:99], v[48:63]
	v_mfma_f32_32x32x16_bf16 v[32:47], v[76:79], v[96:99], v[32:47]
	v_mfma_f32_32x32x16_bf16 v[48:63], v[106:109], v[92:95], v[48:63]
	v_mfma_f32_32x32x16_bf16 v[32:47], v[110:113], v[92:95], v[32:47]
	v_mfma_f32_32x32x16_bf16 v[48:63], v[114:117], v[88:91], v[48:63]
	v_mfma_f32_32x32x16_bf16 v[32:47], v[118:121], v[88:91], v[32:47]
	v_mfma_f32_32x32x16_bf16 v[48:63], v[122:125], v[84:87], v[48:63]
	v_mfma_f32_32x32x16_bf16 v[32:47], v[126:129], v[84:87], v[32:47]
	v_mfma_f32_32x32x16_bf16 v[48:63], v[130:133], v[80:83], v[48:63]
	v_mfma_f32_32x32x16_bf16 v[32:47], v[134:137], v[80:83], v[32:47]
	s_nop 10
	ds_read_b64 v[92:93], v159
	ds_read_b64 v[94:95], v159 offset:16
	ds_read_b64 v[88:89], v159 offset:32
	ds_read_b64 v[90:91], v159 offset:48
	ds_read_b64 v[84:85], v159 offset:64
	ds_read_b64 v[86:87], v159 offset:80
	ds_read_b64 v[80:81], v159 offset:96
	ds_read_b64 v[82:83], v159 offset:112
	ds_read_b64 v[76:77], v159 offset:0x1100
	ds_read_b64 v[78:79], v159 offset:0x1110
	ds_read_b64 v[72:73], v159 offset:0x1120
	ds_read_b64 v[74:75], v159 offset:0x1130
	ds_read_b64 v[68:69], v159 offset:0x1140
	ds_read_b64 v[70:71], v159 offset:0x1150
	ds_read_b64 v[64:65], v159 offset:0x1160
	ds_read_b64 v[66:67], v159 offset:0x1170
	v_max_f32_e32 v96, v48, v32
	v_max_f32_e32 v97, v49, v33
	v_max_f32_e32 v98, v51, v35
	v_max3_f32 v98, v50, v34, v98
	v_max3_f32 v96, v96, v97, v98
	v_max_f32_e32 v97, v53, v37
	v_max_f32_e32 v98, v55, v39
	v_max3_f32 v97, v52, v36, v97
	v_max3_f32 v98, v54, v38, v98
	v_max3_f32 v96, v96, v97, v98
	v_max_f32_e32 v97, v57, v41
	v_max_f32_e32 v98, v59, v43
	v_max3_f32 v97, v56, v40, v97
	v_max3_f32 v98, v58, v42, v98
	v_max3_f32 v96, v96, v97, v98
	v_max_f32_e32 v97, v61, v45
	v_max_f32_e32 v99, v63, v63
	v_max_f32_e32 v98, v99, v47
	v_max3_f32 v97, v60, v44, v97
	v_max3_f32 v98, v62, v46, v98
	v_max3_f32 v96, v96, v97, v98
	v_mov_b32_e32 v97, v96
	s_nop 1
	v_permlane32_swap_b32_e32 v96, v97
	v_max_f32_e32 v96, v96, v97
	v_cmp_lt_f32_e32 vcc, s80, v96
	s_cbranch_vccz .LBB0_865
	v_max_f32_e32 v96, 0, v96
	v_exp_f32_e64 v98, -v96
	v_pk_add_f32 v[48:49], v[48:49], v[96:97] op_sel_hi:[1,0] neg_lo:[0,1] neg_hi:[0,1]
	v_pk_add_f32 v[32:33], v[32:33], v[96:97] op_sel_hi:[1,0] neg_lo:[0,1] neg_hi:[0,1]
	v_pk_add_f32 v[50:51], v[50:51], v[96:97] op_sel_hi:[1,0] neg_lo:[0,1] neg_hi:[0,1]
	v_pk_mul_f32 v[14:15], v[14:15], v[98:99] op_sel_hi:[1,0]
	v_pk_mul_f32 v[12:13], v[12:13], v[98:99] op_sel_hi:[1,0]
	v_pk_mul_f32 v[10:11], v[10:11], v[98:99] op_sel_hi:[1,0]
	v_pk_mul_f32 v[8:9], v[8:9], v[98:99] op_sel_hi:[1,0]
	v_pk_mul_f32 v[6:7], v[6:7], v[98:99] op_sel_hi:[1,0]
	v_pk_mul_f32 v[4:5], v[4:5], v[98:99] op_sel_hi:[1,0]
	v_pk_mul_f32 v[2:3], v[2:3], v[98:99] op_sel_hi:[1,0]
	v_pk_mul_f32 v[0:1], v[0:1], v[98:99] op_sel_hi:[1,0]
	v_pk_mul_f32 v[30:31], v[30:31], v[98:99] op_sel_hi:[1,0]
	v_pk_mul_f32 v[28:29], v[28:29], v[98:99] op_sel_hi:[1,0]
	v_pk_mul_f32 v[26:27], v[26:27], v[98:99] op_sel_hi:[1,0]
	v_pk_mul_f32 v[24:25], v[24:25], v[98:99] op_sel_hi:[1,0]
	v_pk_mul_f32 v[22:23], v[22:23], v[98:99] op_sel_hi:[1,0]
	v_pk_mul_f32 v[20:21], v[20:21], v[98:99] op_sel_hi:[1,0]
	v_pk_mul_f32 v[18:19], v[18:19], v[98:99] op_sel_hi:[1,0]
	v_pk_mul_f32 v[16:17], v[16:17], v[98:99] op_sel_hi:[1,0]
	v_mul_f32_e32 v104, v104, v98
	v_pk_add_f32 v[34:35], v[34:35], v[96:97] op_sel_hi:[1,0] neg_lo:[0,1] neg_hi:[0,1]
	v_pk_add_f32 v[52:53], v[52:53], v[96:97] op_sel_hi:[1,0] neg_lo:[0,1] neg_hi:[0,1]
	v_pk_add_f32 v[36:37], v[36:37], v[96:97] op_sel_hi:[1,0] neg_lo:[0,1] neg_hi:[0,1]
	v_pk_add_f32 v[54:55], v[54:55], v[96:97] op_sel_hi:[1,0] neg_lo:[0,1] neg_hi:[0,1]
	v_pk_add_f32 v[38:39], v[38:39], v[96:97] op_sel_hi:[1,0] neg_lo:[0,1] neg_hi:[0,1]
	v_pk_add_f32 v[56:57], v[56:57], v[96:97] op_sel_hi:[1,0] neg_lo:[0,1] neg_hi:[0,1]
	v_pk_add_f32 v[40:41], v[40:41], v[96:97] op_sel_hi:[1,0] neg_lo:[0,1] neg_hi:[0,1]
	v_pk_add_f32 v[58:59], v[58:59], v[96:97] op_sel_hi:[1,0] neg_lo:[0,1] neg_hi:[0,1]
	v_pk_add_f32 v[42:43], v[42:43], v[96:97] op_sel_hi:[1,0] neg_lo:[0,1] neg_hi:[0,1]
	v_pk_add_f32 v[60:61], v[60:61], v[96:97] op_sel_hi:[1,0] neg_lo:[0,1] neg_hi:[0,1]
	v_pk_add_f32 v[44:45], v[44:45], v[96:97] op_sel_hi:[1,0] neg_lo:[0,1] neg_hi:[0,1]
	v_pk_add_f32 v[62:63], v[62:63], v[96:97] op_sel_hi:[1,0] neg_lo:[0,1] neg_hi:[0,1]
	v_pk_add_f32 v[46:47], v[46:47], v[96:97] op_sel_hi:[1,0] neg_lo:[0,1] neg_hi:[0,1]

.LBB0_873:
	s_or_b64 exec, exec, s[0:1]
	v_add_co_u32_e32 v0, vcc, 0x4000, v164
	v_mad_u32_u24 v50, v32, s24, 0
	s_nop 0
	v_addc_co_u32_e32 v1, vcc, 0, v165, vcc
	global_load_dwordx4 v[68:71], v[0:1], off
	global_load_dwordx4 v[72:75], v[0:1], off offset:256
	v_add_u32_e32 v191, v50, v80
	ds_read_b128 v[0:3], v191
	ds_read_b128 v[16:19], v191 offset:0x1200
	ds_read_b128 v[34:37], v191 offset:32
	ds_read_b128 v[38:41], v191 offset:0x1220
	ds_read_b128 v[42:45], v191 offset:64
	ds_read_b128 v[46:49], v191 offset:0x1240
	ds_read_b128 v[52:55], v191 offset:96
	ds_read_b128 v[56:59], v191 offset:0x1260
	s_waitcnt lgkmcnt(0)
	v_lshlrev_b32_e32 v81, 3, v32
	v_mfma_f32_32x32x16_bf16 v[0:15], v[0:3], v[124:127], 0
	v_lshlrev_b32_e32 v136, 3, v33
	v_sub_u32_e32 v137, v50, v81
	v_add_u32_e32 v99, v137, v136
	v_add_u32_e32 v190, 0x3400, v99
	v_add_u32_e32 v189, 0x5600, v99
	v_mfma_f32_32x32x16_bf16 v[16:31], v[16:19], v[124:127], 0
	v_mfma_f32_32x32x16_bf16 v[0:15], v[34:37], v[120:123], v[0:15]
	v_mfma_f32_32x32x16_bf16 v[16:31], v[38:41], v[120:123], v[16:31]
	v_mfma_f32_32x32x16_bf16 v[0:15], v[42:45], v[116:119], v[0:15]
	v_mfma_f32_32x32x16_bf16 v[16:31], v[46:49], v[116:119], v[16:31]
	v_mfma_f32_32x32x16_bf16 v[16:31], v[56:59], v[112:115], v[16:31]
	ds_read_b64 v[106:107], v190
	ds_read_b64 v[108:109], v190 offset:16
	ds_read_b64 v[44:45], v190 offset:32
	ds_read_b64 v[46:47], v190 offset:48
	ds_read_b64 v[40:41], v190 offset:64
	ds_read_b64 v[42:43], v190 offset:80
	ds_read_b64 v[36:37], v190 offset:96
	ds_read_b64 v[38:39], v190 offset:112
	ds_read_b64 v[32:33], v190 offset:0x1100
	ds_read_b64 v[34:35], v190 offset:0x1110
	ds_read_b64 v[60:61], v190 offset:0x1120
	ds_read_b64 v[62:63], v190 offset:0x1130
	ds_read_b64 v[56:57], v190 offset:0x1140
	ds_read_b64 v[58:59], v190 offset:0x1150
	ds_read_b64 v[48:49], v190 offset:0x1160
	ds_read_b64 v[50:51], v190 offset:0x1170
	s_nop 0
	s_waitcnt lgkmcnt(0)
	v_mfma_f32_32x32x16_bf16 v[0:15], v[52:55], v[112:115], v[0:15]
	s_nop 11
	v_max_f32_e32 v53, v1, v17
	v_max_f32_e32 v54, v3, v19
	v_max_f32_e32 v52, v0, v16
	v_max3_f32 v54, v2, v18, v54
	v_max3_f32 v52, v52, v53, v54
	v_max_f32_e32 v53, v5, v21
	v_max_f32_e32 v54, v7, v23
	v_max3_f32 v53, v4, v20, v53
	v_max3_f32 v54, v6, v22, v54
	v_max3_f32 v52, v52, v53, v54
	v_max_f32_e32 v53, v9, v25
	v_max_f32_e32 v54, v11, v27
	v_max3_f32 v53, v8, v24, v53
	v_max3_f32 v54, v10, v26, v54
	v_max3_f32 v52, v52, v53, v54
	v_max_f32_e32 v53, v13, v29
	v_max_f32_e32 v55, v15, v15
	v_max_f32_e32 v54, v55, v31
	v_max3_f32 v53, v12, v28, v53
	v_max3_f32 v54, v14, v30, v54
	v_max3_f32 v52, v52, v53, v54
	v_mov_b32_e32 v53, v52
	s_nop 1
	v_permlane32_swap_b32_e32 v52, v53
	v_max_f32_e32 v138, v52, v53
	v_sub_f32_e32 v0, v0, v138
	v_sub_f32_e32 v1, v1, v138
	v_sub_f32_e32 v2, v2, v138
	v_sub_f32_e32 v3, v3, v138
	v_sub_f32_e32 v4, v4, v138
	v_sub_f32_e32 v5, v5, v138
	v_sub_f32_e32 v6, v6, v138
	v_sub_f32_e32 v7, v7, v138
	v_exp_f32_e32 v76, v0
	v_exp_f32_e32 v77, v1
	v_exp_f32_e32 v82, v2
	v_exp_f32_e32 v83, v3
	v_exp_f32_e32 v86, v4
	v_exp_f32_e32 v87, v5
	v_exp_f32_e32 v90, v6
	v_exp_f32_e32 v91, v7
	v_sub_f32_e32 v16, v16, v138
	v_sub_f32_e32 v17, v17, v138
	v_sub_f32_e32 v18, v18, v138
	v_sub_f32_e32 v19, v19, v138
	v_sub_f32_e32 v8, v8, v138
	v_sub_f32_e32 v9, v9, v138
	v_sub_f32_e32 v10, v10, v138
	v_sub_f32_e32 v11, v11, v138
	v_sub_f32_e32 v12, v12, v138
	v_exp_f32_e32 v78, v16
	v_exp_f32_e32 v79, v17
	v_exp_f32_e32 v84, v18
	v_exp_f32_e32 v85, v19
	v_cvt_pk_bf16_f32 v16, v76, v77
	v_cvt_pk_bf16_f32 v17, v82, v83
	v_cvt_pk_bf16_f32 v18, v86, v87
	v_cvt_pk_bf16_f32 v19, v90, v91
	v_sub_f32_e32 v52, v13, v138
	v_sub_f32_e32 v53, v14, v138
	v_sub_f32_e32 v54, v15, v138
	v_exp_f32_e32 v94, v8
	v_exp_f32_e32 v95, v9
	v_exp_f32_e32 v102, v10
	v_exp_f32_e32 v103, v11
	v_exp_f32_e32 v104, v12
	v_mfma_f32_32x32x16_bf16 v[0:15], v[106:109], v[16:19], 0
	v_exp_f32_e32 v105, v52
	v_exp_f32_e32 v106, v53
	v_exp_f32_e32 v107, v54
	v_cvt_pk_bf16_f32 v140, v94, v95
	v_cvt_pk_bf16_f32 v141, v102, v103
	v_cvt_pk_bf16_f32 v142, v104, v105
	v_cvt_pk_bf16_f32 v143, v106, v107
	v_sub_f32_e32 v20, v20, v138
	v_sub_f32_e32 v21, v21, v138
	v_mfma_f32_32x32x16_bf16 v[0:15], v[44:47], v[140:143], v[0:15]
	v_sub_f32_e32 v22, v22, v138
	v_sub_f32_e32 v23, v23, v138
	v_exp_f32_e32 v88, v20
	v_exp_f32_e32 v89, v21
	v_exp_f32_e32 v92, v22
	v_exp_f32_e32 v93, v23
	v_cvt_pk_bf16_f32 v144, v78, v79
	v_cvt_pk_bf16_f32 v145, v84, v85
	v_cvt_pk_bf16_f32 v146, v88, v89
	v_cvt_pk_bf16_f32 v147, v92, v93
	v_sub_f32_e32 v24, v24, v138
	v_sub_f32_e32 v25, v25, v138
	v_mfma_f32_32x32x16_bf16 v[0:15], v[40:43], v[144:147], v[0:15]
	v_sub_f32_e32 v26, v26, v138
	v_sub_f32_e32 v27, v27, v138
	v_sub_f32_e32 v28, v28, v138
	v_sub_f32_e32 v29, v29, v138
	v_sub_f32_e32 v30, v30, v138
	v_sub_f32_e32 v31, v31, v138
	v_exp_f32_e32 v96, v24
	v_exp_f32_e32 v97, v25
	v_exp_f32_e32 v132, v26
	v_exp_f32_e32 v133, v27
	v_exp_f32_e32 v108, v28
	v_exp_f32_e32 v109, v29
	v_exp_f32_e32 v134, v30
	v_exp_f32_e32 v135, v31
	v_cvt_pk_bf16_f32 v148, v96, v97
	v_cvt_pk_bf16_f32 v149, v132, v133
	v_cvt_pk_bf16_f32 v150, v108, v109
	v_cvt_pk_bf16_f32 v151, v134, v135
	s_nop 1
	v_mfma_f32_32x32x16_bf16 v[0:15], v[36:39], v[148:151], v[0:15]
	v_mfma_f32_32x32x16_bf16 v[32:47], v[32:35], v[16:19], 0
	v_mfma_f32_32x32x16_bf16 v[32:47], v[60:63], v[140:143], v[32:47]
	v_mfma_f32_32x32x16_bf16 v[32:47], v[56:59], v[144:147], v[32:47]
	v_mfma_f32_32x32x16_bf16 v[32:47], v[48:51], v[148:151], v[32:47]
	ds_read_b64 v[48:49], v189
	ds_read_b64 v[50:51], v189 offset:16
	ds_read_b64 v[168:169], v189 offset:32
	ds_read_b64 v[170:171], v189 offset:48
	ds_read_b64 v[28:29], v189 offset:64
	ds_read_b64 v[30:31], v189 offset:80
	ds_read_b64 v[24:25], v189 offset:96
	ds_read_b64 v[26:27], v189 offset:112
	ds_read_b64 v[20:21], v189 offset:0x1100
	ds_read_b64 v[22:23], v189 offset:0x1110
	ds_read_b64 v[160:161], v189 offset:0x1120
	ds_read_b64 v[162:163], v189 offset:0x1130
	ds_read_b64 v[156:157], v189 offset:0x1140
	ds_read_b64 v[158:159], v189 offset:0x1150
	ds_read_b64 v[152:153], v189 offset:0x1160
	ds_read_b64 v[154:155], v189 offset:0x1170
	s_nop 0
	s_waitcnt lgkmcnt(0)
; #define ATT_LOADK(t, r0, r1) do { r0 = *(const u32x4*)(kg0 + (size_t)(t) * 64 * DK); if (k1on) r1 = *(const u32x4*)(kg1 + (size_t)(t) * 64 * DK); } while (0)
; #define ATT_LOADV(t, r0, r1) do { if (von) { r0 = *(const u32x4*)(vg0 + (size_t)(t) * 64 * DV); r1 = *(const u32x4*)(vg0 + (size_t)(t) * 64 * DV + DV); } } while (0)
; #define ATT_STOREK(bi, r0, r1) do { LAS unsigned char* kb_ = lds + (bi) * ATT_BUF; *(LAS u32x4*)(kb_ + kl0) = r0; if (k1on) *(LAS u32x4*)(kb_ + kl1) = r1; } while (0)
; template <int DK, int DV, int VAR>
; __device__ __forceinline__ void attn_pass(LAS unsigned char* lds, const bf16_t* Qg, const bf16_t* Kg, const bf16_t* Vg, int ntiles, float cs, f32x16 (&O)[DV / 32], float& lsum, int wv) {
;     ...
; #pragma unroll
;     for (int t = 0; t < DV / 32; ++t)
; #pragma unroll
;         for (int i = 0; i < 16; ++i) O[t][i] = 0.f;
;     float mrun = 0.f, lrun = 0.f; (void)cs;
;     f32x16 Sa0, Sa1, negm;
; #pragma unroll
;     for (int i = 0; i < 16; ++i) negm[i] = 0.f;
;     __syncthreads();
;     ATT_LOADK(0, ka0, ka1); ATT_LOADV(0, va0, va1);
;     for (int t = 0; t < ntiles; ++t) {
;         if (VAR != 1 || t < 2) { ATT_STOREK(t & 1, ka0, ka1); ATT_STOREV(t & 1, va0, va1); }
;         __syncthreads();
;         if (VAR != 1) { if (t + 1 < ntiles) { ATT_LOADK(t + 1, ka0, ka1); ATT_LOADV(t + 1, va0, va1); } }
	s_waitcnt vmcnt(2)
	ds_write_b128 v184, v[64:67] offset:32768
	v_mfma_f32_32x32x16_bf16 v[48:63], v[48:51], v[16:19], 0
	v_mfma_f32_32x32x16_bf16 v[48:63], v[168:171], v[140:143], v[48:63]
	v_mfma_f32_32x32x16_bf16 v[48:63], v[28:31], v[144:147], v[48:63]
	v_mfma_f32_32x32x16_bf16 v[48:63], v[24:27], v[148:151], v[48:63]
	v_mfma_f32_32x32x16_bf16 v[16:31], v[20:23], v[16:19], 0
	v_mfma_f32_32x32x16_bf16 v[16:31], v[160:163], v[140:143], v[16:31]
	v_mfma_f32_32x32x16_bf16 v[16:31], v[156:159], v[144:147], v[16:31]
	v_mfma_f32_32x32x16_bf16 v[16:31], v[152:155], v[148:151], v[16:31]
	s_and_saveexec_b64 s[0:1], s[2:3]
	ds_write_b128 v183, v[128:131] offset:32768
	s_or_b64 exec, exec, s[0:1]
	s_waitcnt vmcnt(0)
	v_perm_b32 v64, v72, v68, s85
	v_perm_b32 v65, v72, v68, s86
	v_add_u32_e32 v186, 0xb400, v98
	ds_write2_b32 v186, v64, v65 offset1:34
	v_perm_b32 v64, v73, v69, s85
	v_perm_b32 v65, v73, v69, s86
	ds_write2_b32 v186, v64, v65 offset0:68 offset1:102
	v_perm_b32 v64, v74, v70, s85
	v_perm_b32 v65, v74, v70, s86
	ds_write2_b32 v186, v64, v65 offset0:136 offset1:170
	v_perm_b32 v64, v75, v71, s85
	v_perm_b32 v65, v75, v71, s86
	ds_write2_b32 v186, v64, v65 offset0:204 offset1:238
	v_add_co_u32_e32 v64, vcc, 0x4000, v166
	s_waitcnt lgkmcnt(0)
	s_nop 0
	v_addc_co_u32_e32 v65, vcc, 0, v167, vcc
	s_barrier
	global_load_dwordx4 v[98:101], v[64:65], off
	s_and_saveexec_b64 s[0:1], s[2:3]
	s_cbranch_execz .LBB0_877
	v_add_co_u32_e32 v64, vcc, 0x4000, v110
	s_nop 1
	v_addc_co_u32_e32 v65, vcc, 0, v111, vcc
	global_load_dwordx4 v[128:131], v[64:65], off
.LBB0_877:
	s_or_b64 exec, exec, s[0:1]
	v_pk_add_f32 v[64:65], v[76:77], 0 op_sel_hi:[1,0]
	s_mov_b32 s0, 0x8000
	v_pk_add_f32 v[64:65], v[78:79], v[64:65]
	v_add_u32_e32 v137, v137, v81
	v_pk_add_f32 v[64:65], v[82:83], v[64:65]
	v_add_co_u32_e32 v82, vcc, s0, v164
	v_pk_add_f32 v[64:65], v[84:85], v[64:65]
	s_nop 0
	v_addc_co_u32_e32 v83, vcc, 0, v165, vcc
	v_pk_add_f32 v[64:65], v[86:87], v[64:65]
	v_sub_u32_e32 v162, 0, v81
	v_pk_add_f32 v[64:65], v[88:89], v[64:65]
	v_add3_u32 v188, v137, v80, s0
	v_pk_add_f32 v[64:65], v[90:91], v[64:65]
	s_mov_b32 s0, 0xb400
	v_pk_add_f32 v[64:65], v[92:93], v[64:65]
	s_nop 0
	v_pk_add_f32 v[64:65], v[94:95], v[64:65]
	s_nop 0
	v_pk_add_f32 v[64:65], v[96:97], v[64:65]
	s_nop 0
	v_pk_add_f32 v[64:65], v[102:103], v[64:65]
	s_nop 0
	v_pk_add_f32 v[64:65], v[132:133], v[64:65]
	s_nop 0
	v_pk_add_f32 v[64:65], v[104:105], v[64:65]
	s_nop 0
	v_pk_add_f32 v[64:65], v[108:109], v[64:65]
	s_nop 0
	v_pk_add_f32 v[64:65], v[106:107], v[64:65]
	global_load_dwordx4 v[102:105], v[82:83], off
	global_load_dwordx4 v[106:109], v[82:83], off offset:256
	v_pk_add_f32 v[64:65], v[134:135], v[64:65]
	s_nop 0
	v_pk_add_f32 v[64:65], v[64:65], v[64:65] op_sel:[0,1] op_sel_hi:[1,0]
	s_nop 0
	v_mov_b32_e32 v65, v138
	v_pk_add_f32 v[176:177], v[64:65], 0 op_sel_hi:[1,0]
	ds_read_b128 v[132:135], v188
	ds_read_b128 v[138:141], v188 offset:0x1200
	ds_read_b128 v[142:145], v188 offset:32
	ds_read_b128 v[146:149], v188 offset:0x1220
	ds_read_b128 v[150:153], v188 offset:64
	ds_read_b128 v[154:157], v188 offset:0x1240
	ds_read_b128 v[158:161], v188 offset:96
	ds_read_b128 v[168:171], v188 offset:0x1260
	s_waitcnt lgkmcnt(0)
	s_nop 0
	v_xor_b32_e32 v64, 0x80000000, v177
	v_mov_b32_e32 v65, v64
	v_mov_b32_e32 v66, v64
	v_mov_b32_e32 v67, v64
	v_mov_b32_e32 v68, v64
	v_mov_b32_e32 v69, v64
	v_mov_b32_e32 v70, v64
	v_mov_b32_e32 v71, v64
	v_mov_b32_e32 v72, v64
	v_mov_b32_e32 v73, v64
	v_mov_b32_e32 v74, v64
	v_mov_b32_e32 v75, v64
	v_mov_b32_e32 v76, v64
	v_mov_b32_e32 v77, v64
	v_mov_b32_e32 v78, v64
	v_mov_b32_e32 v79, v64
	s_nop 1
	v_mfma_f32_32x32x16_bf16 v[82:97], v[132:135], v[124:127], v[64:79]
	v_mov_b64_e32 v[80:81], v[78:79]
	s_nop 5
	v_mov_b64_e32 v[78:79], v[76:77]
	v_mov_b64_e32 v[76:77], v[74:75]
	v_mov_b64_e32 v[74:75], v[72:73]
	v_mov_b64_e32 v[72:73], v[70:71]
	v_mov_b64_e32 v[70:71], v[68:69]
	v_mov_b64_e32 v[68:69], v[66:67]
	v_mov_b64_e32 v[66:67], v[64:65]
	v_mfma_f32_32x32x16_bf16 v[82:97], v[142:145], v[120:123], v[82:97]
	v_add_u32_e32 v65, v137, v162
	v_add3_u32 v187, v65, v136, s0
	v_mfma_f32_32x32x16_bf16 v[66:81], v[138:141], v[124:127], v[66:81]
	v_mfma_f32_32x32x16_bf16 v[66:81], v[146:149], v[120:123], v[66:81]
	v_mfma_f32_32x32x16_bf16 v[82:97], v[150:153], v[116:119], v[82:97]
	v_mfma_f32_32x32x16_bf16 v[66:81], v[154:157], v[116:119], v[66:81]
	v_mfma_f32_32x32x16_bf16 v[82:97], v[158:161], v[112:115], v[82:97]
	ds_read_b64 v[160:161], v187
	ds_read_b64 v[162:163], v187 offset:16
	ds_read_b64 v[156:157], v187 offset:32
	ds_read_b64 v[158:159], v187 offset:48
	ds_read_b64 v[152:153], v187 offset:64
	ds_read_b64 v[154:155], v187 offset:80
	ds_read_b64 v[148:149], v187 offset:96
	ds_read_b64 v[150:151], v187 offset:112
	ds_read_b64 v[144:145], v187 offset:0x1100
	ds_read_b64 v[146:147], v187 offset:0x1110
	ds_read_b64 v[140:141], v187 offset:0x1120
	ds_read_b64 v[142:143], v187 offset:0x1130
	ds_read_b64 v[136:137], v187 offset:0x1140
	ds_read_b64 v[138:139], v187 offset:0x1150
	ds_read_b64 v[132:133], v187 offset:0x1160
	ds_read_b64 v[134:135], v187 offset:0x1170
	v_mfma_f32_32x32x16_bf16 v[66:81], v[168:171], v[112:115], v[66:81]
	s_nop 11
	v_max_f32_e32 v65, v82, v66
	v_max_f32_e32 v168, v83, v67
	v_max_f32_e32 v169, v85, v69
	v_max3_f32 v169, v84, v68, v169
	v_max3_f32 v65, v65, v168, v169
	v_max_f32_e32 v168, v87, v71
	v_max_f32_e32 v169, v89, v73
	v_max3_f32 v168, v86, v70, v168
	v_max3_f32 v169, v88, v72, v169
	v_max3_f32 v65, v65, v168, v169
	v_max_f32_e32 v168, v91, v75
	v_max_f32_e32 v169, v93, v77
	v_max3_f32 v168, v90, v74, v168
	v_max3_f32 v169, v92, v76, v169
	v_max3_f32 v65, v65, v168, v169
	v_max_f32_e32 v168, v95, v79
	v_max_f32_e32 v170, v97, v97
	v_max_f32_e32 v169, v170, v81
	v_max3_f32 v168, v94, v78, v168
	v_max3_f32 v169, v96, v80, v169
	v_max3_f32 v65, v65, v168, v169
	v_mov_b32_e32 v168, v65
	s_nop 1
	v_permlane32_swap_b32_e32 v65, v168
	v_max_f32_e32 v65, v65, v168
	v_cmp_lt_f32_e32 vcc, s80, v65
	s_cbranch_vccz .LBB0_879
	v_max_f32_e32 v168, 0, v65
	v_exp_f32_e64 v170, -v168
	v_add_f32_e32 v177, v177, v168
	v_xor_b32_e32 v64, 0x80000000, v177
	v_pk_add_f32 v[82:83], v[82:83], v[168:169] op_sel_hi:[1,0] neg_lo:[0,1] neg_hi:[0,1]
	v_pk_mul_f32 v[14:15], v[14:15], v[170:171] op_sel_hi:[1,0]
	v_pk_mul_f32 v[12:13], v[12:13], v[170:171] op_sel_hi:[1,0]
	v_pk_mul_f32 v[10:11], v[10:11], v[170:171] op_sel_hi:[1,0]
	v_pk_mul_f32 v[8:9], v[8:9], v[170:171] op_sel_hi:[1,0]
	v_pk_mul_f32 v[6:7], v[6:7], v[170:171] op_sel_hi:[1,0]
	v_pk_mul_f32 v[4:5], v[4:5], v[170:171] op_sel_hi:[1,0]
	v_pk_mul_f32 v[2:3], v[2:3], v[170:171] op_sel_hi:[1,0]
	v_pk_mul_f32 v[0:1], v[0:1], v[170:171] op_sel_hi:[1,0]
	v_pk_mul_f32 v[46:47], v[46:47], v[170:171] op_sel_hi:[1,0]
	v_pk_mul_f32 v[44:45], v[44:45], v[170:171] op_sel_hi:[1,0]
	v_pk_mul_f32 v[42:43], v[42:43], v[170:171] op_sel_hi:[1,0]
	v_pk_mul_f32 v[40:41], v[40:41], v[170:171] op_sel_hi:[1,0]
	v_pk_mul_f32 v[38:39], v[38:39], v[170:171] op_sel_hi:[1,0]
	v_pk_mul_f32 v[36:37], v[36:37], v[170:171] op_sel_hi:[1,0]
	v_pk_mul_f32 v[34:35], v[34:35], v[170:171] op_sel_hi:[1,0]
	v_pk_mul_f32 v[32:33], v[32:33], v[170:171] op_sel_hi:[1,0]
	v_pk_mul_f32 v[62:63], v[62:63], v[170:171] op_sel_hi:[1,0]
	v_pk_mul_f32 v[60:61], v[60:61], v[170:171] op_sel_hi:[1,0]
	v_pk_mul_f32 v[58:59], v[58:59], v[170:171] op_sel_hi:[1,0]
	v_pk_mul_f32 v[56:57], v[56:57], v[170:171] op_sel_hi:[1,0]
	v_pk_mul_f32 v[54:55], v[54:55], v[170:171] op_sel_hi:[1,0]
	v_pk_mul_f32 v[52:53], v[52:53], v[170:171] op_sel_hi:[1,0]
	v_pk_mul_f32 v[50:51], v[50:51], v[170:171] op_sel_hi:[1,0]
	v_pk_mul_f32 v[48:49], v[48:49], v[170:171] op_sel_hi:[1,0]
	v_pk_mul_f32 v[30:31], v[30:31], v[170:171] op_sel_hi:[1,0]
	v_pk_mul_f32 v[28:29], v[28:29], v[170:171] op_sel_hi:[1,0]
	v_pk_mul_f32 v[26:27], v[26:27], v[170:171] op_sel_hi:[1,0]
	v_pk_mul_f32 v[24:25], v[24:25], v[170:171] op_sel_hi:[1,0]
	v_pk_mul_f32 v[22:23], v[22:23], v[170:171] op_sel_hi:[1,0]
	v_pk_mul_f32 v[20:21], v[20:21], v[170:171] op_sel_hi:[1,0]
	v_pk_mul_f32 v[18:19], v[18:19], v[170:171] op_sel_hi:[1,0]
	v_pk_mul_f32 v[16:17], v[16:17], v[170:171] op_sel_hi:[1,0]
	v_pk_add_f32 v[66:67], v[66:67], v[168:169] op_sel_hi:[1,0] neg_lo:[0,1] neg_hi:[0,1]
	v_pk_add_f32 v[84:85], v[84:85], v[168:169] op_sel_hi:[1,0] neg_lo:[0,1] neg_hi:[0,1]
	v_pk_add_f32 v[68:69], v[68:69], v[168:169] op_sel_hi:[1,0] neg_lo:[0,1] neg_hi:[0,1]
	v_pk_add_f32 v[86:87], v[86:87], v[168:169] op_sel_hi:[1,0] neg_lo:[0,1] neg_hi:[0,1]
	v_pk_add_f32 v[70:71], v[70:71], v[168:169] op_sel_hi:[1,0] neg_lo:[0,1] neg_hi:[0,1]
	v_pk_add_f32 v[88:89], v[88:89], v[168:169] op_sel_hi:[1,0] neg_lo:[0,1] neg_hi:[0,1]
	v_pk_add_f32 v[72:73], v[72:73], v[168:169] op_sel_hi:[1,0] neg_lo:[0,1] neg_hi:[0,1]
	v_pk_add_f32 v[90:91], v[90:91], v[168:169] op_sel_hi:[1,0] neg_lo:[0,1] neg_hi:[0,1]
	v_pk_add_f32 v[74:75], v[74:75], v[168:169] op_sel_hi:[1,0] neg_lo:[0,1] neg_hi:[0,1]
	v_pk_add_f32 v[92:93], v[92:93], v[168:169] op_sel_hi:[1,0] neg_lo:[0,1] neg_hi:[0,1]
	v_pk_add_f32 v[76:77], v[76:77], v[168:169] op_sel_hi:[1,0] neg_lo:[0,1] neg_hi:[0,1]
	v_pk_add_f32 v[94:95], v[94:95], v[168:169] op_sel_hi:[1,0] neg_lo:[0,1] neg_hi:[0,1]
	v_pk_add_f32 v[78:79], v[78:79], v[168:169] op_sel_hi:[1,0] neg_lo:[0,1] neg_hi:[0,1]
	v_pk_add_f32 v[96:97], v[96:97], v[168:169] op_sel_hi:[1,0] neg_lo:[0,1] neg_hi:[0,1]
	v_pk_add_f32 v[80:81], v[80:81], v[168:169] op_sel_hi:[1,0] neg_lo:[0,1] neg_hi:[0,1]
	v_mul_f32_e32 v176, v176, v170

.LBB0_883:
	s_or_b64 exec, exec, s[0:1]
	v_pk_add_f32 v[82:83], v[82:83], 0 op_sel_hi:[1,0]
	s_mov_b32 s0, 0xc000
	v_pk_add_f32 v[82:83], v[168:169], v[82:83]
	v_mov_b32_e32 v65, v64
	v_pk_add_f32 v[82:83], v[84:85], v[82:83]
	v_mov_b32_e32 v66, v64
	v_pk_add_f32 v[82:83], v[170:171], v[82:83]
	v_mov_b32_e32 v67, v64
	v_pk_add_f32 v[82:83], v[86:87], v[82:83]
	v_mov_b32_e32 v68, v64
	v_pk_add_f32 v[82:83], v[172:173], v[82:83]
	v_mov_b32_e32 v69, v64
	v_pk_add_f32 v[82:83], v[88:89], v[82:83]
	v_mov_b32_e32 v70, v64
	v_pk_add_f32 v[82:83], v[174:175], v[82:83]
	v_mov_b32_e32 v71, v64
	v_pk_add_f32 v[82:83], v[90:91], v[82:83]
	v_mov_b32_e32 v72, v64
	v_pk_add_f32 v[82:83], v[178:179], v[82:83]
	v_mov_b32_e32 v73, v64
	v_pk_add_f32 v[82:83], v[92:93], v[82:83]
	v_mov_b32_e32 v74, v64
	v_pk_add_f32 v[82:83], v[158:159], v[82:83]
	v_mov_b32_e32 v75, v64
	v_pk_add_f32 v[82:83], v[94:95], v[82:83]
	v_mov_b32_e32 v76, v64
	v_pk_add_f32 v[82:83], v[156:157], v[82:83]
	v_mov_b32_e32 v77, v64
	v_pk_add_f32 v[82:83], v[96:97], v[82:83]
	v_mov_b32_e32 v78, v64
	v_pk_add_f32 v[80:81], v[80:81], v[82:83]
	v_mov_b32_e32 v79, v64
	v_add_f32_e32 v80, v80, v81
	v_add_f32_e32 v176, v176, v80
	v_add_co_u32_e32 v80, vcc, s0, v164
	s_nop 1
	v_addc_co_u32_e32 v81, vcc, 0, v165, vcc
	global_load_dwordx4 v[136:139], v[80:81], off
	global_load_dwordx4 v[140:143], v[80:81], off offset:256
	ds_read_b128 v[80:83], v191
	ds_read_b128 v[144:147], v191 offset:0x1200
	ds_read_b128 v[148:151], v191 offset:32
	ds_read_b128 v[152:155], v191 offset:0x1220
	ds_read_b128 v[156:159], v191 offset:64
	ds_read_b128 v[160:163], v191 offset:0x1240
	ds_read_b128 v[164:167], v191 offset:96
	ds_read_b128 v[168:171], v191 offset:0x1260
	s_waitcnt lgkmcnt(0)
	s_nop 0
	v_mfma_f32_32x32x16_bf16 v[96:111], v[80:83], v[124:127], v[64:79]
	v_mfma_f32_32x32x16_bf16 v[80:95], v[144:147], v[124:127], v[64:79]
	v_mfma_f32_32x32x16_bf16 v[96:111], v[148:151], v[120:123], v[96:111]
	v_mfma_f32_32x32x16_bf16 v[80:95], v[152:155], v[120:123], v[80:95]
	v_mfma_f32_32x32x16_bf16 v[96:111], v[156:159], v[116:119], v[96:111]
	v_mfma_f32_32x32x16_bf16 v[80:95], v[160:163], v[116:119], v[80:95]
	v_mfma_f32_32x32x16_bf16 v[96:111], v[164:167], v[112:115], v[96:111]
	v_mfma_f32_32x32x16_bf16 v[80:95], v[168:171], v[112:115], v[80:95]
	s_nop 10
	ds_read_b64 v[172:173], v190
	ds_read_b64 v[174:175], v190 offset:16
	ds_read_b64 v[168:169], v190 offset:32
	ds_read_b64 v[170:171], v190 offset:48
	ds_read_b64 v[164:165], v190 offset:64
	ds_read_b64 v[166:167], v190 offset:80
	ds_read_b64 v[160:161], v190 offset:96
	ds_read_b64 v[162:163], v190 offset:112
	ds_read_b64 v[156:157], v190 offset:0x1100
	ds_read_b64 v[158:159], v190 offset:0x1110
	ds_read_b64 v[152:153], v190 offset:0x1120
	ds_read_b64 v[154:155], v190 offset:0x1130
	ds_read_b64 v[148:149], v190 offset:0x1140
	ds_read_b64 v[150:151], v190 offset:0x1150
	ds_read_b64 v[144:145], v190 offset:0x1160
	ds_read_b64 v[146:147], v190 offset:0x1170
	v_max_f32_e32 v178, v96, v80
	v_max_f32_e32 v179, v97, v81
	v_max_f32_e32 v190, v99, v83
	v_max3_f32 v190, v98, v82, v190
	v_max3_f32 v178, v178, v179, v190
	v_max_f32_e32 v179, v101, v85
	v_max_f32_e32 v190, v103, v87
	v_max3_f32 v179, v100, v84, v179
	v_max3_f32 v190, v102, v86, v190
	v_max3_f32 v178, v178, v179, v190
	v_max_f32_e32 v179, v105, v89
	v_max_f32_e32 v190, v107, v91
	v_max3_f32 v179, v104, v88, v179
	v_max3_f32 v190, v106, v90, v190
	v_max3_f32 v178, v178, v179, v190
	v_max_f32_e32 v179, v109, v93
	v_max_f32_e32 v191, v111, v111
	v_max_f32_e32 v190, v191, v95
	v_max3_f32 v179, v108, v92, v179
	v_max3_f32 v190, v110, v94, v190
	v_max3_f32 v178, v178, v179, v190
	v_mov_b32_e32 v179, v178
	s_nop 1
	v_permlane32_swap_b32_e32 v178, v179
	v_max_f32_e32 v178, v178, v179
	v_cmp_lt_f32_e32 vcc, s80, v178
	s_cbranch_vccz .LBB0_885
	v_max_f32_e32 v66, 0, v178
	v_exp_f32_e64 v64, -v66
	v_pk_add_f32 v[96:97], v[96:97], v[66:67] op_sel_hi:[1,0] neg_lo:[0,1] neg_hi:[0,1]
	v_pk_add_f32 v[80:81], v[80:81], v[66:67] op_sel_hi:[1,0] neg_lo:[0,1] neg_hi:[0,1]
	v_pk_add_f32 v[98:99], v[98:99], v[66:67] op_sel_hi:[1,0] neg_lo:[0,1] neg_hi:[0,1]
	v_pk_mul_f32 v[14:15], v[14:15], v[64:65] op_sel_hi:[1,0]
	v_pk_mul_f32 v[12:13], v[12:13], v[64:65] op_sel_hi:[1,0]
	v_pk_mul_f32 v[10:11], v[10:11], v[64:65] op_sel_hi:[1,0]
	v_pk_mul_f32 v[8:9], v[8:9], v[64:65] op_sel_hi:[1,0]
	v_pk_mul_f32 v[6:7], v[6:7], v[64:65] op_sel_hi:[1,0]
	v_pk_mul_f32 v[4:5], v[4:5], v[64:65] op_sel_hi:[1,0]
	v_pk_mul_f32 v[2:3], v[2:3], v[64:65] op_sel_hi:[1,0]
	v_pk_mul_f32 v[0:1], v[0:1], v[64:65] op_sel_hi:[1,0]
	v_pk_mul_f32 v[46:47], v[46:47], v[64:65] op_sel_hi:[1,0]
	v_pk_mul_f32 v[44:45], v[44:45], v[64:65] op_sel_hi:[1,0]
	v_pk_mul_f32 v[42:43], v[42:43], v[64:65] op_sel_hi:[1,0]
	v_pk_mul_f32 v[40:41], v[40:41], v[64:65] op_sel_hi:[1,0]
	v_pk_mul_f32 v[38:39], v[38:39], v[64:65] op_sel_hi:[1,0]
	v_pk_mul_f32 v[36:37], v[36:37], v[64:65] op_sel_hi:[1,0]
	v_pk_mul_f32 v[34:35], v[34:35], v[64:65] op_sel_hi:[1,0]
	v_pk_mul_f32 v[32:33], v[32:33], v[64:65] op_sel_hi:[1,0]
	v_pk_mul_f32 v[62:63], v[62:63], v[64:65] op_sel_hi:[1,0]
	v_pk_mul_f32 v[60:61], v[60:61], v[64:65] op_sel_hi:[1,0]
	v_pk_mul_f32 v[58:59], v[58:59], v[64:65] op_sel_hi:[1,0]
	v_pk_mul_f32 v[56:57], v[56:57], v[64:65] op_sel_hi:[1,0]
	v_pk_mul_f32 v[54:55], v[54:55], v[64:65] op_sel_hi:[1,0]
	v_pk_mul_f32 v[52:53], v[52:53], v[64:65] op_sel_hi:[1,0]
	v_pk_mul_f32 v[50:51], v[50:51], v[64:65] op_sel_hi:[1,0]
	v_pk_mul_f32 v[48:49], v[48:49], v[64:65] op_sel_hi:[1,0]
	v_pk_mul_f32 v[30:31], v[30:31], v[64:65] op_sel_hi:[1,0]
	v_pk_mul_f32 v[28:29], v[28:29], v[64:65] op_sel_hi:[1,0]
	v_pk_mul_f32 v[26:27], v[26:27], v[64:65] op_sel_hi:[1,0]
	v_pk_mul_f32 v[24:25], v[24:25], v[64:65] op_sel_hi:[1,0]
	v_pk_mul_f32 v[22:23], v[22:23], v[64:65] op_sel_hi:[1,0]
	v_pk_mul_f32 v[20:21], v[20:21], v[64:65] op_sel_hi:[1,0]
	v_pk_mul_f32 v[18:19], v[18:19], v[64:65] op_sel_hi:[1,0]
	v_pk_mul_f32 v[16:17], v[16:17], v[64:65] op_sel_hi:[1,0]
	v_mul_f32_e32 v176, v176, v64
	v_add_f32_e32 v64, v177, v66
	v_xor_b32_e32 v64, 0x80000000, v64
	v_pk_add_f32 v[82:83], v[82:83], v[66:67] op_sel_hi:[1,0] neg_lo:[0,1] neg_hi:[0,1]
	v_pk_add_f32 v[100:101], v[100:101], v[66:67] op_sel_hi:[1,0] neg_lo:[0,1] neg_hi:[0,1]
	v_pk_add_f32 v[84:85], v[84:85], v[66:67] op_sel_hi:[1,0] neg_lo:[0,1] neg_hi:[0,1]
	v_pk_add_f32 v[102:103], v[102:103], v[66:67] op_sel_hi:[1,0] neg_lo:[0,1] neg_hi:[0,1]
	v_pk_add_f32 v[86:87], v[86:87], v[66:67] op_sel_hi:[1,0] neg_lo:[0,1] neg_hi:[0,1]
	v_pk_add_f32 v[104:105], v[104:105], v[66:67] op_sel_hi:[1,0] neg_lo:[0,1] neg_hi:[0,1]
	v_pk_add_f32 v[88:89], v[88:89], v[66:67] op_sel_hi:[1,0] neg_lo:[0,1] neg_hi:[0,1]
	v_pk_add_f32 v[106:107], v[106:107], v[66:67] op_sel_hi:[1,0] neg_lo:[0,1] neg_hi:[0,1]
	v_pk_add_f32 v[90:91], v[90:91], v[66:67] op_sel_hi:[1,0] neg_lo:[0,1] neg_hi:[0,1]
	v_pk_add_f32 v[108:109], v[108:109], v[66:67] op_sel_hi:[1,0] neg_lo:[0,1] neg_hi:[0,1]
	v_pk_add_f32 v[92:93], v[92:93], v[66:67] op_sel_hi:[1,0] neg_lo:[0,1] neg_hi:[0,1]
	v_pk_add_f32 v[110:111], v[110:111], v[66:67] op_sel_hi:[1,0] neg_lo:[0,1] neg_hi:[0,1]
	v_pk_add_f32 v[94:95], v[94:95], v[66:67] op_sel_hi:[1,0] neg_lo:[0,1] neg_hi:[0,1]
	v_mov_b32_e32 v65, v64
	v_mov_b32_e32 v66, v64
	v_mov_b32_e32 v67, v64
	v_mov_b32_e32 v68, v64
	v_mov_b32_e32 v69, v64
	v_mov_b32_e32 v70, v64
	v_mov_b32_e32 v71, v64
	v_mov_b32_e32 v72, v64
	v_mov_b32_e32 v73, v64
	v_mov_b32_e32 v74, v64
	v_mov_b32_e32 v75, v64
	v_mov_b32_e32 v76, v64
	v_mov_b32_e32 v77, v64
	v_mov_b32_e32 v78, v64
	v_mov_b32_e32 v79, v64
.LBB0_885:
	v_exp_f32_e32 v96, v96
	v_exp_f32_e32 v97, v97
	v_exp_f32_e32 v98, v98
	v_exp_f32_e32 v99, v99
	v_exp_f32_e32 v100, v100
	v_exp_f32_e32 v101, v101
	v_exp_f32_e32 v102, v102
	v_exp_f32_e32 v103, v103
	v_cvt_pk_bf16_f32 v204, v96, v97
	v_cvt_pk_bf16_f32 v205, v98, v99
	v_cvt_pk_bf16_f32 v206, v100, v101
	v_cvt_pk_bf16_f32 v207, v102, v103
	s_waitcnt lgkmcnt(0)
	v_exp_f32_e32 v104, v104
	v_exp_f32_e32 v105, v105
	v_mfma_f32_32x32x16_bf16 v[0:15], v[172:175], v[204:207], v[0:15]
	v_exp_f32_e32 v106, v106
	v_exp_f32_e32 v107, v107
	v_exp_f32_e32 v108, v108
	v_exp_f32_e32 v109, v109
	v_exp_f32_e32 v110, v110
	v_exp_f32_e32 v111, v111
	v_cvt_pk_bf16_f32 v172, v104, v105
	v_mfma_f32_32x32x16_bf16 v[32:47], v[156:159], v[204:207], v[32:47]
	v_cvt_pk_bf16_f32 v173, v106, v107
	v_cvt_pk_bf16_f32 v174, v108, v109
	v_cvt_pk_bf16_f32 v175, v110, v111
	v_exp_f32_e32 v80, v80
	v_exp_f32_e32 v81, v81
	v_exp_f32_e32 v82, v82
	v_exp_f32_e32 v83, v83
	v_mfma_f32_32x32x16_bf16 v[0:15], v[168:171], v[172:175], v[0:15]
	v_exp_f32_e32 v84, v84
	v_exp_f32_e32 v85, v85
	v_exp_f32_e32 v86, v86
	v_exp_f32_e32 v87, v87
	v_cvt_pk_bf16_f32 v208, v80, v81
	v_cvt_pk_bf16_f32 v209, v82, v83
	v_cvt_pk_bf16_f32 v210, v84, v85
	v_mfma_f32_32x32x16_bf16 v[32:47], v[152:155], v[172:175], v[32:47]
	v_cvt_pk_bf16_f32 v211, v86, v87
	v_exp_f32_e32 v88, v88
	v_exp_f32_e32 v89, v89
	v_exp_f32_e32 v168, v90
	v_exp_f32_e32 v169, v91
	v_exp_f32_e32 v90, v92
	v_exp_f32_e32 v91, v93
	v_mfma_f32_32x32x16_bf16 v[0:15], v[164:167], v[208:211], v[0:15]
	v_exp_f32_e32 v92, v94
	v_exp_f32_e32 v93, v95
	v_cvt_pk_bf16_f32 v164, v88, v89
	v_cvt_pk_bf16_f32 v165, v168, v169
	v_cvt_pk_bf16_f32 v166, v90, v91
	v_cvt_pk_bf16_f32 v167, v92, v93
	v_mfma_f32_32x32x16_bf16 v[32:47], v[148:151], v[208:211], v[32:47]
	s_nop 0
	v_mfma_f32_32x32x16_bf16 v[0:15], v[160:163], v[164:167], v[0:15]
	v_mfma_f32_32x32x16_bf16 v[32:47], v[144:147], v[164:167], v[32:47]
	ds_read_b64 v[220:221], v189
	ds_read_b64 v[222:223], v189 offset:16
	ds_read_b64 v[216:217], v189 offset:32
	ds_read_b64 v[218:219], v189 offset:48
	ds_read_b64 v[212:213], v189 offset:64
	ds_read_b64 v[214:215], v189 offset:80
	ds_read_b64 v[160:161], v189 offset:96
	ds_read_b64 v[162:163], v189 offset:112
	ds_read_b64 v[156:157], v189 offset:0x1100
	ds_read_b64 v[158:159], v189 offset:0x1110
	ds_read_b64 v[152:153], v189 offset:0x1120
	ds_read_b64 v[154:155], v189 offset:0x1130
	ds_read_b64 v[148:149], v189 offset:0x1140
	ds_read_b64 v[150:151], v189 offset:0x1150
	ds_read_b64 v[144:145], v189 offset:0x1160
	ds_read_b64 v[146:147], v189 offset:0x1170
	s_nop 0
	s_waitcnt lgkmcnt(0)
	s_waitcnt vmcnt(2)
	ds_write_b128 v184, v[132:135] offset:32768
	v_mfma_f32_32x32x16_bf16 v[48:63], v[220:223], v[204:207], v[48:63]
	v_mfma_f32_32x32x16_bf16 v[16:31], v[156:159], v[204:207], v[16:31]
	v_mfma_f32_32x32x16_bf16 v[48:63], v[216:219], v[172:175], v[48:63]
	v_mfma_f32_32x32x16_bf16 v[16:31], v[152:155], v[172:175], v[16:31]
	v_mfma_f32_32x32x16_bf16 v[48:63], v[212:215], v[208:211], v[48:63]
	v_mfma_f32_32x32x16_bf16 v[16:31], v[148:151], v[208:211], v[16:31]
	v_mfma_f32_32x32x16_bf16 v[48:63], v[160:163], v[164:167], v[48:63]
	v_mfma_f32_32x32x16_bf16 v[16:31], v[144:147], v[164:167], v[16:31]
	s_and_saveexec_b64 s[0:1], s[2:3]
	ds_write_b128 v183, v[128:131] offset:32768
	s_or_b64 exec, exec, s[0:1]
	v_pk_add_f32 v[94:95], v[96:97], 0 op_sel_hi:[1,0]
	s_nop 0
	v_pk_add_f32 v[80:81], v[80:81], v[94:95]
	s_nop 0
	v_pk_add_f32 v[80:81], v[98:99], v[80:81]
	s_nop 0
	v_pk_add_f32 v[80:81], v[82:83], v[80:81]
	s_nop 0
	v_pk_add_f32 v[80:81], v[100:101], v[80:81]
	s_nop 0
	v_pk_add_f32 v[80:81], v[84:85], v[80:81]
	s_nop 0
	v_pk_add_f32 v[80:81], v[102:103], v[80:81]
	s_nop 0
	v_pk_add_f32 v[80:81], v[86:87], v[80:81]
	s_nop 0
	v_pk_add_f32 v[80:81], v[104:105], v[80:81]
	s_nop 0
	v_pk_add_f32 v[80:81], v[88:89], v[80:81]
	s_nop 0
	v_pk_add_f32 v[80:81], v[106:107], v[80:81]
	s_nop 0
	v_pk_add_f32 v[80:81], v[168:169], v[80:81]
	s_nop 0
	v_pk_add_f32 v[80:81], v[108:109], v[80:81]
	s_nop 0
	v_pk_add_f32 v[80:81], v[90:91], v[80:81]
	s_nop 0
	v_pk_add_f32 v[80:81], v[110:111], v[80:81]
	s_nop 0
	v_pk_add_f32 v[80:81], v[92:93], v[80:81]
	s_nop 0
	v_add_f32_e32 v80, v80, v81
	v_add_f32_e32 v128, v176, v80
	s_waitcnt vmcnt(0)
	v_perm_b32 v80, v140, v136, s85
	v_perm_b32 v81, v140, v136, s86
	ds_write2_b32 v186, v80, v81 offset1:34
	v_perm_b32 v80, v141, v137, s85
	v_perm_b32 v81, v141, v137, s86
	ds_write2_b32 v186, v80, v81 offset0:68 offset1:102
	v_perm_b32 v80, v142, v138, s85
	v_perm_b32 v81, v142, v138, s86
	ds_write2_b32 v186, v80, v81 offset0:136 offset1:170
	v_perm_b32 v80, v143, v139, s85
	v_perm_b32 v81, v143, v139, s86
	ds_write2_b32 v186, v80, v81 offset0:204 offset1:238
	s_waitcnt lgkmcnt(0)
	s_barrier
	ds_read_b128 v[96:99], v188
	ds_read_b128 v[100:103], v188 offset:0x1200
	ds_read_b128 v[104:107], v188 offset:32
	ds_read_b128 v[108:111], v188 offset:0x1220
	ds_read_b128 v[130:133], v188 offset:64
	ds_read_b128 v[134:137], v188 offset:0x1240
	ds_read_b128 v[138:141], v188 offset:96
	ds_read_b128 v[142:145], v188 offset:0x1260
	s_waitcnt lgkmcnt(0)
	s_nop 0
	v_mfma_f32_32x32x16_bf16 v[80:95], v[96:99], v[124:127], v[64:79]
	v_mfma_f32_32x32x16_bf16 v[64:79], v[100:103], v[124:127], v[64:79]
	v_mfma_f32_32x32x16_bf16 v[80:95], v[104:107], v[120:123], v[80:95]
	v_mfma_f32_32x32x16_bf16 v[64:79], v[108:111], v[120:123], v[64:79]
	v_mfma_f32_32x32x16_bf16 v[80:95], v[130:133], v[116:119], v[80:95]
	v_mfma_f32_32x32x16_bf16 v[64:79], v[134:137], v[116:119], v[64:79]
	v_mfma_f32_32x32x16_bf16 v[80:95], v[138:141], v[112:115], v[80:95]
	v_mfma_f32_32x32x16_bf16 v[64:79], v[142:145], v[112:115], v[64:79]
	s_nop 10
	ds_read_b64 v[124:125], v187
	ds_read_b64 v[126:127], v187 offset:16
	ds_read_b64 v[120:121], v187 offset:32
	ds_read_b64 v[122:123], v187 offset:48
	ds_read_b64 v[116:117], v187 offset:64
	ds_read_b64 v[118:119], v187 offset:80
	ds_read_b64 v[112:113], v187 offset:96
	ds_read_b64 v[114:115], v187 offset:112
	ds_read_b64 v[108:109], v187 offset:0x1100
	ds_read_b64 v[110:111], v187 offset:0x1110
	ds_read_b64 v[104:105], v187 offset:0x1120
	ds_read_b64 v[106:107], v187 offset:0x1130
	ds_read_b64 v[100:101], v187 offset:0x1140
	ds_read_b64 v[102:103], v187 offset:0x1150
	ds_read_b64 v[96:97], v187 offset:0x1160
	ds_read_b64 v[98:99], v187 offset:0x1170
	v_max_f32_e32 v129, v80, v64
	v_max_f32_e32 v130, v81, v65
	v_max_f32_e32 v131, v83, v67
	v_max3_f32 v131, v82, v66, v131
	v_max3_f32 v129, v129, v130, v131
	v_max_f32_e32 v130, v85, v69
	v_max_f32_e32 v131, v87, v71
	v_max3_f32 v130, v84, v68, v130
	v_max3_f32 v131, v86, v70, v131
	v_max3_f32 v129, v129, v130, v131
	v_max_f32_e32 v130, v89, v73
	v_max_f32_e32 v131, v91, v75
	v_max3_f32 v130, v88, v72, v130
	v_max3_f32 v131, v90, v74, v131
	v_max3_f32 v129, v129, v130, v131
	v_max_f32_e32 v130, v93, v77
	v_max_f32_e32 v132, v95, v95
	v_max_f32_e32 v131, v132, v79
	v_max3_f32 v130, v92, v76, v130
	v_max3_f32 v131, v94, v78, v131
	v_max3_f32 v129, v129, v130, v131
	v_mov_b32_e32 v130, v129
	s_nop 1
	v_permlane32_swap_b32_e32 v129, v130
	v_max_f32_e32 v129, v129, v130
	v_cmp_lt_f32_e32 vcc, s80, v129
	s_cbranch_vccz .LBB0_889
	v_max_f32_e32 v130, 0, v129
	v_exp_f32_e64 v132, -v130
	v_pk_add_f32 v[80:81], v[80:81], v[130:131] op_sel_hi:[1,0] neg_lo:[0,1] neg_hi:[0,1]
	v_pk_add_f32 v[64:65], v[64:65], v[130:131] op_sel_hi:[1,0] neg_lo:[0,1] neg_hi:[0,1]
	v_pk_add_f32 v[82:83], v[82:83], v[130:131] op_sel_hi:[1,0] neg_lo:[0,1] neg_hi:[0,1]
	v_pk_mul_f32 v[14:15], v[14:15], v[132:133] op_sel_hi:[1,0]
	v_pk_mul_f32 v[12:13], v[12:13], v[132:133] op_sel_hi:[1,0]
	v_pk_mul_f32 v[10:11], v[10:11], v[132:133] op_sel_hi:[1,0]
	v_pk_mul_f32 v[8:9], v[8:9], v[132:133] op_sel_hi:[1,0]
	v_pk_mul_f32 v[6:7], v[6:7], v[132:133] op_sel_hi:[1,0]
	v_pk_mul_f32 v[4:5], v[4:5], v[132:133] op_sel_hi:[1,0]
	v_pk_mul_f32 v[2:3], v[2:3], v[132:133] op_sel_hi:[1,0]
	v_pk_mul_f32 v[0:1], v[0:1], v[132:133] op_sel_hi:[1,0]
	v_pk_mul_f32 v[46:47], v[46:47], v[132:133] op_sel_hi:[1,0]
	v_pk_mul_f32 v[44:45], v[44:45], v[132:133] op_sel_hi:[1,0]
	v_pk_mul_f32 v[42:43], v[42:43], v[132:133] op_sel_hi:[1,0]
	v_pk_mul_f32 v[40:41], v[40:41], v[132:133] op_sel_hi:[1,0]
	v_pk_mul_f32 v[38:39], v[38:39], v[132:133] op_sel_hi:[1,0]
	v_pk_mul_f32 v[36:37], v[36:37], v[132:133] op_sel_hi:[1,0]
	v_pk_mul_f32 v[34:35], v[34:35], v[132:133] op_sel_hi:[1,0]
	v_pk_mul_f32 v[32:33], v[32:33], v[132:133] op_sel_hi:[1,0]
	v_pk_mul_f32 v[62:63], v[62:63], v[132:133] op_sel_hi:[1,0]
	v_pk_mul_f32 v[60:61], v[60:61], v[132:133] op_sel_hi:[1,0]
	v_pk_mul_f32 v[58:59], v[58:59], v[132:133] op_sel_hi:[1,0]
	v_pk_mul_f32 v[56:57], v[56:57], v[132:133] op_sel_hi:[1,0]
	v_pk_mul_f32 v[54:55], v[54:55], v[132:133] op_sel_hi:[1,0]
	v_pk_mul_f32 v[52:53], v[52:53], v[132:133] op_sel_hi:[1,0]
	v_pk_mul_f32 v[50:51], v[50:51], v[132:133] op_sel_hi:[1,0]
	v_pk_mul_f32 v[48:49], v[48:49], v[132:133] op_sel_hi:[1,0]
	v_pk_mul_f32 v[30:31], v[30:31], v[132:133] op_sel_hi:[1,0]
	v_pk_mul_f32 v[28:29], v[28:29], v[132:133] op_sel_hi:[1,0]
	v_pk_mul_f32 v[26:27], v[26:27], v[132:133] op_sel_hi:[1,0]
	v_pk_mul_f32 v[24:25], v[24:25], v[132:133] op_sel_hi:[1,0]
	v_pk_mul_f32 v[22:23], v[22:23], v[132:133] op_sel_hi:[1,0]
	v_pk_mul_f32 v[20:21], v[20:21], v[132:133] op_sel_hi:[1,0]
	v_pk_mul_f32 v[18:19], v[18:19], v[132:133] op_sel_hi:[1,0]
	v_pk_mul_f32 v[16:17], v[16:17], v[132:133] op_sel_hi:[1,0]
	v_mul_f32_e32 v128, v128, v132
	v_pk_add_f32 v[66:67], v[66:67], v[130:131] op_sel_hi:[1,0] neg_lo:[0,1] neg_hi:[0,1]
	v_pk_add_f32 v[84:85], v[84:85], v[130:131] op_sel_hi:[1,0] neg_lo:[0,1] neg_hi:[0,1]
	v_pk_add_f32 v[68:69], v[68:69], v[130:131] op_sel_hi:[1,0] neg_lo:[0,1] neg_hi:[0,1]
	v_pk_add_f32 v[86:87], v[86:87], v[130:131] op_sel_hi:[1,0] neg_lo:[0,1] neg_hi:[0,1]
	v_pk_add_f32 v[70:71], v[70:71], v[130:131] op_sel_hi:[1,0] neg_lo:[0,1] neg_hi:[0,1]
	v_pk_add_f32 v[88:89], v[88:89], v[130:131] op_sel_hi:[1,0] neg_lo:[0,1] neg_hi:[0,1]
	v_pk_add_f32 v[72:73], v[72:73], v[130:131] op_sel_hi:[1,0] neg_lo:[0,1] neg_hi:[0,1]
	v_pk_add_f32 v[90:91], v[90:91], v[130:131] op_sel_hi:[1,0] neg_lo:[0,1] neg_hi:[0,1]
	v_pk_add_f32 v[74:75], v[74:75], v[130:131] op_sel_hi:[1,0] neg_lo:[0,1] neg_hi:[0,1]
	v_pk_add_f32 v[92:93], v[92:93], v[130:131] op_sel_hi:[1,0] neg_lo:[0,1] neg_hi:[0,1]
	v_pk_add_f32 v[76:77], v[76:77], v[130:131] op_sel_hi:[1,0] neg_lo:[0,1] neg_hi:[0,1]
	v_pk_add_f32 v[94:95], v[94:95], v[130:131] op_sel_hi:[1,0] neg_lo:[0,1] neg_hi:[0,1]
	v_pk_add_f32 v[78:79], v[78:79], v[130:131] op_sel_hi:[1,0] neg_lo:[0,1] neg_hi:[0,1]

.LBB0_895:
	s_or_b64 exec, exec, s[0:1]
	v_add_co_u32_e32 v0, vcc, 0x4000, v110
	v_mad_u32_u24 v58, v32, s17, 0
	s_nop 0
	v_addc_co_u32_e32 v1, vcc, 0, v111, vcc
	global_load_dwordx4 v[68:71], v[0:1], off
	global_load_dwordx4 v[72:75], v[0:1], off offset:256
	v_add_u32_e32 v205, v58, v192
	ds_read_b128 v[0:3], v205
	ds_read_b128 v[16:19], v205 offset:0x1200
	ds_read_b128 v[34:37], v205 offset:32
	ds_read_b128 v[38:41], v205 offset:0x1220
	ds_read_b128 v[42:45], v205 offset:64
	ds_read_b128 v[46:49], v205 offset:0x1240
	ds_read_b128 v[50:53], v205 offset:96
	ds_read_b128 v[54:57], v205 offset:0x1260
	s_waitcnt lgkmcnt(0)
	v_lshlrev_b32_e32 v139, 3, v32
	v_mfma_f32_32x32x16_bf16 v[0:15], v[0:3], v[124:127], 0
	v_lshlrev_b32_e32 v138, 3, v33
	v_sub_u32_e32 v140, v58, v139
	v_add_u32_e32 v99, v140, v138
	v_add_u32_e32 v204, 0x3400, v99
	v_add_u32_e32 v191, 0x5600, v99
	v_mfma_f32_32x32x16_bf16 v[16:31], v[16:19], v[124:127], 0
	v_mfma_f32_32x32x16_bf16 v[0:15], v[34:37], v[120:123], v[0:15]
	v_mfma_f32_32x32x16_bf16 v[16:31], v[38:41], v[120:123], v[16:31]
	v_mfma_f32_32x32x16_bf16 v[0:15], v[42:45], v[116:119], v[0:15]
	v_mfma_f32_32x32x16_bf16 v[16:31], v[46:49], v[116:119], v[16:31]
	v_mfma_f32_32x32x16_bf16 v[16:31], v[54:57], v[112:115], v[16:31]
	ds_read_b64 v[54:55], v204
	ds_read_b64 v[56:57], v204 offset:16
	ds_read_b64 v[44:45], v204 offset:32
	ds_read_b64 v[46:47], v204 offset:48
	ds_read_b64 v[40:41], v204 offset:64
	ds_read_b64 v[42:43], v204 offset:80
	ds_read_b64 v[36:37], v204 offset:96
	ds_read_b64 v[38:39], v204 offset:112
	ds_read_b64 v[32:33], v204 offset:0x1100
	ds_read_b64 v[34:35], v204 offset:0x1110
	ds_read_b64 v[146:147], v204 offset:0x1120
	ds_read_b64 v[148:149], v204 offset:0x1130
	ds_read_b64 v[142:143], v204 offset:0x1140
	ds_read_b64 v[144:145], v204 offset:0x1150
	ds_read_b64 v[76:77], v204 offset:0x1160
	ds_read_b64 v[78:79], v204 offset:0x1170
	s_nop 0
	s_waitcnt lgkmcnt(0)
	v_mfma_f32_32x32x16_bf16 v[0:15], v[50:53], v[112:115], v[0:15]
	s_nop 10
	s_nop 0
	v_max_f32_e32 v48, v0, v16
	v_max_f32_e32 v49, v1, v17
	v_max_f32_e32 v50, v3, v19
	v_max3_f32 v50, v2, v18, v50
	v_max3_f32 v48, v48, v49, v50
	v_max_f32_e32 v49, v5, v21
	v_max_f32_e32 v50, v7, v23
	v_max3_f32 v49, v4, v20, v49
	v_max3_f32 v50, v6, v22, v50
	v_max3_f32 v48, v48, v49, v50
	v_max_f32_e32 v49, v9, v25
	v_max_f32_e32 v50, v11, v27
	v_max3_f32 v49, v8, v24, v49
	v_max3_f32 v50, v10, v26, v50
	v_max3_f32 v48, v48, v49, v50
	v_max_f32_e32 v49, v13, v29
	v_max_f32_e32 v50, v15, v31
	v_max3_f32 v49, v12, v28, v49
	v_max3_f32 v50, v14, v30, v50
	v_max3_f32 v48, v48, v49, v50
	v_mov_b32_e32 v49, v48
	s_nop 1
	v_permlane32_swap_b32_e32 v48, v49
	v_max_f32_e32 v141, v48, v49
	v_sub_f32_e32 v0, v0, v141
	v_sub_f32_e32 v1, v1, v141
	v_sub_f32_e32 v2, v2, v141
	v_sub_f32_e32 v3, v3, v141
	v_sub_f32_e32 v4, v4, v141
	v_sub_f32_e32 v5, v5, v141
	v_sub_f32_e32 v6, v6, v141
	v_sub_f32_e32 v7, v7, v141
	v_exp_f32_e32 v80, v0
	v_exp_f32_e32 v81, v1
	v_exp_f32_e32 v84, v2
	v_exp_f32_e32 v85, v3
	v_exp_f32_e32 v88, v4
	v_exp_f32_e32 v89, v5
	v_exp_f32_e32 v92, v6
	v_exp_f32_e32 v93, v7
	v_cvt_pk_bf16_f32 v0, v80, v81
	v_cvt_pk_bf16_f32 v1, v84, v85
	v_cvt_pk_bf16_f32 v2, v88, v89
	v_cvt_pk_bf16_f32 v3, v92, v93
	v_sub_f32_e32 v8, v8, v141
	v_sub_f32_e32 v9, v9, v141
	v_mfma_f32_32x32x16_bf16 v[48:63], v[54:57], v[0:3], 0
	v_sub_f32_e32 v10, v10, v141
	v_sub_f32_e32 v11, v11, v141
	v_sub_f32_e32 v12, v12, v141
	v_sub_f32_e32 v13, v13, v141
	v_sub_f32_e32 v14, v14, v141
	v_sub_f32_e32 v15, v15, v141
	v_exp_f32_e32 v96, v8
	v_exp_f32_e32 v97, v9
	v_exp_f32_e32 v104, v10
	v_exp_f32_e32 v105, v11
	v_exp_f32_e32 v106, v12
	v_exp_f32_e32 v107, v13
	v_exp_f32_e32 v108, v14
	v_exp_f32_e32 v109, v15
	v_cvt_pk_bf16_f32 v150, v96, v97
	v_cvt_pk_bf16_f32 v151, v104, v105
	v_cvt_pk_bf16_f32 v152, v106, v107
	v_cvt_pk_bf16_f32 v153, v108, v109
	v_sub_f32_e32 v16, v16, v141
	v_sub_f32_e32 v17, v17, v141
	v_mfma_f32_32x32x16_bf16 v[48:63], v[44:47], v[150:153], v[48:63]
	v_sub_f32_e32 v18, v18, v141
	v_sub_f32_e32 v19, v19, v141
	v_sub_f32_e32 v20, v20, v141
	v_sub_f32_e32 v21, v21, v141
	v_sub_f32_e32 v22, v22, v141
	v_sub_f32_e32 v23, v23, v141
	v_exp_f32_e32 v82, v16
	v_exp_f32_e32 v83, v17
	v_exp_f32_e32 v86, v18
	v_exp_f32_e32 v87, v19
	v_exp_f32_e32 v90, v20
	v_exp_f32_e32 v91, v21
	v_exp_f32_e32 v94, v22
	v_exp_f32_e32 v95, v23
	v_cvt_pk_bf16_f32 v154, v82, v83
	v_cvt_pk_bf16_f32 v155, v86, v87
	v_cvt_pk_bf16_f32 v156, v90, v91
	v_cvt_pk_bf16_f32 v157, v94, v95
	v_sub_f32_e32 v24, v24, v141
	v_sub_f32_e32 v25, v25, v141
	v_mfma_f32_32x32x16_bf16 v[48:63], v[40:43], v[154:157], v[48:63]
	v_sub_f32_e32 v26, v26, v141
	v_sub_f32_e32 v27, v27, v141
	v_sub_f32_e32 v28, v28, v141
	v_sub_f32_e32 v29, v29, v141
	v_sub_f32_e32 v30, v30, v141
	v_sub_f32_e32 v31, v31, v141
	v_exp_f32_e32 v102, v24
	v_exp_f32_e32 v103, v25
	v_exp_f32_e32 v134, v26
	v_exp_f32_e32 v135, v27
	v_exp_f32_e32 v132, v28
	v_exp_f32_e32 v133, v29
	v_exp_f32_e32 v136, v30
	v_exp_f32_e32 v137, v31
	v_cvt_pk_bf16_f32 v158, v102, v103
	v_cvt_pk_bf16_f32 v159, v134, v135
	v_cvt_pk_bf16_f32 v160, v132, v133
	v_cvt_pk_bf16_f32 v161, v136, v137
	s_nop 1
	v_mfma_f32_32x32x16_bf16 v[48:63], v[36:39], v[158:161], v[48:63]
	v_mfma_f32_32x32x16_bf16 v[32:47], v[32:35], v[0:3], 0
	v_mfma_f32_32x32x16_bf16 v[32:47], v[146:149], v[150:153], v[32:47]
	v_mfma_f32_32x32x16_bf16 v[32:47], v[142:145], v[154:157], v[32:47]
	v_mfma_f32_32x32x16_bf16 v[32:47], v[76:79], v[158:161], v[32:47]
	ds_read_b64 v[16:17], v191
	ds_read_b64 v[18:19], v191 offset:16
	ds_read_b64 v[168:169], v191 offset:32
	ds_read_b64 v[170:171], v191 offset:48
	ds_read_b64 v[12:13], v191 offset:64
	ds_read_b64 v[14:15], v191 offset:80
	ds_read_b64 v[8:9], v191 offset:96
	ds_read_b64 v[10:11], v191 offset:112
	ds_read_b64 v[4:5], v191 offset:0x1100
	ds_read_b64 v[6:7], v191 offset:0x1110
	ds_read_b64 v[146:147], v191 offset:0x1120
	ds_read_b64 v[148:149], v191 offset:0x1130
	ds_read_b64 v[142:143], v191 offset:0x1140
	ds_read_b64 v[144:145], v191 offset:0x1150
	ds_read_b64 v[76:77], v191 offset:0x1160
	ds_read_b64 v[78:79], v191 offset:0x1170
	s_nop 0
	s_waitcnt lgkmcnt(0)
	s_waitcnt vmcnt(2)
	ds_write_b128 v186, v[64:67] offset:32768
	v_mfma_f32_32x32x16_bf16 v[16:31], v[16:19], v[0:3], 0
	v_mfma_f32_32x32x16_bf16 v[16:31], v[168:171], v[150:153], v[16:31]
	v_mfma_f32_32x32x16_bf16 v[16:31], v[12:15], v[154:157], v[16:31]
	v_mfma_f32_32x32x16_bf16 v[16:31], v[8:11], v[158:161], v[16:31]
	v_mfma_f32_32x32x16_bf16 v[0:15], v[4:7], v[0:3], 0
	v_mfma_f32_32x32x16_bf16 v[0:15], v[146:149], v[150:153], v[0:15]
	v_mfma_f32_32x32x16_bf16 v[0:15], v[142:145], v[154:157], v[0:15]
	v_mfma_f32_32x32x16_bf16 v[0:15], v[76:79], v[158:161], v[0:15]
	s_and_saveexec_b64 s[0:1], s[2:3]
	ds_write_b128 v185, v[128:131] offset:32768
	s_or_b64 exec, exec, s[0:1]
	s_waitcnt vmcnt(0)
	v_perm_b32 v64, v72, v68, s85
	v_perm_b32 v65, v72, v68, s86
	v_add_u32_e32 v188, 0xb400, v98
	ds_write2_b32 v188, v64, v65 offset1:34
	v_perm_b32 v64, v73, v69, s85
	v_perm_b32 v65, v73, v69, s86
	ds_write2_b32 v188, v64, v65 offset0:68 offset1:102
	v_perm_b32 v64, v74, v70, s85
	v_perm_b32 v65, v74, v70, s86
	ds_write2_b32 v188, v64, v65 offset0:136 offset1:170
	v_perm_b32 v64, v75, v71, s85
	v_perm_b32 v65, v75, v71, s86
	ds_write2_b32 v188, v64, v65 offset0:204 offset1:238
	v_add_co_u32_e32 v64, vcc, 0x4000, v166
	s_waitcnt lgkmcnt(0)
	s_nop 0
	v_addc_co_u32_e32 v65, vcc, 0, v167, vcc
	s_barrier
	global_load_dwordx4 v[98:101], v[64:65], off
	s_and_saveexec_b64 s[0:1], s[2:3]
	s_cbranch_execz .LBB0_899
	v_add_co_u32_e32 v64, vcc, 0x4000, v164
	s_nop 1
	v_addc_co_u32_e32 v65, vcc, 0, v165, vcc
	global_load_dwordx4 v[128:131], v[64:65], off
.LBB0_899:
	s_or_b64 exec, exec, s[0:1]
	v_pk_add_f32 v[64:65], v[80:81], 0 op_sel_hi:[1,0]
	s_mov_b32 s0, 0x8000
	v_pk_add_f32 v[64:65], v[82:83], v[64:65]
	v_add_co_u32_e32 v80, vcc, s0, v110
	v_pk_add_f32 v[64:65], v[84:85], v[64:65]
	s_nop 0
	v_addc_co_u32_e32 v81, vcc, 0, v111, vcc
	v_pk_add_f32 v[64:65], v[86:87], v[64:65]
	v_sub_u32_e32 v172, 0, v139
	v_pk_add_f32 v[64:65], v[88:89], v[64:65]
	s_nop 0
	v_pk_add_f32 v[64:65], v[90:91], v[64:65]
	s_nop 0
	v_pk_add_f32 v[64:65], v[92:93], v[64:65]
	s_nop 0
	v_pk_add_f32 v[64:65], v[94:95], v[64:65]
	s_nop 0
	v_pk_add_f32 v[64:65], v[96:97], v[64:65]
	s_nop 0
	v_pk_add_f32 v[64:65], v[102:103], v[64:65]
	s_nop 0
	v_pk_add_f32 v[64:65], v[104:105], v[64:65]
	s_nop 0
	v_pk_add_f32 v[64:65], v[134:135], v[64:65]
	s_nop 0
	v_pk_add_f32 v[64:65], v[106:107], v[64:65]
	s_nop 0
	v_pk_add_f32 v[64:65], v[132:133], v[64:65]
	s_nop 0
	v_pk_add_f32 v[64:65], v[108:109], v[64:65]
	global_load_dwordx4 v[102:105], v[80:81], off
	global_load_dwordx4 v[106:109], v[80:81], off offset:256
	v_pk_add_f32 v[64:65], v[136:137], v[64:65]
	v_add_u32_e32 v136, v140, v139
	v_pk_add_f32 v[64:65], v[64:65], v[64:65] op_sel:[0,1] op_sel_hi:[1,0]
	v_add3_u32 v190, v136, v192, s0
	v_mov_b32_e32 v65, v141
	v_pk_add_f32 v[176:177], v[64:65], 0 op_sel_hi:[1,0]
	ds_read_b128 v[132:135], v190
	ds_read_b128 v[140:143], v190 offset:0x1200
	ds_read_b128 v[144:147], v190 offset:32
	ds_read_b128 v[148:151], v190 offset:0x1220
	ds_read_b128 v[152:155], v190 offset:64
	ds_read_b128 v[156:159], v190 offset:0x1240
	ds_read_b128 v[160:163], v190 offset:96
	ds_read_b128 v[168:171], v190 offset:0x1260
	s_waitcnt lgkmcnt(0)
	s_mov_b32 s0, 0xb400
	v_xor_b32_e32 v64, 0x80000000, v177
	v_mov_b32_e32 v65, v64
	v_mov_b32_e32 v66, v64
	v_mov_b32_e32 v67, v64
	v_mov_b32_e32 v68, v64
	v_mov_b32_e32 v69, v64
	v_mov_b32_e32 v70, v64
	v_mov_b32_e32 v71, v64
	v_mov_b32_e32 v72, v64
	v_mov_b32_e32 v73, v64
	v_mov_b32_e32 v74, v64
	v_mov_b32_e32 v75, v64
	v_mov_b32_e32 v76, v64
	v_mov_b32_e32 v77, v64
	v_mov_b32_e32 v78, v64
	v_mov_b32_e32 v79, v64
	s_nop 1
	v_mfma_f32_32x32x16_bf16 v[82:97], v[132:135], v[124:127], v[64:79]
	v_mov_b64_e32 v[80:81], v[78:79]
	s_nop 5
	v_mov_b64_e32 v[78:79], v[76:77]
	v_mov_b64_e32 v[76:77], v[74:75]
	v_mov_b64_e32 v[74:75], v[72:73]
	v_mov_b64_e32 v[72:73], v[70:71]
	v_mov_b64_e32 v[70:71], v[68:69]
	v_mov_b64_e32 v[68:69], v[66:67]
	v_mov_b64_e32 v[66:67], v[64:65]
	v_mfma_f32_32x32x16_bf16 v[82:97], v[144:147], v[120:123], v[82:97]
	v_add_u32_e32 v65, v136, v172
	v_add3_u32 v189, v65, v138, s0
	v_mfma_f32_32x32x16_bf16 v[66:81], v[140:143], v[124:127], v[66:81]
	v_mfma_f32_32x32x16_bf16 v[66:81], v[148:151], v[120:123], v[66:81]
	v_mfma_f32_32x32x16_bf16 v[82:97], v[152:155], v[116:119], v[82:97]
	v_mfma_f32_32x32x16_bf16 v[66:81], v[156:159], v[116:119], v[66:81]
	v_mfma_f32_32x32x16_bf16 v[82:97], v[160:163], v[112:115], v[82:97]
	ds_read_b64 v[160:161], v189
	ds_read_b64 v[162:163], v189 offset:16
	ds_read_b64 v[156:157], v189 offset:32
	ds_read_b64 v[158:159], v189 offset:48
	ds_read_b64 v[152:153], v189 offset:64
	ds_read_b64 v[154:155], v189 offset:80
	ds_read_b64 v[148:149], v189 offset:96
	ds_read_b64 v[150:151], v189 offset:112
	ds_read_b64 v[144:145], v189 offset:0x1100
	ds_read_b64 v[146:147], v189 offset:0x1110
	ds_read_b64 v[140:141], v189 offset:0x1120
	ds_read_b64 v[142:143], v189 offset:0x1130
	ds_read_b64 v[136:137], v189 offset:0x1140
	ds_read_b64 v[138:139], v189 offset:0x1150
	ds_read_b64 v[132:133], v189 offset:0x1160
	ds_read_b64 v[134:135], v189 offset:0x1170
	v_mfma_f32_32x32x16_bf16 v[66:81], v[168:171], v[112:115], v[66:81]
	s_nop 11
	v_max_f32_e32 v65, v82, v66
	v_max_f32_e32 v168, v83, v67
	v_max_f32_e32 v169, v85, v69
	v_max3_f32 v169, v84, v68, v169
	v_max3_f32 v65, v65, v168, v169
	v_max_f32_e32 v168, v87, v71
	v_max_f32_e32 v169, v89, v73
	v_max3_f32 v168, v86, v70, v168
	v_max3_f32 v169, v88, v72, v169
	v_max3_f32 v65, v65, v168, v169
	v_max_f32_e32 v168, v91, v75
	v_max_f32_e32 v169, v93, v77
	v_max3_f32 v168, v90, v74, v168
	v_max3_f32 v169, v92, v76, v169
	v_max3_f32 v65, v65, v168, v169
	v_max_f32_e32 v168, v95, v79
	v_max_f32_e32 v170, v97, v97
	v_max_f32_e32 v169, v170, v81
	v_max3_f32 v168, v94, v78, v168
	v_max3_f32 v169, v96, v80, v169
	v_max3_f32 v65, v65, v168, v169
	v_mov_b32_e32 v168, v65
	s_nop 1
	v_permlane32_swap_b32_e32 v65, v168
	v_max_f32_e32 v65, v65, v168
	v_cmp_lt_f32_e32 vcc, s80, v65
	s_cbranch_vccz .LBB0_901
	v_max_f32_e32 v168, 0, v65
	v_exp_f32_e64 v170, -v168
	v_add_f32_e32 v177, v177, v168
	v_xor_b32_e32 v64, 0x80000000, v177
	v_pk_add_f32 v[82:83], v[82:83], v[168:169] op_sel_hi:[1,0] neg_lo:[0,1] neg_hi:[0,1]
	v_pk_mul_f32 v[62:63], v[62:63], v[170:171] op_sel_hi:[1,0]
	v_pk_mul_f32 v[60:61], v[60:61], v[170:171] op_sel_hi:[1,0]
	v_pk_mul_f32 v[58:59], v[58:59], v[170:171] op_sel_hi:[1,0]
	v_pk_mul_f32 v[56:57], v[56:57], v[170:171] op_sel_hi:[1,0]
	v_pk_mul_f32 v[54:55], v[54:55], v[170:171] op_sel_hi:[1,0]
	v_pk_mul_f32 v[52:53], v[52:53], v[170:171] op_sel_hi:[1,0]
	v_pk_mul_f32 v[50:51], v[50:51], v[170:171] op_sel_hi:[1,0]
	v_pk_mul_f32 v[48:49], v[48:49], v[170:171] op_sel_hi:[1,0]
	v_pk_mul_f32 v[46:47], v[46:47], v[170:171] op_sel_hi:[1,0]
	v_pk_mul_f32 v[44:45], v[44:45], v[170:171] op_sel_hi:[1,0]
	v_pk_mul_f32 v[42:43], v[42:43], v[170:171] op_sel_hi:[1,0]
	v_pk_mul_f32 v[40:41], v[40:41], v[170:171] op_sel_hi:[1,0]
	v_pk_mul_f32 v[38:39], v[38:39], v[170:171] op_sel_hi:[1,0]
	v_pk_mul_f32 v[36:37], v[36:37], v[170:171] op_sel_hi:[1,0]
	v_pk_mul_f32 v[34:35], v[34:35], v[170:171] op_sel_hi:[1,0]
	v_pk_mul_f32 v[32:33], v[32:33], v[170:171] op_sel_hi:[1,0]
	v_pk_mul_f32 v[30:31], v[30:31], v[170:171] op_sel_hi:[1,0]
	v_pk_mul_f32 v[28:29], v[28:29], v[170:171] op_sel_hi:[1,0]
	v_pk_mul_f32 v[26:27], v[26:27], v[170:171] op_sel_hi:[1,0]
	v_pk_mul_f32 v[24:25], v[24:25], v[170:171] op_sel_hi:[1,0]
	v_pk_mul_f32 v[22:23], v[22:23], v[170:171] op_sel_hi:[1,0]
	v_pk_mul_f32 v[20:21], v[20:21], v[170:171] op_sel_hi:[1,0]
	v_pk_mul_f32 v[18:19], v[18:19], v[170:171] op_sel_hi:[1,0]
	v_pk_mul_f32 v[16:17], v[16:17], v[170:171] op_sel_hi:[1,0]
	v_pk_mul_f32 v[14:15], v[14:15], v[170:171] op_sel_hi:[1,0]
	v_pk_mul_f32 v[12:13], v[12:13], v[170:171] op_sel_hi:[1,0]
	v_pk_mul_f32 v[10:11], v[10:11], v[170:171] op_sel_hi:[1,0]
	v_pk_mul_f32 v[8:9], v[8:9], v[170:171] op_sel_hi:[1,0]
	v_pk_mul_f32 v[6:7], v[6:7], v[170:171] op_sel_hi:[1,0]
	v_pk_mul_f32 v[4:5], v[4:5], v[170:171] op_sel_hi:[1,0]
	v_pk_mul_f32 v[2:3], v[2:3], v[170:171] op_sel_hi:[1,0]
	v_pk_mul_f32 v[0:1], v[0:1], v[170:171] op_sel_hi:[1,0]
	v_pk_add_f32 v[66:67], v[66:67], v[168:169] op_sel_hi:[1,0] neg_lo:[0,1] neg_hi:[0,1]
	v_pk_add_f32 v[84:85], v[84:85], v[168:169] op_sel_hi:[1,0] neg_lo:[0,1] neg_hi:[0,1]
	v_pk_add_f32 v[68:69], v[68:69], v[168:169] op_sel_hi:[1,0] neg_lo:[0,1] neg_hi:[0,1]
	v_pk_add_f32 v[86:87], v[86:87], v[168:169] op_sel_hi:[1,0] neg_lo:[0,1] neg_hi:[0,1]
	v_pk_add_f32 v[70:71], v[70:71], v[168:169] op_sel_hi:[1,0] neg_lo:[0,1] neg_hi:[0,1]
	v_pk_add_f32 v[88:89], v[88:89], v[168:169] op_sel_hi:[1,0] neg_lo:[0,1] neg_hi:[0,1]
	v_pk_add_f32 v[72:73], v[72:73], v[168:169] op_sel_hi:[1,0] neg_lo:[0,1] neg_hi:[0,1]
	v_pk_add_f32 v[90:91], v[90:91], v[168:169] op_sel_hi:[1,0] neg_lo:[0,1] neg_hi:[0,1]
	v_pk_add_f32 v[74:75], v[74:75], v[168:169] op_sel_hi:[1,0] neg_lo:[0,1] neg_hi:[0,1]
	v_pk_add_f32 v[92:93], v[92:93], v[168:169] op_sel_hi:[1,0] neg_lo:[0,1] neg_hi:[0,1]
	v_pk_add_f32 v[76:77], v[76:77], v[168:169] op_sel_hi:[1,0] neg_lo:[0,1] neg_hi:[0,1]
	v_pk_add_f32 v[94:95], v[94:95], v[168:169] op_sel_hi:[1,0] neg_lo:[0,1] neg_hi:[0,1]
	v_pk_add_f32 v[78:79], v[78:79], v[168:169] op_sel_hi:[1,0] neg_lo:[0,1] neg_hi:[0,1]
	v_pk_add_f32 v[96:97], v[96:97], v[168:169] op_sel_hi:[1,0] neg_lo:[0,1] neg_hi:[0,1]
	v_pk_add_f32 v[80:81], v[80:81], v[168:169] op_sel_hi:[1,0] neg_lo:[0,1] neg_hi:[0,1]
	v_mul_f32_e32 v176, v176, v170

.LBB0_905:
	s_or_b64 exec, exec, s[0:1]
	v_pk_add_f32 v[82:83], v[82:83], 0 op_sel_hi:[1,0]
	s_mov_b32 s0, 0xc000
	v_pk_add_f32 v[82:83], v[168:169], v[82:83]
	v_mov_b32_e32 v65, v64
	v_pk_add_f32 v[82:83], v[84:85], v[82:83]
	v_mov_b32_e32 v66, v64
	v_pk_add_f32 v[82:83], v[170:171], v[82:83]
	v_mov_b32_e32 v67, v64
	v_pk_add_f32 v[82:83], v[86:87], v[82:83]
	v_mov_b32_e32 v68, v64
	v_pk_add_f32 v[82:83], v[172:173], v[82:83]
	v_mov_b32_e32 v69, v64
	v_pk_add_f32 v[82:83], v[88:89], v[82:83]
	v_mov_b32_e32 v70, v64
	v_pk_add_f32 v[82:83], v[174:175], v[82:83]
	v_mov_b32_e32 v71, v64
	v_pk_add_f32 v[82:83], v[90:91], v[82:83]
	v_mov_b32_e32 v72, v64
	v_pk_add_f32 v[82:83], v[178:179], v[82:83]
	v_mov_b32_e32 v73, v64
	v_pk_add_f32 v[82:83], v[92:93], v[82:83]
	v_mov_b32_e32 v74, v64
	v_pk_add_f32 v[82:83], v[158:159], v[82:83]
	v_mov_b32_e32 v75, v64
	v_pk_add_f32 v[82:83], v[94:95], v[82:83]
	v_mov_b32_e32 v76, v64
	v_pk_add_f32 v[82:83], v[156:157], v[82:83]
	v_mov_b32_e32 v77, v64
	v_pk_add_f32 v[82:83], v[96:97], v[82:83]
	v_mov_b32_e32 v78, v64
	v_pk_add_f32 v[80:81], v[80:81], v[82:83]
	v_mov_b32_e32 v79, v64
	v_add_f32_e32 v80, v80, v81
	v_add_f32_e32 v176, v176, v80
	v_add_co_u32_e32 v80, vcc, s0, v110
	s_nop 1
	v_addc_co_u32_e32 v81, vcc, 0, v111, vcc
	global_load_dwordx4 v[136:139], v[80:81], off
	global_load_dwordx4 v[140:143], v[80:81], off offset:256
	ds_read_b128 v[80:83], v205
	ds_read_b128 v[144:147], v205 offset:0x1200
	ds_read_b128 v[148:151], v205 offset:32
	ds_read_b128 v[152:155], v205 offset:0x1220
	ds_read_b128 v[156:159], v205 offset:64
	ds_read_b128 v[160:163], v205 offset:0x1240
	ds_read_b128 v[164:167], v205 offset:96
	ds_read_b128 v[168:171], v205 offset:0x1260
	s_waitcnt lgkmcnt(0)
	s_nop 0
	v_mfma_f32_32x32x16_bf16 v[96:111], v[80:83], v[124:127], v[64:79]
	v_mfma_f32_32x32x16_bf16 v[80:95], v[144:147], v[124:127], v[64:79]
	v_mfma_f32_32x32x16_bf16 v[96:111], v[148:151], v[120:123], v[96:111]
	v_mfma_f32_32x32x16_bf16 v[80:95], v[152:155], v[120:123], v[80:95]
	v_mfma_f32_32x32x16_bf16 v[96:111], v[156:159], v[116:119], v[96:111]
	v_mfma_f32_32x32x16_bf16 v[80:95], v[160:163], v[116:119], v[80:95]
	v_mfma_f32_32x32x16_bf16 v[96:111], v[164:167], v[112:115], v[96:111]
	v_mfma_f32_32x32x16_bf16 v[80:95], v[168:171], v[112:115], v[80:95]
	s_nop 10
	ds_read_b64 v[172:173], v204
	ds_read_b64 v[174:175], v204 offset:16
	ds_read_b64 v[168:169], v204 offset:32
	ds_read_b64 v[170:171], v204 offset:48
	ds_read_b64 v[164:165], v204 offset:64
	ds_read_b64 v[166:167], v204 offset:80
	ds_read_b64 v[160:161], v204 offset:96
	ds_read_b64 v[162:163], v204 offset:112
	ds_read_b64 v[156:157], v204 offset:0x1100
	ds_read_b64 v[158:159], v204 offset:0x1110
	ds_read_b64 v[152:153], v204 offset:0x1120
	ds_read_b64 v[154:155], v204 offset:0x1130
	ds_read_b64 v[148:149], v204 offset:0x1140
	ds_read_b64 v[150:151], v204 offset:0x1150
	ds_read_b64 v[144:145], v204 offset:0x1160
	ds_read_b64 v[146:147], v204 offset:0x1170
	v_max_f32_e32 v178, v96, v80
	v_max_f32_e32 v179, v97, v81
	v_max_f32_e32 v192, v99, v83
	v_max3_f32 v192, v98, v82, v192
	v_max3_f32 v178, v178, v179, v192
	v_max_f32_e32 v179, v101, v85
	v_max_f32_e32 v192, v103, v87
	v_max3_f32 v179, v100, v84, v179
	v_max3_f32 v192, v102, v86, v192
	v_max3_f32 v178, v178, v179, v192
	v_max_f32_e32 v179, v105, v89
	v_max_f32_e32 v192, v107, v91
	v_max3_f32 v179, v104, v88, v179
	v_max3_f32 v192, v106, v90, v192
	v_max3_f32 v178, v178, v179, v192
	v_max_f32_e32 v179, v109, v93
	v_max_f32_e32 v204, v111, v111
	v_max_f32_e32 v192, v204, v95
	v_max3_f32 v179, v108, v92, v179
	v_max3_f32 v192, v110, v94, v192
	v_max3_f32 v178, v178, v179, v192
	v_mov_b32_e32 v179, v178
	s_nop 1
	v_permlane32_swap_b32_e32 v178, v179
	v_max_f32_e32 v178, v178, v179
	v_cmp_lt_f32_e32 vcc, s80, v178
	s_cbranch_vccz .LBB0_907
	v_max_f32_e32 v66, 0, v178
	v_exp_f32_e64 v64, -v66
	v_pk_add_f32 v[96:97], v[96:97], v[66:67] op_sel_hi:[1,0] neg_lo:[0,1] neg_hi:[0,1]
	v_pk_add_f32 v[80:81], v[80:81], v[66:67] op_sel_hi:[1,0] neg_lo:[0,1] neg_hi:[0,1]
	v_pk_add_f32 v[98:99], v[98:99], v[66:67] op_sel_hi:[1,0] neg_lo:[0,1] neg_hi:[0,1]
	v_pk_mul_f32 v[62:63], v[62:63], v[64:65] op_sel_hi:[1,0]
	v_pk_mul_f32 v[60:61], v[60:61], v[64:65] op_sel_hi:[1,0]
	v_pk_mul_f32 v[58:59], v[58:59], v[64:65] op_sel_hi:[1,0]
	v_pk_mul_f32 v[56:57], v[56:57], v[64:65] op_sel_hi:[1,0]
	v_pk_mul_f32 v[54:55], v[54:55], v[64:65] op_sel_hi:[1,0]
	v_pk_mul_f32 v[52:53], v[52:53], v[64:65] op_sel_hi:[1,0]
	v_pk_mul_f32 v[50:51], v[50:51], v[64:65] op_sel_hi:[1,0]
	v_pk_mul_f32 v[48:49], v[48:49], v[64:65] op_sel_hi:[1,0]
	v_pk_mul_f32 v[46:47], v[46:47], v[64:65] op_sel_hi:[1,0]
	v_pk_mul_f32 v[44:45], v[44:45], v[64:65] op_sel_hi:[1,0]
	v_pk_mul_f32 v[42:43], v[42:43], v[64:65] op_sel_hi:[1,0]
	v_pk_mul_f32 v[40:41], v[40:41], v[64:65] op_sel_hi:[1,0]
	v_pk_mul_f32 v[38:39], v[38:39], v[64:65] op_sel_hi:[1,0]
	v_pk_mul_f32 v[36:37], v[36:37], v[64:65] op_sel_hi:[1,0]
	v_pk_mul_f32 v[34:35], v[34:35], v[64:65] op_sel_hi:[1,0]
	v_pk_mul_f32 v[32:33], v[32:33], v[64:65] op_sel_hi:[1,0]
	v_pk_mul_f32 v[30:31], v[30:31], v[64:65] op_sel_hi:[1,0]
	v_pk_mul_f32 v[28:29], v[28:29], v[64:65] op_sel_hi:[1,0]
	v_pk_mul_f32 v[26:27], v[26:27], v[64:65] op_sel_hi:[1,0]
	v_pk_mul_f32 v[24:25], v[24:25], v[64:65] op_sel_hi:[1,0]
	v_pk_mul_f32 v[22:23], v[22:23], v[64:65] op_sel_hi:[1,0]
	v_pk_mul_f32 v[20:21], v[20:21], v[64:65] op_sel_hi:[1,0]
	v_pk_mul_f32 v[18:19], v[18:19], v[64:65] op_sel_hi:[1,0]
	v_pk_mul_f32 v[16:17], v[16:17], v[64:65] op_sel_hi:[1,0]
	v_pk_mul_f32 v[14:15], v[14:15], v[64:65] op_sel_hi:[1,0]
	v_pk_mul_f32 v[12:13], v[12:13], v[64:65] op_sel_hi:[1,0]
	v_pk_mul_f32 v[10:11], v[10:11], v[64:65] op_sel_hi:[1,0]
	v_pk_mul_f32 v[8:9], v[8:9], v[64:65] op_sel_hi:[1,0]
	v_pk_mul_f32 v[6:7], v[6:7], v[64:65] op_sel_hi:[1,0]
	v_pk_mul_f32 v[4:5], v[4:5], v[64:65] op_sel_hi:[1,0]
	v_pk_mul_f32 v[2:3], v[2:3], v[64:65] op_sel_hi:[1,0]
	v_pk_mul_f32 v[0:1], v[0:1], v[64:65] op_sel_hi:[1,0]
	v_mul_f32_e32 v176, v176, v64
	v_add_f32_e32 v64, v177, v66
	v_xor_b32_e32 v64, 0x80000000, v64
	v_pk_add_f32 v[82:83], v[82:83], v[66:67] op_sel_hi:[1,0] neg_lo:[0,1] neg_hi:[0,1]
	v_pk_add_f32 v[100:101], v[100:101], v[66:67] op_sel_hi:[1,0] neg_lo:[0,1] neg_hi:[0,1]
	v_pk_add_f32 v[84:85], v[84:85], v[66:67] op_sel_hi:[1,0] neg_lo:[0,1] neg_hi:[0,1]
	v_pk_add_f32 v[102:103], v[102:103], v[66:67] op_sel_hi:[1,0] neg_lo:[0,1] neg_hi:[0,1]
	v_pk_add_f32 v[86:87], v[86:87], v[66:67] op_sel_hi:[1,0] neg_lo:[0,1] neg_hi:[0,1]
	v_pk_add_f32 v[104:105], v[104:105], v[66:67] op_sel_hi:[1,0] neg_lo:[0,1] neg_hi:[0,1]
	v_pk_add_f32 v[88:89], v[88:89], v[66:67] op_sel_hi:[1,0] neg_lo:[0,1] neg_hi:[0,1]
	v_pk_add_f32 v[106:107], v[106:107], v[66:67] op_sel_hi:[1,0] neg_lo:[0,1] neg_hi:[0,1]
	v_pk_add_f32 v[90:91], v[90:91], v[66:67] op_sel_hi:[1,0] neg_lo:[0,1] neg_hi:[0,1]
	v_pk_add_f32 v[108:109], v[108:109], v[66:67] op_sel_hi:[1,0] neg_lo:[0,1] neg_hi:[0,1]
	v_pk_add_f32 v[92:93], v[92:93], v[66:67] op_sel_hi:[1,0] neg_lo:[0,1] neg_hi:[0,1]
	v_pk_add_f32 v[110:111], v[110:111], v[66:67] op_sel_hi:[1,0] neg_lo:[0,1] neg_hi:[0,1]
	v_pk_add_f32 v[94:95], v[94:95], v[66:67] op_sel_hi:[1,0] neg_lo:[0,1] neg_hi:[0,1]
	v_mov_b32_e32 v65, v64
	v_mov_b32_e32 v66, v64
	v_mov_b32_e32 v67, v64
	v_mov_b32_e32 v68, v64
	v_mov_b32_e32 v69, v64
	v_mov_b32_e32 v70, v64
	v_mov_b32_e32 v71, v64
	v_mov_b32_e32 v72, v64
	v_mov_b32_e32 v73, v64
	v_mov_b32_e32 v74, v64
	v_mov_b32_e32 v75, v64
	v_mov_b32_e32 v76, v64
	v_mov_b32_e32 v77, v64
	v_mov_b32_e32 v78, v64
	v_mov_b32_e32 v79, v64
.LBB0_907:
	v_exp_f32_e32 v96, v96
	v_exp_f32_e32 v97, v97
	v_exp_f32_e32 v98, v98
	v_exp_f32_e32 v99, v99
	v_exp_f32_e32 v100, v100
	v_exp_f32_e32 v101, v101
	v_exp_f32_e32 v102, v102
	v_exp_f32_e32 v103, v103
	v_cvt_pk_bf16_f32 v204, v96, v97
	v_cvt_pk_bf16_f32 v205, v98, v99
	v_cvt_pk_bf16_f32 v206, v100, v101
	v_cvt_pk_bf16_f32 v207, v102, v103
	s_waitcnt lgkmcnt(0)
	v_exp_f32_e32 v104, v104
	v_exp_f32_e32 v105, v105
	v_mfma_f32_32x32x16_bf16 v[48:63], v[172:175], v[204:207], v[48:63]
	v_exp_f32_e32 v106, v106
	v_exp_f32_e32 v107, v107
	v_exp_f32_e32 v108, v108
	v_exp_f32_e32 v109, v109
	v_exp_f32_e32 v110, v110
	v_exp_f32_e32 v111, v111
	v_cvt_pk_bf16_f32 v172, v104, v105
	v_mfma_f32_32x32x16_bf16 v[32:47], v[156:159], v[204:207], v[32:47]
	v_cvt_pk_bf16_f32 v173, v106, v107
	v_cvt_pk_bf16_f32 v174, v108, v109
	v_cvt_pk_bf16_f32 v175, v110, v111
	v_exp_f32_e32 v80, v80
	v_exp_f32_e32 v81, v81
	v_exp_f32_e32 v82, v82
	v_exp_f32_e32 v83, v83
	v_mfma_f32_32x32x16_bf16 v[48:63], v[168:171], v[172:175], v[48:63]
	v_exp_f32_e32 v84, v84
	v_exp_f32_e32 v85, v85
	v_exp_f32_e32 v86, v86
	v_exp_f32_e32 v87, v87
	v_cvt_pk_bf16_f32 v208, v80, v81
	v_cvt_pk_bf16_f32 v209, v82, v83
	v_cvt_pk_bf16_f32 v210, v84, v85
	v_mfma_f32_32x32x16_bf16 v[32:47], v[152:155], v[172:175], v[32:47]
	v_cvt_pk_bf16_f32 v211, v86, v87
	v_exp_f32_e32 v88, v88
	v_exp_f32_e32 v89, v89
	v_exp_f32_e32 v168, v90
	v_exp_f32_e32 v169, v91
	v_exp_f32_e32 v90, v92
	v_exp_f32_e32 v91, v93
	v_mfma_f32_32x32x16_bf16 v[48:63], v[164:167], v[208:211], v[48:63]
	v_exp_f32_e32 v92, v94
	v_exp_f32_e32 v93, v95
	v_cvt_pk_bf16_f32 v164, v88, v89
	v_cvt_pk_bf16_f32 v165, v168, v169
	v_cvt_pk_bf16_f32 v166, v90, v91
	v_cvt_pk_bf16_f32 v167, v92, v93
	v_mfma_f32_32x32x16_bf16 v[32:47], v[148:151], v[208:211], v[32:47]
	s_nop 0
	v_mfma_f32_32x32x16_bf16 v[48:63], v[160:163], v[164:167], v[48:63]
	v_mfma_f32_32x32x16_bf16 v[32:47], v[144:147], v[164:167], v[32:47]
	ds_read_b64 v[220:221], v191
	ds_read_b64 v[222:223], v191 offset:16
	ds_read_b64 v[216:217], v191 offset:32
	ds_read_b64 v[218:219], v191 offset:48
	ds_read_b64 v[212:213], v191 offset:64
	ds_read_b64 v[214:215], v191 offset:80
	ds_read_b64 v[160:161], v191 offset:96
	ds_read_b64 v[162:163], v191 offset:112
	ds_read_b64 v[156:157], v191 offset:0x1100
	ds_read_b64 v[158:159], v191 offset:0x1110
	ds_read_b64 v[152:153], v191 offset:0x1120
	ds_read_b64 v[154:155], v191 offset:0x1130
	ds_read_b64 v[148:149], v191 offset:0x1140
	ds_read_b64 v[150:151], v191 offset:0x1150
	ds_read_b64 v[144:145], v191 offset:0x1160
	ds_read_b64 v[146:147], v191 offset:0x1170
	s_nop 0
	s_waitcnt lgkmcnt(0)
	s_waitcnt vmcnt(2)
	ds_write_b128 v186, v[132:135] offset:32768
	v_mfma_f32_32x32x16_bf16 v[16:31], v[220:223], v[204:207], v[16:31]
	v_mfma_f32_32x32x16_bf16 v[0:15], v[156:159], v[204:207], v[0:15]
	v_mfma_f32_32x32x16_bf16 v[16:31], v[216:219], v[172:175], v[16:31]
	v_mfma_f32_32x32x16_bf16 v[0:15], v[152:155], v[172:175], v[0:15]
	v_mfma_f32_32x32x16_bf16 v[16:31], v[212:215], v[208:211], v[16:31]
	v_mfma_f32_32x32x16_bf16 v[0:15], v[148:151], v[208:211], v[0:15]
	v_mfma_f32_32x32x16_bf16 v[16:31], v[160:163], v[164:167], v[16:31]
	v_mfma_f32_32x32x16_bf16 v[0:15], v[144:147], v[164:167], v[0:15]
	s_and_saveexec_b64 s[0:1], s[2:3]
	ds_write_b128 v185, v[128:131] offset:32768
	s_or_b64 exec, exec, s[0:1]
	v_pk_add_f32 v[94:95], v[96:97], 0 op_sel_hi:[1,0]
	s_nop 0
	v_pk_add_f32 v[80:81], v[80:81], v[94:95]
	s_nop 0
	v_pk_add_f32 v[80:81], v[98:99], v[80:81]
	s_nop 0
	v_pk_add_f32 v[80:81], v[82:83], v[80:81]
	s_nop 0
	v_pk_add_f32 v[80:81], v[100:101], v[80:81]
	s_nop 0
	v_pk_add_f32 v[80:81], v[84:85], v[80:81]
	s_nop 0
	v_pk_add_f32 v[80:81], v[102:103], v[80:81]
	s_nop 0
	v_pk_add_f32 v[80:81], v[86:87], v[80:81]
	s_nop 0
	v_pk_add_f32 v[80:81], v[104:105], v[80:81]
	s_nop 0
	v_pk_add_f32 v[80:81], v[88:89], v[80:81]
	s_nop 0
	v_pk_add_f32 v[80:81], v[106:107], v[80:81]
	s_nop 0
	v_pk_add_f32 v[80:81], v[168:169], v[80:81]
	s_nop 0
	v_pk_add_f32 v[80:81], v[108:109], v[80:81]
	s_nop 0
	v_pk_add_f32 v[80:81], v[90:91], v[80:81]
	s_nop 0
	v_pk_add_f32 v[80:81], v[110:111], v[80:81]
	s_nop 0
	v_pk_add_f32 v[80:81], v[92:93], v[80:81]
	s_nop 0
	v_add_f32_e32 v80, v80, v81
	v_add_f32_e32 v128, v176, v80
	s_waitcnt vmcnt(0)
	v_perm_b32 v80, v140, v136, s85
	v_perm_b32 v81, v140, v136, s86
	ds_write2_b32 v188, v80, v81 offset1:34
	v_perm_b32 v80, v141, v137, s85
	v_perm_b32 v81, v141, v137, s86
	ds_write2_b32 v188, v80, v81 offset0:68 offset1:102
	v_perm_b32 v80, v142, v138, s85
	v_perm_b32 v81, v142, v138, s86
	ds_write2_b32 v188, v80, v81 offset0:136 offset1:170
	v_perm_b32 v80, v143, v139, s85
	v_perm_b32 v81, v143, v139, s86
	ds_write2_b32 v188, v80, v81 offset0:204 offset1:238
	s_waitcnt lgkmcnt(0)
	s_barrier
	ds_read_b128 v[96:99], v190
	ds_read_b128 v[100:103], v190 offset:0x1200
	ds_read_b128 v[104:107], v190 offset:32
	ds_read_b128 v[108:111], v190 offset:0x1220
	ds_read_b128 v[130:133], v190 offset:64
	ds_read_b128 v[134:137], v190 offset:0x1240
	ds_read_b128 v[138:141], v190 offset:96
	ds_read_b128 v[142:145], v190 offset:0x1260
	s_waitcnt lgkmcnt(0)
	s_nop 0
	v_mfma_f32_32x32x16_bf16 v[80:95], v[96:99], v[124:127], v[64:79]
	v_mfma_f32_32x32x16_bf16 v[64:79], v[100:103], v[124:127], v[64:79]
	v_mfma_f32_32x32x16_bf16 v[80:95], v[104:107], v[120:123], v[80:95]
	v_mfma_f32_32x32x16_bf16 v[64:79], v[108:111], v[120:123], v[64:79]
	v_mfma_f32_32x32x16_bf16 v[80:95], v[130:133], v[116:119], v[80:95]
	v_mfma_f32_32x32x16_bf16 v[64:79], v[134:137], v[116:119], v[64:79]
	v_mfma_f32_32x32x16_bf16 v[80:95], v[138:141], v[112:115], v[80:95]
	v_mfma_f32_32x32x16_bf16 v[64:79], v[142:145], v[112:115], v[64:79]
	s_nop 10
	ds_read_b64 v[124:125], v189
	ds_read_b64 v[126:127], v189 offset:16
	ds_read_b64 v[120:121], v189 offset:32
	ds_read_b64 v[122:123], v189 offset:48
	ds_read_b64 v[116:117], v189 offset:64
	ds_read_b64 v[118:119], v189 offset:80
	ds_read_b64 v[112:113], v189 offset:96
	ds_read_b64 v[114:115], v189 offset:112
	ds_read_b64 v[108:109], v189 offset:0x1100
	ds_read_b64 v[110:111], v189 offset:0x1110
	ds_read_b64 v[104:105], v189 offset:0x1120
	ds_read_b64 v[106:107], v189 offset:0x1130
	ds_read_b64 v[100:101], v189 offset:0x1140
	ds_read_b64 v[102:103], v189 offset:0x1150
	ds_read_b64 v[96:97], v189 offset:0x1160
	ds_read_b64 v[98:99], v189 offset:0x1170
	v_max_f32_e32 v129, v80, v64
	v_max_f32_e32 v130, v81, v65
	v_max_f32_e32 v131, v83, v67
	v_max3_f32 v131, v82, v66, v131
	v_max3_f32 v129, v129, v130, v131
	v_max_f32_e32 v130, v85, v69
	v_max_f32_e32 v131, v87, v71
	v_max3_f32 v130, v84, v68, v130
	v_max3_f32 v131, v86, v70, v131
	v_max3_f32 v129, v129, v130, v131
	v_max_f32_e32 v130, v89, v73
	v_max_f32_e32 v131, v91, v75
	v_max3_f32 v130, v88, v72, v130
	v_max3_f32 v131, v90, v74, v131
	v_max3_f32 v129, v129, v130, v131
	v_max_f32_e32 v130, v93, v77
	v_max_f32_e32 v132, v95, v95
	v_max_f32_e32 v131, v132, v79
	v_max3_f32 v130, v92, v76, v130
	v_max3_f32 v131, v94, v78, v131
	v_max3_f32 v129, v129, v130, v131
	v_mov_b32_e32 v130, v129
	s_nop 1
	v_permlane32_swap_b32_e32 v129, v130
	v_max_f32_e32 v129, v129, v130
	v_cmp_lt_f32_e32 vcc, s80, v129
	s_cbranch_vccz .LBB0_911
	v_max_f32_e32 v130, 0, v129
	v_exp_f32_e64 v132, -v130
	v_pk_add_f32 v[80:81], v[80:81], v[130:131] op_sel_hi:[1,0] neg_lo:[0,1] neg_hi:[0,1]
	v_pk_add_f32 v[64:65], v[64:65], v[130:131] op_sel_hi:[1,0] neg_lo:[0,1] neg_hi:[0,1]
	v_pk_add_f32 v[82:83], v[82:83], v[130:131] op_sel_hi:[1,0] neg_lo:[0,1] neg_hi:[0,1]
	v_pk_mul_f32 v[62:63], v[62:63], v[132:133] op_sel_hi:[1,0]
	v_pk_mul_f32 v[60:61], v[60:61], v[132:133] op_sel_hi:[1,0]
	v_pk_mul_f32 v[58:59], v[58:59], v[132:133] op_sel_hi:[1,0]
	v_pk_mul_f32 v[56:57], v[56:57], v[132:133] op_sel_hi:[1,0]
	v_pk_mul_f32 v[54:55], v[54:55], v[132:133] op_sel_hi:[1,0]
	v_pk_mul_f32 v[52:53], v[52:53], v[132:133] op_sel_hi:[1,0]
	v_pk_mul_f32 v[50:51], v[50:51], v[132:133] op_sel_hi:[1,0]
	v_pk_mul_f32 v[48:49], v[48:49], v[132:133] op_sel_hi:[1,0]
	v_pk_mul_f32 v[46:47], v[46:47], v[132:133] op_sel_hi:[1,0]
	v_pk_mul_f32 v[44:45], v[44:45], v[132:133] op_sel_hi:[1,0]
	v_pk_mul_f32 v[42:43], v[42:43], v[132:133] op_sel_hi:[1,0]
	v_pk_mul_f32 v[40:41], v[40:41], v[132:133] op_sel_hi:[1,0]
	v_pk_mul_f32 v[38:39], v[38:39], v[132:133] op_sel_hi:[1,0]
	v_pk_mul_f32 v[36:37], v[36:37], v[132:133] op_sel_hi:[1,0]
	v_pk_mul_f32 v[34:35], v[34:35], v[132:133] op_sel_hi:[1,0]
	v_pk_mul_f32 v[32:33], v[32:33], v[132:133] op_sel_hi:[1,0]
	v_pk_mul_f32 v[30:31], v[30:31], v[132:133] op_sel_hi:[1,0]
	v_pk_mul_f32 v[28:29], v[28:29], v[132:133] op_sel_hi:[1,0]
	v_pk_mul_f32 v[26:27], v[26:27], v[132:133] op_sel_hi:[1,0]
	v_pk_mul_f32 v[24:25], v[24:25], v[132:133] op_sel_hi:[1,0]
	v_pk_mul_f32 v[22:23], v[22:23], v[132:133] op_sel_hi:[1,0]
	v_pk_mul_f32 v[20:21], v[20:21], v[132:133] op_sel_hi:[1,0]
	v_pk_mul_f32 v[18:19], v[18:19], v[132:133] op_sel_hi:[1,0]
	v_pk_mul_f32 v[16:17], v[16:17], v[132:133] op_sel_hi:[1,0]
	v_pk_mul_f32 v[14:15], v[14:15], v[132:133] op_sel_hi:[1,0]
	v_pk_mul_f32 v[12:13], v[12:13], v[132:133] op_sel_hi:[1,0]
	v_pk_mul_f32 v[10:11], v[10:11], v[132:133] op_sel_hi:[1,0]
	v_pk_mul_f32 v[8:9], v[8:9], v[132:133] op_sel_hi:[1,0]
	v_pk_mul_f32 v[6:7], v[6:7], v[132:133] op_sel_hi:[1,0]
	v_pk_mul_f32 v[4:5], v[4:5], v[132:133] op_sel_hi:[1,0]
	v_pk_mul_f32 v[2:3], v[2:3], v[132:133] op_sel_hi:[1,0]
	v_pk_mul_f32 v[0:1], v[0:1], v[132:133] op_sel_hi:[1,0]
	v_mul_f32_e32 v128, v128, v132
	v_pk_add_f32 v[66:67], v[66:67], v[130:131] op_sel_hi:[1,0] neg_lo:[0,1] neg_hi:[0,1]
	v_pk_add_f32 v[84:85], v[84:85], v[130:131] op_sel_hi:[1,0] neg_lo:[0,1] neg_hi:[0,1]
	v_pk_add_f32 v[68:69], v[68:69], v[130:131] op_sel_hi:[1,0] neg_lo:[0,1] neg_hi:[0,1]
	v_pk_add_f32 v[86:87], v[86:87], v[130:131] op_sel_hi:[1,0] neg_lo:[0,1] neg_hi:[0,1]
	v_pk_add_f32 v[70:71], v[70:71], v[130:131] op_sel_hi:[1,0] neg_lo:[0,1] neg_hi:[0,1]
	v_pk_add_f32 v[88:89], v[88:89], v[130:131] op_sel_hi:[1,0] neg_lo:[0,1] neg_hi:[0,1]
	v_pk_add_f32 v[72:73], v[72:73], v[130:131] op_sel_hi:[1,0] neg_lo:[0,1] neg_hi:[0,1]
	v_pk_add_f32 v[90:91], v[90:91], v[130:131] op_sel_hi:[1,0] neg_lo:[0,1] neg_hi:[0,1]
	v_pk_add_f32 v[74:75], v[74:75], v[130:131] op_sel_hi:[1,0] neg_lo:[0,1] neg_hi:[0,1]
	v_pk_add_f32 v[92:93], v[92:93], v[130:131] op_sel_hi:[1,0] neg_lo:[0,1] neg_hi:[0,1]
	v_pk_add_f32 v[76:77], v[76:77], v[130:131] op_sel_hi:[1,0] neg_lo:[0,1] neg_hi:[0,1]
	v_pk_add_f32 v[94:95], v[94:95], v[130:131] op_sel_hi:[1,0] neg_lo:[0,1] neg_hi:[0,1]
	v_pk_add_f32 v[78:79], v[78:79], v[130:131] op_sel_hi:[1,0] neg_lo:[0,1] neg_hi:[0,1]

.LBB0_925:
	s_or_b64 exec, exec, s[8:9]
	v_mad_u32_u24 v33, v32, s20, 0
	v_add_u32_e32 v192, v33, v168
	ds_read_b128 v[0:3], v192
	ds_read_b128 v[16:19], v192 offset:0x1a00
	ds_read_b128 v[34:37], v192 offset:32
	ds_read_b128 v[38:41], v192 offset:0x1a20
	ds_read_b128 v[42:45], v192 offset:64
	ds_read_b128 v[46:49], v192 offset:0x1a40
	ds_read_b128 v[50:53], v192 offset:96
	ds_read_b128 v[54:57], v192 offset:0x1a60
	ds_read_b128 v[58:61], v192 offset:128
	ds_read_b128 v[62:65], v192 offset:0x1a80
	ds_read_b128 v[66:69], v192 offset:160
	ds_read_b128 v[70:73], v192 offset:0x1aa0
	s_waitcnt lgkmcnt(0)
	v_lshlrev_b32_e32 v189, 3, v10
	v_mfma_f32_32x32x16_bf16 v[0:15], v[0:3], v[116:119], 0
	v_mul_u32_u24_e32 v190, 0xd0, v32
	v_mul_u32_u24_e32 v191, 0x88, v32
	v_mul_i32_i24_e32 v32, 0xffffffb8, v32
	v_add3_u32 v204, v33, v32, v189
	s_lshr_b32 s8, s15, 8
	s_and_b32 s9, s14, 56
	s_add_i32 s8, s8, s9
	v_mfma_f32_32x32x16_bf16 v[16:31], v[16:19], v[116:119], 0
	s_add_i32 s17, s8, s17
	s_movk_i32 s19, 0x1000
	s_mul_i32 s76, s17, 0x900
	s_lshl_b64 s[8:9], s[76:77], 7
	s_mul_i32 s17, s17, 0x6c000
	s_mul_hi_u32 s18, s76, 0xc0
	v_mov_b32_e32 v171, s9
	v_mfma_f32_32x32x16_bf16 v[0:15], v[34:37], v[112:115], v[0:15]
	v_mfma_f32_32x32x16_bf16 v[16:31], v[38:41], v[112:115], v[16:31]
	v_mfma_f32_32x32x16_bf16 v[0:15], v[42:45], v[108:111], v[0:15]
	v_mfma_f32_32x32x16_bf16 v[16:31], v[46:49], v[108:111], v[16:31]
	v_mfma_f32_32x32x16_bf16 v[0:15], v[50:53], v[104:107], v[0:15]
	v_mfma_f32_32x32x16_bf16 v[16:31], v[54:57], v[104:107], v[16:31]
	v_mfma_f32_32x32x16_bf16 v[0:15], v[58:61], v[100:103], v[0:15]
	v_mfma_f32_32x32x16_bf16 v[16:31], v[62:65], v[100:103], v[16:31]
	v_add_u32_e32 v64, 0x3400, v204
	ds_read_b64 v[60:61], v64
	ds_read_b64 v[62:63], v64 offset:16
	ds_read_b64 v[56:57], v64 offset:32
	ds_read_b64 v[58:59], v64 offset:48
	ds_read_b64 v[52:53], v64 offset:64
	ds_read_b64 v[54:55], v64 offset:80
	ds_read_b64 v[48:49], v64 offset:96
	ds_read_b64 v[50:51], v64 offset:112
	ds_read_b64 v[44:45], v64 offset:0x1100
	ds_read_b64 v[46:47], v64 offset:0x1110
	ds_read_b64 v[40:41], v64 offset:0x1120
	ds_read_b64 v[42:43], v64 offset:0x1130
	ds_read_b64 v[36:37], v64 offset:0x1140
	ds_read_b64 v[38:39], v64 offset:0x1150
	ds_read_b64 v[32:33], v64 offset:0x1160
	ds_read_b64 v[34:35], v64 offset:0x1170
	s_nop 0
	s_waitcnt lgkmcnt(0)
	v_mfma_f32_32x32x16_bf16 v[0:15], v[66:69], v[96:99], v[0:15]
	v_mfma_f32_32x32x16_bf16 v[16:31], v[70:73], v[96:99], v[16:31]
	s_nop 11
	v_max_f32_e32 v64, v0, v16
	v_max_f32_e32 v65, v1, v17
	v_max_f32_e32 v66, v3, v19
	v_max3_f32 v66, v2, v18, v66
	v_max3_f32 v64, v64, v65, v66
	v_max_f32_e32 v65, v5, v21
	v_max_f32_e32 v66, v7, v23
	v_max3_f32 v65, v4, v20, v65
	v_max3_f32 v66, v6, v22, v66
	v_max3_f32 v64, v64, v65, v66
	v_max_f32_e32 v65, v9, v25
	v_max_f32_e32 v66, v11, v27
	v_max3_f32 v65, v8, v24, v65
	v_max3_f32 v66, v10, v26, v66
	v_max3_f32 v64, v64, v65, v66
	v_max_f32_e32 v65, v13, v29
	v_max_f32_e32 v66, v15, v31
	v_max3_f32 v65, v12, v28, v65
	v_max3_f32 v66, v14, v30, v66
	v_max3_f32 v64, v64, v65, v66
	v_mov_b32_e32 v65, v64
	s_nop 1
	v_permlane32_swap_b32_e32 v64, v65
	v_max_f32_e32 v84, v64, v65
	v_sub_f32_e32 v0, v0, v84
	v_sub_f32_e32 v1, v1, v84
	v_sub_f32_e32 v16, v16, v84
	v_sub_f32_e32 v17, v17, v84
	v_exp_f32_e32 v0, v0
	v_exp_f32_e32 v1, v1
	v_sub_f32_e32 v64, v26, v84
	v_sub_f32_e32 v65, v27, v84
	v_sub_f32_e32 v26, v2, v84
	v_sub_f32_e32 v27, v3, v84
	v_exp_f32_e32 v2, v16
	v_exp_f32_e32 v3, v17
	v_sub_f32_e32 v18, v18, v84
	v_sub_f32_e32 v19, v19, v84
	v_sub_f32_e32 v68, v30, v84
	v_sub_f32_e32 v69, v31, v84
	v_sub_f32_e32 v30, v6, v84
	v_sub_f32_e32 v31, v7, v84
	v_exp_f32_e32 v6, v26
	v_exp_f32_e32 v7, v27
	v_sub_f32_e32 v66, v28, v84
	v_sub_f32_e32 v67, v29, v84
	v_sub_f32_e32 v28, v4, v84
	v_sub_f32_e32 v29, v5, v84
	v_sub_f32_e32 v70, v8, v84
	v_sub_f32_e32 v71, v9, v84
	v_exp_f32_e32 v8, v18
	v_exp_f32_e32 v9, v19
	v_sub_f32_e32 v20, v20, v84
	v_sub_f32_e32 v21, v21, v84
	v_sub_f32_e32 v72, v10, v84
	v_sub_f32_e32 v73, v11, v84
	v_pk_add_f32 v[4:5], v[0:1], 0 op_sel_hi:[1,0]
	v_exp_f32_e32 v10, v28
	v_exp_f32_e32 v11, v29
	v_sub_f32_e32 v74, v12, v84
	v_sub_f32_e32 v75, v13, v84
	v_pk_add_f32 v[4:5], v[2:3], v[4:5]
	v_exp_f32_e32 v12, v20
	v_exp_f32_e32 v13, v21
	v_sub_f32_e32 v22, v22, v84
	v_sub_f32_e32 v23, v23, v84
	v_sub_f32_e32 v85, v14, v84
	v_sub_f32_e32 v86, v15, v84
	v_pk_add_f32 v[4:5], v[6:7], v[4:5]
	v_exp_f32_e32 v14, v30
	v_exp_f32_e32 v15, v31
	v_pk_add_f32 v[4:5], v[8:9], v[4:5]
	v_exp_f32_e32 v20, v22
	v_exp_f32_e32 v21, v23
	v_sub_f32_e32 v24, v24, v84
	v_sub_f32_e32 v25, v25, v84
	v_pk_add_f32 v[4:5], v[10:11], v[4:5]
	v_exp_f32_e32 v22, v70
	v_exp_f32_e32 v23, v71
	v_pk_add_f32 v[4:5], v[12:13], v[4:5]
	v_exp_f32_e32 v24, v24
	v_exp_f32_e32 v25, v25
	v_pk_add_f32 v[4:5], v[14:15], v[4:5]
	v_exp_f32_e32 v26, v72
	v_exp_f32_e32 v27, v73
	v_pk_add_f32 v[4:5], v[20:21], v[4:5]
	v_exp_f32_e32 v28, v64
	v_exp_f32_e32 v29, v65
	v_pk_add_f32 v[4:5], v[22:23], v[4:5]
	v_exp_f32_e32 v30, v74
	v_exp_f32_e32 v31, v75
	v_pk_add_f32 v[4:5], v[24:25], v[4:5]
	v_exp_f32_e32 v66, v66
	v_exp_f32_e32 v67, v67
	v_pk_add_f32 v[4:5], v[26:27], v[4:5]
	v_exp_f32_e32 v64, v85
	v_exp_f32_e32 v65, v86
	v_pk_add_f32 v[4:5], v[28:29], v[4:5]
	v_exp_f32_e32 v92, v68
	v_exp_f32_e32 v93, v69
	v_pk_add_f32 v[4:5], v[30:31], v[4:5]
	v_cvt_pk_bf16_f32 v16, v0, v1
	v_pk_add_f32 v[4:5], v[66:67], v[4:5]
	v_cvt_pk_bf16_f32 v17, v6, v7
	v_pk_add_f32 v[4:5], v[64:65], v[4:5]
	v_cvt_pk_bf16_f32 v18, v10, v11
	v_pk_add_f32 v[4:5], v[92:93], v[4:5]
	v_cvt_pk_bf16_f32 v19, v14, v15
	v_pk_add_f32 v[86:87], v[4:5], v[4:5] op_sel_hi:[0,1]
	v_cvt_pk_bf16_f32 v72, v22, v23
	v_cvt_pk_bf16_f32 v73, v26, v27
	v_cvt_pk_bf16_f32 v74, v30, v31
	v_cvt_pk_bf16_f32 v75, v64, v65
	v_cvt_pk_bf16_f32 v68, v2, v3
	v_cvt_pk_bf16_f32 v69, v8, v9
	v_cvt_pk_bf16_f32 v70, v12, v13
	v_cvt_pk_bf16_f32 v71, v20, v21
	v_cvt_pk_bf16_f32 v64, v24, v25
	v_cvt_pk_bf16_f32 v65, v28, v29
	v_mfma_f32_32x32x16_bf16 v[0:15], v[60:63], v[16:19], 0
	v_cvt_pk_bf16_f32 v66, v66, v67
	v_cvt_pk_bf16_f32 v67, v92, v93
	v_mov_b32_e32 v85, v87
	v_add_f32_e64 v176, v84, 0
	v_add_f32_e64 v177, v85, 0
	v_mfma_f32_32x32x16_bf16 v[16:31], v[44:47], v[16:19], 0
	v_mfma_f32_32x32x16_bf16 v[0:15], v[56:59], v[72:75], v[0:15]
	v_mfma_f32_32x32x16_bf16 v[16:31], v[40:43], v[72:75], v[16:31]
	v_mfma_f32_32x32x16_bf16 v[0:15], v[52:55], v[68:71], v[0:15]
	v_mfma_f32_32x32x16_bf16 v[16:31], v[36:39], v[68:71], v[16:31]
	v_mfma_f32_32x32x16_bf16 v[0:15], v[48:51], v[64:67], v[0:15]
	v_add_f32_e64 v48, -v176, neg(0)
	v_add_f32_e64 v49, -v177, neg(0)
	v_mov_b32_e32 v49, v48
	v_mov_b32_e32 v50, v48
	v_mov_b32_e32 v51, v48
	v_mov_b32_e32 v52, v48
	v_mov_b32_e32 v53, v48
	v_mfma_f32_32x32x16_bf16 v[16:31], v[32:35], v[64:67], v[16:31]
	v_lshlrev_b32_e32 v32, 8, v90
	v_lshlrev_b32_e32 v33, 5, v88
	v_and_or_b32 v32, v33, s19, v32
	v_lshlrev_b32_e32 v33, 4, v89
	v_and_or_b32 v33, v88, 64, v33
	v_or3_b32 v170, s8, v32, v33
	s_add_u32 s8, s17, 0x12b06000
	s_addc_u32 s9, s18, 0
	v_lshl_add_u64 v[32:33], v[80:81], 1, s[8:9]
	v_lshl_add_u64 v[172:173], v[82:83], 1, v[32:33]
	v_lshl_add_u64 v[32:33], v[76:77], 1, s[8:9]
	v_lshl_add_u64 v[174:175], v[78:79], 1, v[32:33]
	s_mov_b32 s17, 0x8000
	v_mov_b32_e32 v54, v48
	v_mov_b32_e32 v55, v48
	v_mov_b32_e32 v56, v48
	v_mov_b32_e32 v57, v48
	v_mov_b32_e32 v58, v48
	v_mov_b32_e32 v59, v48
	v_mov_b32_e32 v60, v48
	v_mov_b32_e32 v61, v48
	v_mov_b32_e32 v62, v48
	v_mov_b32_e32 v63, v48

.LBB0_934:
	s_or_b64 exec, exec, s[8:9]
	v_add3_u32 v64, s18, v190, v168
	ds_read_b128 v[32:35], v64
	ds_read_b128 v[36:39], v64 offset:0x1a00
	ds_read_b128 v[40:43], v64 offset:32
	ds_read_b128 v[44:47], v64 offset:0x1a20
	ds_read_b128 v[136:139], v64 offset:64
	ds_read_b128 v[140:143], v64 offset:0x1a40
	ds_read_b128 v[144:147], v64 offset:96
	ds_read_b128 v[148:151], v64 offset:0x1a60
	ds_read_b128 v[152:155], v64 offset:128
	ds_read_b128 v[156:159], v64 offset:0x1a80
	ds_read_b128 v[206:209], v64 offset:160
	ds_read_b128 v[160:163], v64 offset:0x1aa0
	s_waitcnt lgkmcnt(0)
	s_nop 0
	v_mfma_f32_32x32x16_bf16 v[80:95], v[32:35], v[116:119], v[48:63]
	v_add_u32_e32 v32, s18, v191
	v_add3_u32 v32, v32, v189, s87
	v_mfma_f32_32x32x16_bf16 v[64:79], v[36:39], v[116:119], v[48:63]
	v_mfma_f32_32x32x16_bf16 v[80:95], v[40:43], v[112:115], v[80:95]
	v_mfma_f32_32x32x16_bf16 v[64:79], v[44:47], v[112:115], v[64:79]
	v_mfma_f32_32x32x16_bf16 v[80:95], v[136:139], v[108:111], v[80:95]
	v_mfma_f32_32x32x16_bf16 v[64:79], v[140:143], v[108:111], v[64:79]
	v_mfma_f32_32x32x16_bf16 v[80:95], v[144:147], v[104:107], v[80:95]
	v_mfma_f32_32x32x16_bf16 v[64:79], v[148:151], v[104:107], v[64:79]
	v_mfma_f32_32x32x16_bf16 v[80:95], v[152:155], v[100:103], v[80:95]
	v_mfma_f32_32x32x16_bf16 v[64:79], v[156:159], v[100:103], v[64:79]
	v_mfma_f32_32x32x16_bf16 v[64:79], v[160:163], v[96:99], v[64:79]
	ds_read_b64 v[164:165], v32
	ds_read_b64 v[166:167], v32 offset:16
	ds_read_b64 v[160:161], v32 offset:32
	ds_read_b64 v[162:163], v32 offset:48
	ds_read_b64 v[156:157], v32 offset:64
	ds_read_b64 v[158:159], v32 offset:80
	ds_read_b64 v[152:153], v32 offset:96
	ds_read_b64 v[154:155], v32 offset:112
	ds_read_b64 v[148:149], v32 offset:0x1100
	ds_read_b64 v[150:151], v32 offset:0x1110
	ds_read_b64 v[144:145], v32 offset:0x1120
	ds_read_b64 v[146:147], v32 offset:0x1130
	ds_read_b64 v[140:141], v32 offset:0x1140
	ds_read_b64 v[142:143], v32 offset:0x1150
	ds_read_b64 v[136:137], v32 offset:0x1160
	ds_read_b64 v[138:139], v32 offset:0x1170
	v_mfma_f32_32x32x16_bf16 v[80:95], v[206:209], v[96:99], v[80:95]
	s_nop 11
	v_max_f32_e32 v32, v80, v64
	v_max_f32_e32 v33, v81, v65
	v_max_f32_e32 v34, v83, v67
	v_max3_f32 v34, v82, v66, v34
	v_max3_f32 v32, v32, v33, v34
	v_max_f32_e32 v33, v85, v69
	v_max_f32_e32 v34, v87, v71
	v_max3_f32 v33, v84, v68, v33
	v_max3_f32 v34, v86, v70, v34
	v_max3_f32 v32, v32, v33, v34
	v_max_f32_e32 v33, v89, v73
	v_max_f32_e32 v34, v91, v75
	v_max3_f32 v33, v88, v72, v33
	v_max3_f32 v34, v90, v74, v34
	v_max3_f32 v32, v32, v33, v34
	v_max_f32_e32 v33, v93, v77
	v_max_f32_e32 v35, v95, v95
	v_max_f32_e32 v34, v35, v79
	v_max3_f32 v33, v92, v76, v33
	v_max3_f32 v34, v94, v78, v34
	v_max3_f32 v32, v32, v33, v34
	v_mov_b32_e32 v33, v32
	s_nop 1
	v_permlane32_swap_b32_e32 v32, v33
	v_max_f32_e32 v32, v32, v33
	v_cmp_lt_f32_e32 vcc, s80, v32
	s_cbranch_vccz .LBB0_936
	v_max_f32_e32 v48, 0, v32
	v_exp_f32_e64 v32, -v48
	s_nop 0
	v_mov_b32_e32 v49, v32
	v_pk_mul_f32 v[30:31], v[30:31], v[32:33] op_sel_hi:[1,0]
	v_pk_mul_f32 v[28:29], v[28:29], v[32:33] op_sel_hi:[1,0]
	v_pk_mul_f32 v[26:27], v[26:27], v[32:33] op_sel_hi:[1,0]
	v_pk_mul_f32 v[24:25], v[24:25], v[32:33] op_sel_hi:[1,0]
	v_pk_mul_f32 v[22:23], v[22:23], v[32:33] op_sel_hi:[1,0]
	v_pk_mul_f32 v[20:21], v[20:21], v[32:33] op_sel_hi:[1,0]
	v_pk_mul_f32 v[18:19], v[18:19], v[32:33] op_sel_hi:[1,0]
	v_pk_mul_f32 v[14:15], v[14:15], v[32:33] op_sel_hi:[1,0]
	v_pk_mul_f32 v[12:13], v[12:13], v[32:33] op_sel_hi:[1,0]
	v_pk_mul_f32 v[10:11], v[10:11], v[32:33] op_sel_hi:[1,0]
	v_pk_mul_f32 v[8:9], v[8:9], v[32:33] op_sel_hi:[1,0]
	v_pk_mul_f32 v[6:7], v[6:7], v[32:33] op_sel_hi:[1,0]
	v_pk_mul_f32 v[4:5], v[4:5], v[32:33] op_sel_hi:[1,0]
	v_pk_mul_f32 v[2:3], v[2:3], v[32:33] op_sel_hi:[1,0]
	v_pk_mul_f32 v[16:17], v[16:17], v[32:33] op_sel_hi:[1,0]
	v_pk_mul_f32 v[0:1], v[0:1], v[32:33] op_sel_hi:[1,0]
	v_pk_add_f32 v[178:179], v[176:177], v[48:49]
	v_pk_mul_f32 v[32:33], v[176:177], v[48:49]
	v_pk_add_f32 v[80:81], v[80:81], v[48:49] op_sel_hi:[1,0] neg_lo:[0,1] neg_hi:[0,1]
	v_mov_b32_e32 v179, v33
	v_pk_add_f32 v[32:33], v[178:179], 0 neg_lo:[1,1] neg_hi:[1,1]
	v_pk_add_f32 v[64:65], v[64:65], v[48:49] op_sel_hi:[1,0] neg_lo:[0,1] neg_hi:[0,1]
	v_pk_add_f32 v[82:83], v[82:83], v[48:49] op_sel_hi:[1,0] neg_lo:[0,1] neg_hi:[0,1]
	v_pk_add_f32 v[66:67], v[66:67], v[48:49] op_sel_hi:[1,0] neg_lo:[0,1] neg_hi:[0,1]
	v_pk_add_f32 v[84:85], v[84:85], v[48:49] op_sel_hi:[1,0] neg_lo:[0,1] neg_hi:[0,1]
	v_pk_add_f32 v[68:69], v[68:69], v[48:49] op_sel_hi:[1,0] neg_lo:[0,1] neg_hi:[0,1]
	v_pk_add_f32 v[86:87], v[86:87], v[48:49] op_sel_hi:[1,0] neg_lo:[0,1] neg_hi:[0,1]
	v_pk_add_f32 v[70:71], v[70:71], v[48:49] op_sel_hi:[1,0] neg_lo:[0,1] neg_hi:[0,1]
	v_pk_add_f32 v[88:89], v[88:89], v[48:49] op_sel_hi:[1,0] neg_lo:[0,1] neg_hi:[0,1]
	v_pk_add_f32 v[72:73], v[72:73], v[48:49] op_sel_hi:[1,0] neg_lo:[0,1] neg_hi:[0,1]
	v_pk_add_f32 v[90:91], v[90:91], v[48:49] op_sel_hi:[1,0] neg_lo:[0,1] neg_hi:[0,1]
	v_pk_add_f32 v[74:75], v[74:75], v[48:49] op_sel_hi:[1,0] neg_lo:[0,1] neg_hi:[0,1]
	v_pk_add_f32 v[92:93], v[92:93], v[48:49] op_sel_hi:[1,0] neg_lo:[0,1] neg_hi:[0,1]
	v_pk_add_f32 v[76:77], v[76:77], v[48:49] op_sel_hi:[1,0] neg_lo:[0,1] neg_hi:[0,1]
	v_mov_b32_e32 v33, v32
	v_mov_b32_e32 v34, v32
	v_mov_b32_e32 v35, v32
	v_mov_b32_e32 v36, v32
	v_mov_b32_e32 v37, v32
	v_mov_b32_e32 v38, v32
	v_mov_b32_e32 v39, v32
	v_mov_b32_e32 v40, v32
	v_mov_b32_e32 v41, v32
	v_mov_b32_e32 v42, v32
	v_mov_b32_e32 v43, v32
	v_mov_b32_e32 v44, v32
	v_mov_b32_e32 v45, v32
	v_mov_b32_e32 v46, v32
	v_mov_b32_e32 v47, v32
	v_pk_add_f32 v[94:95], v[94:95], v[48:49] op_sel_hi:[1,0] neg_lo:[0,1] neg_hi:[0,1]
	v_pk_add_f32 v[78:79], v[78:79], v[48:49] op_sel_hi:[1,0] neg_lo:[0,1] neg_hi:[0,1]
	v_mov_b32_e32 v48, v32
	v_mov_b32_e32 v49, v32
	v_mov_b32_e32 v50, v32
	v_mov_b32_e32 v51, v32
	v_mov_b32_e32 v52, v32
	v_mov_b32_e32 v53, v32
	v_mov_b32_e32 v54, v32
	v_mov_b32_e32 v55, v32
	v_mov_b32_e32 v56, v32
	v_mov_b32_e32 v57, v32
	v_mov_b32_e32 v58, v32
	v_mov_b32_e32 v59, v32
	v_mov_b32_e32 v60, v32
	v_mov_b32_e32 v61, v32
	v_mov_b32_e32 v62, v32
	v_mov_b32_e32 v63, v32
	v_mov_b32_e32 v176, v178
	s_branch .LBB0_937

.LBB0_943:
	s_or_b64 exec, exec, s[2:3]
	v_add_u32_e32 v48, 0x8000, v192
	s_waitcnt lgkmcnt(0)
	s_barrier
	ds_read_b128 v[64:67], v48
	ds_read_b128 v[68:71], v48 offset:0x1a00
	ds_read_b128 v[72:75], v48 offset:32
	ds_read_b128 v[76:79], v48 offset:0x1a20
	ds_read_b128 v[80:83], v48 offset:64
	ds_read_b128 v[84:87], v48 offset:0x1a40
	ds_read_b128 v[88:91], v48 offset:96
	ds_read_b128 v[92:95], v48 offset:0x1a60
	ds_read_b128 v[120:123], v48 offset:128
	ds_read_b128 v[124:127], v48 offset:0x1a80
	ds_read_b128 v[128:131], v48 offset:160
	ds_read_b128 v[132:135], v48 offset:0x1aa0
	s_waitcnt lgkmcnt(0)
	s_nop 0
	v_mfma_f32_32x32x16_bf16 v[48:63], v[64:67], v[116:119], v[32:47]
	v_mfma_f32_32x32x16_bf16 v[32:47], v[68:71], v[116:119], v[32:47]
	v_mfma_f32_32x32x16_bf16 v[48:63], v[72:75], v[112:115], v[48:63]
	v_mfma_f32_32x32x16_bf16 v[32:47], v[76:79], v[112:115], v[32:47]
	v_mfma_f32_32x32x16_bf16 v[48:63], v[80:83], v[108:111], v[48:63]
	v_mfma_f32_32x32x16_bf16 v[32:47], v[84:87], v[108:111], v[32:47]
	v_mfma_f32_32x32x16_bf16 v[48:63], v[88:91], v[104:107], v[48:63]
	v_mfma_f32_32x32x16_bf16 v[32:47], v[92:95], v[104:107], v[32:47]
	v_mfma_f32_32x32x16_bf16 v[48:63], v[120:123], v[100:103], v[48:63]
	v_mfma_f32_32x32x16_bf16 v[32:47], v[124:127], v[100:103], v[32:47]
	v_add_u32_e32 v100, 0xb400, v204
	ds_read_b64 v[92:93], v100
	ds_read_b64 v[94:95], v100 offset:16
	ds_read_b64 v[88:89], v100 offset:32
	ds_read_b64 v[90:91], v100 offset:48
	ds_read_b64 v[84:85], v100 offset:64
	ds_read_b64 v[86:87], v100 offset:80
	ds_read_b64 v[80:81], v100 offset:96
	ds_read_b64 v[82:83], v100 offset:112
	ds_read_b64 v[76:77], v100 offset:0x1100
	ds_read_b64 v[78:79], v100 offset:0x1110
	ds_read_b64 v[72:73], v100 offset:0x1120
	ds_read_b64 v[74:75], v100 offset:0x1130
	ds_read_b64 v[68:69], v100 offset:0x1140
	ds_read_b64 v[70:71], v100 offset:0x1150
	ds_read_b64 v[64:65], v100 offset:0x1160
	ds_read_b64 v[66:67], v100 offset:0x1170
	v_mfma_f32_32x32x16_bf16 v[32:47], v[132:135], v[96:99], v[32:47]
	v_mfma_f32_32x32x16_bf16 v[48:63], v[128:131], v[96:99], v[48:63]
	s_nop 10
	v_max_f32_e32 v100, v32, v32
	v_max_f32_e32 v97, v49, v33
	v_max_f32_e32 v98, v51, v35
	v_max_f32_e32 v96, v48, v100
	v_max3_f32 v98, v50, v34, v98
	v_max3_f32 v96, v96, v97, v98
	v_max_f32_e32 v97, v53, v37
	v_max_f32_e32 v98, v55, v39
	v_max3_f32 v97, v52, v36, v97
	v_max3_f32 v98, v54, v38, v98
	v_max3_f32 v96, v96, v97, v98
	v_max_f32_e32 v97, v57, v41
	v_max_f32_e32 v98, v59, v43
	v_max3_f32 v97, v56, v40, v97
	v_max3_f32 v98, v58, v42, v98
	v_max3_f32 v96, v96, v97, v98
	v_max_f32_e32 v97, v61, v45
	v_max_f32_e32 v99, v63, v63
	v_max_f32_e32 v98, v99, v47
	v_max3_f32 v97, v60, v44, v97
	v_max3_f32 v98, v62, v46, v98
	v_max3_f32 v96, v96, v97, v98
	v_mov_b32_e32 v97, v96
	s_nop 1
	v_permlane32_swap_b32_e32 v96, v97
	v_max_f32_e32 v96, v96, v97
	v_cmp_lt_f32_e32 vcc, s80, v96
	s_cbranch_vccz .LBB0_945
	v_max_f32_e32 v96, 0, v96
	v_exp_f32_e64 v98, -v96
	v_pk_add_f32 v[48:49], v[48:49], v[96:97] op_sel_hi:[1,0] neg_lo:[0,1] neg_hi:[0,1]
	v_pk_add_f32 v[32:33], v[32:33], v[96:97] op_sel_hi:[1,0] neg_lo:[0,1] neg_hi:[0,1]
	v_pk_add_f32 v[50:51], v[50:51], v[96:97] op_sel_hi:[1,0] neg_lo:[0,1] neg_hi:[0,1]
	v_pk_mul_f32 v[14:15], v[14:15], v[98:99] op_sel_hi:[1,0]
	v_pk_mul_f32 v[12:13], v[12:13], v[98:99] op_sel_hi:[1,0]
	v_pk_mul_f32 v[10:11], v[10:11], v[98:99] op_sel_hi:[1,0]
	v_pk_mul_f32 v[8:9], v[8:9], v[98:99] op_sel_hi:[1,0]
	v_pk_mul_f32 v[6:7], v[6:7], v[98:99] op_sel_hi:[1,0]
	v_pk_mul_f32 v[4:5], v[4:5], v[98:99] op_sel_hi:[1,0]
	v_pk_mul_f32 v[2:3], v[2:3], v[98:99] op_sel_hi:[1,0]
	v_pk_mul_f32 v[0:1], v[0:1], v[98:99] op_sel_hi:[1,0]
	v_pk_mul_f32 v[30:31], v[30:31], v[98:99] op_sel_hi:[1,0]
	v_pk_mul_f32 v[28:29], v[28:29], v[98:99] op_sel_hi:[1,0]
	v_pk_mul_f32 v[26:27], v[26:27], v[98:99] op_sel_hi:[1,0]
	v_pk_mul_f32 v[24:25], v[24:25], v[98:99] op_sel_hi:[1,0]
	v_pk_mul_f32 v[22:23], v[22:23], v[98:99] op_sel_hi:[1,0]
	v_pk_mul_f32 v[20:21], v[20:21], v[98:99] op_sel_hi:[1,0]
	v_pk_mul_f32 v[18:19], v[18:19], v[98:99] op_sel_hi:[1,0]
	v_pk_mul_f32 v[16:17], v[16:17], v[98:99] op_sel_hi:[1,0]
	v_mul_f32_e32 v136, v136, v98
	v_pk_add_f32 v[34:35], v[34:35], v[96:97] op_sel_hi:[1,0] neg_lo:[0,1] neg_hi:[0,1]
	v_pk_add_f32 v[52:53], v[52:53], v[96:97] op_sel_hi:[1,0] neg_lo:[0,1] neg_hi:[0,1]
	v_pk_add_f32 v[36:37], v[36:37], v[96:97] op_sel_hi:[1,0] neg_lo:[0,1] neg_hi:[0,1]
	v_pk_add_f32 v[54:55], v[54:55], v[96:97] op_sel_hi:[1,0] neg_lo:[0,1] neg_hi:[0,1]
	v_pk_add_f32 v[38:39], v[38:39], v[96:97] op_sel_hi:[1,0] neg_lo:[0,1] neg_hi:[0,1]
	v_pk_add_f32 v[56:57], v[56:57], v[96:97] op_sel_hi:[1,0] neg_lo:[0,1] neg_hi:[0,1]
	v_pk_add_f32 v[40:41], v[40:41], v[96:97] op_sel_hi:[1,0] neg_lo:[0,1] neg_hi:[0,1]
	v_pk_add_f32 v[58:59], v[58:59], v[96:97] op_sel_hi:[1,0] neg_lo:[0,1] neg_hi:[0,1]
	v_pk_add_f32 v[42:43], v[42:43], v[96:97] op_sel_hi:[1,0] neg_lo:[0,1] neg_hi:[0,1]
	v_pk_add_f32 v[60:61], v[60:61], v[96:97] op_sel_hi:[1,0] neg_lo:[0,1] neg_hi:[0,1]
	v_pk_add_f32 v[44:45], v[44:45], v[96:97] op_sel_hi:[1,0] neg_lo:[0,1] neg_hi:[0,1]
	v_pk_add_f32 v[62:63], v[62:63], v[96:97] op_sel_hi:[1,0] neg_lo:[0,1] neg_hi:[0,1]
	v_pk_add_f32 v[46:47], v[46:47], v[96:97] op_sel_hi:[1,0] neg_lo:[0,1] neg_hi:[0,1]

.LBB0_954:
	s_or_b64 exec, exec, s[0:1]
	v_add_co_u32_e32 v0, vcc, 0x4000, v16
	v_mad_u32_u24 v33, v73, s9, 0
	s_nop 0
	v_addc_co_u32_e32 v1, vcc, 0, v17, vcc
	global_load_dwordx4 v[152:155], v[0:1], off
	global_load_dwordx4 v[156:159], v[0:1], off offset:256
	v_add_u32_e32 v242, v33, v204
	ds_read_b128 v[0:3], v242
	ds_read_b128 v[16:19], v242 offset:0x1200
	ds_read_b128 v[34:37], v242 offset:32
	ds_read_b128 v[38:41], v242 offset:0x1220
	ds_read_b128 v[42:45], v242 offset:64
	ds_read_b128 v[46:49], v242 offset:0x1240
	ds_read_b128 v[56:59], v242 offset:96
	ds_read_b128 v[50:53], v242 offset:0x1260
	s_waitcnt lgkmcnt(0)
	v_lshlrev_b32_e32 v244, 3, v32
	v_mfma_f32_32x32x16_bf16 v[0:15], v[0:3], v[140:143], 0
	v_lshlrev_b32_e32 v32, 3, v73
	v_sub_u32_e32 v32, v33, v32
	v_add_u32_e32 v243, v32, v244
	v_add_u32_e32 v72, 0x3400, v243
	v_and_b32_e32 v91, 15, v91
	v_mul_u32_u24_e32 v245, 0x90, v73
	v_mul_u32_u24_e32 v246, 0x88, v73
	v_mfma_f32_32x32x16_bf16 v[16:31], v[16:19], v[140:143], 0
	s_movk_i32 s1, 0xffe0
	s_and_b32 s0, s13, 28
	s_add_i32 s0, s8, s0
	s_mul_hi_i32 s9, s0, 0x90000
	s_mul_i32 s8, s0, 0x90000
	s_mov_b32 s28, 0x8000
	v_mfma_f32_32x32x16_bf16 v[0:15], v[34:37], v[136:139], v[0:15]
	v_mfma_f32_32x32x16_bf16 v[16:31], v[38:41], v[136:139], v[16:31]
	v_mfma_f32_32x32x16_bf16 v[0:15], v[42:45], v[132:135], v[0:15]
	v_mfma_f32_32x32x16_bf16 v[16:31], v[46:49], v[132:135], v[16:31]
	v_mfma_f32_32x32x16_bf16 v[16:31], v[50:53], v[128:131], v[16:31]
	ds_read_b64 v[94:95], v72
	ds_read_b64 v[96:97], v72 offset:16
	ds_read_b64 v[60:61], v72 offset:32
	ds_read_b64 v[62:63], v72 offset:48
	ds_read_b64 v[52:53], v72 offset:64
	ds_read_b64 v[54:55], v72 offset:80
	ds_read_b64 v[48:49], v72 offset:96
	ds_read_b64 v[50:51], v72 offset:112
	ds_read_b64 v[44:45], v72 offset:0x1100
	ds_read_b64 v[46:47], v72 offset:0x1110
	ds_read_b64 v[40:41], v72 offset:0x1120
	ds_read_b64 v[42:43], v72 offset:0x1130
	ds_read_b64 v[36:37], v72 offset:0x1140
	ds_read_b64 v[38:39], v72 offset:0x1150
	ds_read_b64 v[32:33], v72 offset:0x1160
	ds_read_b64 v[34:35], v72 offset:0x1170
	s_nop 0
	s_waitcnt lgkmcnt(0)
	v_mfma_f32_32x32x16_bf16 v[0:15], v[56:59], v[128:131], v[0:15]
	s_nop 11
	v_max_f32_e32 v57, v1, v17
	v_max_f32_e32 v58, v3, v19
	v_max_f32_e32 v56, v0, v16
	v_max3_f32 v58, v2, v18, v58
	v_max3_f32 v56, v56, v57, v58
	v_max_f32_e32 v57, v5, v21
	v_max_f32_e32 v58, v7, v23
	v_max3_f32 v57, v4, v20, v57
	v_max3_f32 v58, v6, v22, v58
	v_max3_f32 v56, v56, v57, v58
	v_max_f32_e32 v57, v9, v25
	v_max_f32_e32 v58, v11, v27
	v_max3_f32 v57, v8, v24, v57
	v_max3_f32 v58, v10, v26, v58
	v_max3_f32 v56, v56, v57, v58
	v_max_f32_e32 v57, v13, v29
	v_max_f32_e32 v59, v15, v15
	v_max_f32_e32 v58, v59, v31
	v_max3_f32 v57, v12, v28, v57
	v_max3_f32 v58, v14, v30, v58
	v_max3_f32 v56, v56, v57, v58
	v_mov_b32_e32 v57, v56
	s_nop 1
	v_permlane32_swap_b32_e32 v56, v57
	v_max_f32_e32 v72, v56, v57
	v_sub_f32_e32 v0, v0, v72
	v_sub_f32_e32 v1, v1, v72
	v_sub_f32_e32 v2, v2, v72
	v_sub_f32_e32 v3, v3, v72
	v_sub_f32_e32 v4, v4, v72
	v_sub_f32_e32 v5, v5, v72
	v_sub_f32_e32 v6, v6, v72
	v_sub_f32_e32 v7, v7, v72
	v_exp_f32_e32 v74, v0
	v_exp_f32_e32 v75, v1
	v_exp_f32_e32 v78, v2
	v_exp_f32_e32 v79, v3
	v_exp_f32_e32 v84, v4
	v_exp_f32_e32 v85, v5
	v_exp_f32_e32 v86, v6
	v_exp_f32_e32 v87, v7
	v_sub_f32_e32 v16, v16, v72
	v_sub_f32_e32 v17, v17, v72
	v_sub_f32_e32 v18, v18, v72
	v_sub_f32_e32 v19, v19, v72
	v_sub_f32_e32 v20, v20, v72
	v_sub_f32_e32 v21, v21, v72
	v_sub_f32_e32 v22, v22, v72
	v_sub_f32_e32 v23, v23, v72
	v_sub_f32_e32 v24, v24, v72
	v_sub_f32_e32 v25, v25, v72
	v_sub_f32_e32 v26, v26, v72
	v_sub_f32_e32 v27, v27, v72
	v_sub_f32_e32 v28, v28, v72
	v_sub_f32_e32 v29, v29, v72
	v_sub_f32_e32 v30, v30, v72
	v_sub_f32_e32 v31, v31, v72
	v_sub_f32_e32 v8, v8, v72
	v_sub_f32_e32 v9, v9, v72
	v_sub_f32_e32 v10, v10, v72
	v_sub_f32_e32 v11, v11, v72
	v_sub_f32_e32 v12, v12, v72
	v_cvt_pk_bf16_f32 v98, v74, v75
	v_cvt_pk_bf16_f32 v99, v78, v79
	v_cvt_pk_bf16_f32 v100, v84, v85
	v_cvt_pk_bf16_f32 v101, v86, v87
	v_sub_f32_e32 v56, v13, v72
	v_sub_f32_e32 v57, v14, v72
	v_sub_f32_e32 v58, v15, v72
	v_exp_f32_e32 v76, v16
	v_exp_f32_e32 v77, v17
	v_exp_f32_e32 v80, v18
	v_exp_f32_e32 v81, v19
	v_exp_f32_e32 v82, v20
	v_exp_f32_e32 v83, v21
	v_exp_f32_e32 v88, v22
	v_exp_f32_e32 v89, v23
	v_exp_f32_e32 v122, v8
	v_exp_f32_e32 v123, v9
	v_exp_f32_e32 v124, v24
	v_exp_f32_e32 v125, v25
	v_exp_f32_e32 v126, v10
	v_exp_f32_e32 v127, v11
	v_exp_f32_e32 v160, v12
	v_mfma_f32_32x32x16_bf16 v[0:15], v[94:97], v[98:101], 0
	v_exp_f32_e32 v164, v26
	v_exp_f32_e32 v165, v27
	v_exp_f32_e32 v166, v28
	v_exp_f32_e32 v167, v29
	v_exp_f32_e32 v168, v30
	v_exp_f32_e32 v169, v31
	v_exp_f32_e32 v161, v56
	v_mfma_f32_32x32x16_bf16 v[16:31], v[44:47], v[98:101], 0
	v_exp_f32_e32 v162, v57
	v_exp_f32_e32 v163, v58
	v_cvt_pk_bf16_f32 v94, v122, v123
	v_cvt_pk_bf16_f32 v95, v126, v127
	v_cvt_pk_bf16_f32 v96, v160, v161
	v_cvt_pk_bf16_f32 v97, v162, v163
	v_cvt_pk_bf16_f32 v102, v76, v77
	v_cvt_pk_bf16_f32 v103, v80, v81
	v_mfma_f32_32x32x16_bf16 v[0:15], v[60:63], v[94:97], v[0:15]
	v_cvt_pk_bf16_f32 v104, v82, v83
	v_cvt_pk_bf16_f32 v105, v88, v89
	v_cvt_pk_bf16_f32 v106, v124, v125
	v_cvt_pk_bf16_f32 v107, v164, v165
	v_cvt_pk_bf16_f32 v108, v166, v167
	v_cvt_pk_bf16_f32 v109, v168, v169
	v_pk_add_f32 v[74:75], v[74:75], 0 op_sel_hi:[1,0]
	v_mfma_f32_32x32x16_bf16 v[16:31], v[40:43], v[94:97], v[16:31]
	v_add_f32_e64 v74, v76, v74
	v_add_f32_e64 v75, v77, v75
	v_add_f32_e64 v74, v78, v74
	v_add_f32_e64 v75, v79, v75
	v_add_f32_e64 v74, v80, v74
	v_add_f32_e64 v75, v81, v75
	v_pk_add_f32 v[74:75], v[84:85], v[74:75]
	v_mfma_f32_32x32x16_bf16 v[0:15], v[52:55], v[102:105], v[0:15]
	v_add_u32_e32 v52, 0x5600, v243
	v_add_f32_e64 v74, v82, v74
	v_add_f32_e64 v75, v83, v75
	v_add_f32_e64 v74, v86, v74
	v_add_f32_e64 v75, v87, v75
	v_pk_add_f32 v[74:75], v[88:89], v[74:75]
	v_mfma_f32_32x32x16_bf16 v[16:31], v[36:39], v[102:105], v[16:31]
	v_add_f32_e64 v74, v122, v74
	v_add_f32_e64 v75, v123, v75
	v_add_f32_e64 v74, v124, v74
	v_add_f32_e64 v75, v125, v75
	v_add_f32_e64 v74, v126, v74
	v_add_f32_e64 v75, v127, v75
	v_pk_add_f32 v[74:75], v[164:165], v[74:75]
	v_mfma_f32_32x32x16_bf16 v[0:15], v[48:51], v[106:109], v[0:15]
	v_add_f32_e64 v74, v160, v74
	v_add_f32_e64 v75, v161, v75
	v_add_f32_e64 v74, v166, v74
	v_add_f32_e64 v75, v167, v75
	v_add_f32_e64 v74, v162, v74
	v_add_f32_e64 v75, v163, v75
	v_pk_add_f32 v[74:75], v[168:169], v[74:75]
	v_mfma_f32_32x32x16_bf16 v[16:31], v[32:35], v[106:109], v[16:31]
	ds_read_b64 v[48:49], v52
	ds_read_b64 v[50:51], v52 offset:16
	ds_read_b64 v[44:45], v52 offset:32
	ds_read_b64 v[46:47], v52 offset:48
	ds_read_b64 v[40:41], v52 offset:64
	ds_read_b64 v[42:43], v52 offset:80
	ds_read_b64 v[36:37], v52 offset:96
	ds_read_b64 v[38:39], v52 offset:112
	ds_read_b64 v[32:33], v52 offset:0x1100
	ds_read_b64 v[34:35], v52 offset:0x1110
	ds_read_b64 v[118:119], v52 offset:0x1120
	ds_read_b64 v[120:121], v52 offset:0x1130
	ds_read_b64 v[114:115], v52 offset:0x1140
	ds_read_b64 v[116:117], v52 offset:0x1150
	ds_read_b64 v[110:111], v52 offset:0x1160
	ds_read_b64 v[112:113], v52 offset:0x1170
	v_pk_add_f32 v[74:75], v[74:75], v[74:75] op_sel_hi:[0,1]
	s_waitcnt lgkmcnt(0)
	v_mov_b32_e32 v73, v75
	v_pk_add_f32 v[212:213], v[72:73], 0 op_sel_hi:[1,0]
	v_lshlrev_b32_e32 v72, 1, v93
	v_lshlrev_b32_e32 v73, 1, v91
	v_mfma_f32_32x32x16_bf16 v[48:63], v[48:51], v[98:101], 0
	v_and_or_b32 v72, v72, s1, v73
	v_ashrrev_i32_e32 v73, 31, v72
	v_lshlrev_b64 v[72:73], 8, v[72:73]
	v_mov_b32_e32 v74, 0x90000
	v_mad_i64_i32 v[206:207], s[0:1], s0, v74, v[72:73]
	s_add_i32 s0, s20, s21
	v_mfma_f32_32x32x16_bf16 v[48:63], v[44:47], v[94:97], v[48:63]
	s_mul_i32 s21, s0, 0x48000
	s_mul_hi_i32 s20, s0, 0x48000
	s_add_u32 s0, s21, 0x9604000
	s_addc_u32 s1, s20, 0
	v_add_f32_e64 v80, -v212, neg(0)
	v_add_f32_e64 v81, -v213, neg(0)
	v_lshlrev_b32_e32 v72, 4, v92
	v_and_b32_e32 v73, 0xc0, v90
	v_mfma_f32_32x32x16_bf16 v[48:63], v[40:43], v[102:105], v[48:63]
	v_lshl_add_u64 v[68:69], v[68:69], 1, s[0:1]
	v_lshl_add_u64 v[64:65], v[64:65], 1, s[0:1]
	v_or3_b32 v206, v73, v72, v206
	v_lshl_add_u64 v[208:209], v[70:71], 1, v[68:69]
	v_lshl_add_u64 v[210:211], v[66:67], 1, v[64:65]
	v_mov_b32_e32 v81, v80
	v_mov_b32_e32 v82, v80
	v_mfma_f32_32x32x16_bf16 v[48:63], v[36:39], v[106:109], v[48:63]
	v_mov_b32_e32 v83, v80
	v_mov_b32_e32 v84, v80
	v_mov_b32_e32 v85, v80
	v_mov_b32_e32 v86, v80
	v_mov_b32_e32 v87, v80
	v_mov_b32_e32 v88, v80
	v_mov_b32_e32 v89, v80
	v_mfma_f32_32x32x16_bf16 v[32:47], v[32:35], v[98:101], 0
	v_mov_b32_e32 v90, v80
	v_mov_b32_e32 v91, v80
	v_mov_b32_e32 v92, v80
	v_mov_b32_e32 v93, v80
	v_mfma_f32_32x32x16_bf16 v[32:47], v[118:121], v[94:97], v[32:47]
	v_mov_b32_e32 v94, v80
	v_mov_b32_e32 v95, v80
	v_mfma_f32_32x32x16_bf16 v[32:47], v[114:117], v[102:105], v[32:47]
	v_mfma_f32_32x32x16_bf16 v[32:47], v[110:113], v[106:109], v[32:47]

.LBB0_959:
	s_or_b64 exec, exec, s[0:1]
	v_lshl_add_u64 v[64:65], s[4:5], 0, v[206:207]
	v_add_co_u32_e32 v64, vcc, 0xa808000, v64
	v_add3_u32 v96, s29, v245, v204
	s_nop 0
	v_addc_co_u32_e32 v65, vcc, 0, v65, vcc
	global_load_dwordx4 v[152:155], v[64:65], off
	global_load_dwordx4 v[156:159], v[64:65], off offset:256
	ds_read_b128 v[64:67], v96
	ds_read_b128 v[68:71], v96 offset:0x1200
	ds_read_b128 v[72:75], v96 offset:32
	ds_read_b128 v[76:79], v96 offset:0x1220
	ds_read_b128 v[160:163], v96 offset:64
	ds_read_b128 v[164:167], v96 offset:0x1240
	ds_read_b128 v[168:171], v96 offset:96
	ds_read_b128 v[172:175], v96 offset:0x1260
	s_waitcnt lgkmcnt(0)
	s_nop 0
	v_mfma_f32_32x32x16_bf16 v[112:127], v[64:67], v[140:143], v[80:95]
	v_add_u32_e32 v64, s29, v246
	v_add3_u32 v247, v64, v244, s87
	v_mfma_f32_32x32x16_bf16 v[96:111], v[68:71], v[140:143], v[80:95]
	v_mfma_f32_32x32x16_bf16 v[112:127], v[72:75], v[136:139], v[112:127]
	v_mfma_f32_32x32x16_bf16 v[96:111], v[76:79], v[136:139], v[96:111]
	v_mfma_f32_32x32x16_bf16 v[112:127], v[160:163], v[132:135], v[112:127]
	v_mfma_f32_32x32x16_bf16 v[96:111], v[164:167], v[132:135], v[96:111]
	v_mfma_f32_32x32x16_bf16 v[112:127], v[168:171], v[128:131], v[112:127]
	v_mfma_f32_32x32x16_bf16 v[96:111], v[172:175], v[128:131], v[96:111]
	s_nop 10
	ds_read_b64 v[188:189], v247
	ds_read_b64 v[190:191], v247 offset:16
	ds_read_b64 v[184:185], v247 offset:32
	ds_read_b64 v[186:187], v247 offset:48
	ds_read_b64 v[180:181], v247 offset:64
	ds_read_b64 v[182:183], v247 offset:80
	ds_read_b64 v[176:177], v247 offset:96
	ds_read_b64 v[178:179], v247 offset:112
	ds_read_b64 v[172:173], v247 offset:0x1100
	ds_read_b64 v[174:175], v247 offset:0x1110
	ds_read_b64 v[168:169], v247 offset:0x1120
	ds_read_b64 v[170:171], v247 offset:0x1130
	ds_read_b64 v[164:165], v247 offset:0x1140
	ds_read_b64 v[166:167], v247 offset:0x1150
	ds_read_b64 v[160:161], v247 offset:0x1160
	ds_read_b64 v[162:163], v247 offset:0x1170
	v_max_f32_e32 v64, v112, v96
	v_max_f32_e32 v65, v113, v97
	v_max_f32_e32 v66, v115, v99
	v_max3_f32 v66, v114, v98, v66
	v_max3_f32 v64, v64, v65, v66
	v_max_f32_e32 v65, v117, v101
	v_max_f32_e32 v66, v119, v103
	v_max3_f32 v65, v116, v100, v65
	v_max3_f32 v66, v118, v102, v66
	v_max3_f32 v64, v64, v65, v66
	v_max_f32_e32 v65, v121, v105
	v_max_f32_e32 v66, v123, v107
	v_max3_f32 v65, v120, v104, v65
	v_max3_f32 v66, v122, v106, v66
	v_max3_f32 v64, v64, v65, v66
	v_max_f32_e32 v65, v125, v109
	v_max_f32_e32 v67, v127, v127
	v_max_f32_e32 v66, v67, v111
	v_max3_f32 v65, v124, v108, v65
	v_max3_f32 v66, v126, v110, v66
	v_max3_f32 v64, v64, v65, v66
	v_mov_b32_e32 v65, v64
	s_nop 1
	v_permlane32_swap_b32_e32 v64, v65
	v_max_f32_e32 v64, v64, v65
	v_cmp_lt_f32_e32 vcc, s80, v64
	s_cbranch_vccz .LBB0_961
	v_max_f32_e32 v80, 0, v64
	v_exp_f32_e64 v64, -v80
	s_nop 0
	v_mov_b32_e32 v81, v64
	v_pk_mul_f32 v[14:15], v[14:15], v[64:65] op_sel_hi:[1,0]
	v_pk_mul_f32 v[12:13], v[12:13], v[64:65] op_sel_hi:[1,0]
	v_pk_mul_f32 v[10:11], v[10:11], v[64:65] op_sel_hi:[1,0]
	v_pk_mul_f32 v[8:9], v[8:9], v[64:65] op_sel_hi:[1,0]
	v_pk_mul_f32 v[6:7], v[6:7], v[64:65] op_sel_hi:[1,0]
	v_pk_mul_f32 v[4:5], v[4:5], v[64:65] op_sel_hi:[1,0]
	v_pk_mul_f32 v[2:3], v[2:3], v[64:65] op_sel_hi:[1,0]
	v_pk_mul_f32 v[0:1], v[0:1], v[64:65] op_sel_hi:[1,0]
	v_pk_mul_f32 v[30:31], v[30:31], v[64:65] op_sel_hi:[1,0]
	v_pk_mul_f32 v[28:29], v[28:29], v[64:65] op_sel_hi:[1,0]
	v_pk_mul_f32 v[26:27], v[26:27], v[64:65] op_sel_hi:[1,0]
	v_pk_mul_f32 v[24:25], v[24:25], v[64:65] op_sel_hi:[1,0]
	v_pk_mul_f32 v[22:23], v[22:23], v[64:65] op_sel_hi:[1,0]
	v_pk_mul_f32 v[20:21], v[20:21], v[64:65] op_sel_hi:[1,0]
	v_pk_mul_f32 v[18:19], v[18:19], v[64:65] op_sel_hi:[1,0]
	v_pk_mul_f32 v[16:17], v[16:17], v[64:65] op_sel_hi:[1,0]
	v_pk_mul_f32 v[62:63], v[62:63], v[64:65] op_sel_hi:[1,0]
	v_pk_mul_f32 v[60:61], v[60:61], v[64:65] op_sel_hi:[1,0]
	v_pk_mul_f32 v[58:59], v[58:59], v[64:65] op_sel_hi:[1,0]
	v_pk_mul_f32 v[56:57], v[56:57], v[64:65] op_sel_hi:[1,0]
	v_pk_mul_f32 v[54:55], v[54:55], v[64:65] op_sel_hi:[1,0]
	v_pk_mul_f32 v[52:53], v[52:53], v[64:65] op_sel_hi:[1,0]
	v_pk_mul_f32 v[50:51], v[50:51], v[64:65] op_sel_hi:[1,0]
	v_pk_mul_f32 v[48:49], v[48:49], v[64:65] op_sel_hi:[1,0]
	v_pk_mul_f32 v[46:47], v[46:47], v[64:65] op_sel_hi:[1,0]
	v_pk_mul_f32 v[44:45], v[44:45], v[64:65] op_sel_hi:[1,0]
	v_pk_mul_f32 v[42:43], v[42:43], v[64:65] op_sel_hi:[1,0]
	v_pk_mul_f32 v[40:41], v[40:41], v[64:65] op_sel_hi:[1,0]
	v_pk_mul_f32 v[38:39], v[38:39], v[64:65] op_sel_hi:[1,0]
	v_pk_mul_f32 v[36:37], v[36:37], v[64:65] op_sel_hi:[1,0]
	v_pk_mul_f32 v[34:35], v[34:35], v[64:65] op_sel_hi:[1,0]
	v_pk_mul_f32 v[32:33], v[32:33], v[64:65] op_sel_hi:[1,0]
	v_pk_add_f32 v[214:215], v[212:213], v[80:81]
	v_pk_mul_f32 v[64:65], v[212:213], v[80:81]
	v_pk_add_f32 v[112:113], v[112:113], v[80:81] op_sel_hi:[1,0] neg_lo:[0,1] neg_hi:[0,1]
	v_mov_b32_e32 v215, v65
	v_pk_add_f32 v[64:65], v[214:215], 0 neg_lo:[1,1] neg_hi:[1,1]
	v_pk_add_f32 v[96:97], v[96:97], v[80:81] op_sel_hi:[1,0] neg_lo:[0,1] neg_hi:[0,1]
	v_pk_add_f32 v[114:115], v[114:115], v[80:81] op_sel_hi:[1,0] neg_lo:[0,1] neg_hi:[0,1]
	v_pk_add_f32 v[98:99], v[98:99], v[80:81] op_sel_hi:[1,0] neg_lo:[0,1] neg_hi:[0,1]
	v_pk_add_f32 v[116:117], v[116:117], v[80:81] op_sel_hi:[1,0] neg_lo:[0,1] neg_hi:[0,1]
	v_pk_add_f32 v[100:101], v[100:101], v[80:81] op_sel_hi:[1,0] neg_lo:[0,1] neg_hi:[0,1]
	v_pk_add_f32 v[118:119], v[118:119], v[80:81] op_sel_hi:[1,0] neg_lo:[0,1] neg_hi:[0,1]
	v_pk_add_f32 v[102:103], v[102:103], v[80:81] op_sel_hi:[1,0] neg_lo:[0,1] neg_hi:[0,1]
	v_pk_add_f32 v[120:121], v[120:121], v[80:81] op_sel_hi:[1,0] neg_lo:[0,1] neg_hi:[0,1]
	v_pk_add_f32 v[104:105], v[104:105], v[80:81] op_sel_hi:[1,0] neg_lo:[0,1] neg_hi:[0,1]
	v_pk_add_f32 v[122:123], v[122:123], v[80:81] op_sel_hi:[1,0] neg_lo:[0,1] neg_hi:[0,1]
	v_pk_add_f32 v[106:107], v[106:107], v[80:81] op_sel_hi:[1,0] neg_lo:[0,1] neg_hi:[0,1]
	v_pk_add_f32 v[124:125], v[124:125], v[80:81] op_sel_hi:[1,0] neg_lo:[0,1] neg_hi:[0,1]
	v_pk_add_f32 v[108:109], v[108:109], v[80:81] op_sel_hi:[1,0] neg_lo:[0,1] neg_hi:[0,1]
	v_mov_b32_e32 v65, v64
	v_mov_b32_e32 v66, v64
	v_mov_b32_e32 v67, v64
	v_mov_b32_e32 v68, v64
	v_mov_b32_e32 v69, v64
	v_mov_b32_e32 v70, v64
	v_mov_b32_e32 v71, v64
	v_mov_b32_e32 v72, v64
	v_mov_b32_e32 v73, v64
	v_mov_b32_e32 v74, v64
	v_mov_b32_e32 v75, v64
	v_mov_b32_e32 v76, v64
	v_mov_b32_e32 v77, v64
	v_mov_b32_e32 v78, v64
	v_mov_b32_e32 v79, v64
	v_pk_add_f32 v[126:127], v[126:127], v[80:81] op_sel_hi:[1,0] neg_lo:[0,1] neg_hi:[0,1]
	v_pk_add_f32 v[110:111], v[110:111], v[80:81] op_sel_hi:[1,0] neg_lo:[0,1] neg_hi:[0,1]
	v_mov_b32_e32 v80, v64
	v_mov_b32_e32 v81, v64
	v_mov_b32_e32 v82, v64
	v_mov_b32_e32 v83, v64
	v_mov_b32_e32 v84, v64
	v_mov_b32_e32 v85, v64
	v_mov_b32_e32 v86, v64
	v_mov_b32_e32 v87, v64
	v_mov_b32_e32 v88, v64
	v_mov_b32_e32 v89, v64
	v_mov_b32_e32 v90, v64
	v_mov_b32_e32 v91, v64
	v_mov_b32_e32 v92, v64
	v_mov_b32_e32 v93, v64
	v_mov_b32_e32 v94, v64
	v_mov_b32_e32 v95, v64
	v_mov_b32_e32 v212, v214
	s_branch .LBB0_962

.LBB0_964:
	s_waitcnt vmcnt(2)
	ds_write_b128 v222, v[148:151] offset:32768
	s_and_saveexec_b64 s[0:1], s[2:3]
	ds_write_b128 v192, v[144:147] offset:32768
	s_or_b64 exec, exec, s[0:1]
	s_waitcnt vmcnt(0)
	v_perm_b32 v80, v156, v152, s85
	v_perm_b32 v81, v156, v152, s86
	v_add_u32_e32 v82, 0xb400, v223
	ds_write2_b32 v82, v80, v81 offset1:34
	v_perm_b32 v80, v157, v153, s85
	v_perm_b32 v81, v157, v153, s86
	ds_write2_b32 v82, v80, v81 offset0:68 offset1:102
	v_perm_b32 v80, v158, v154, s85
	v_perm_b32 v81, v158, v154, s86
	ds_write2_b32 v82, v80, v81 offset0:136 offset1:170
	v_perm_b32 v80, v159, v155, s85
	v_perm_b32 v81, v159, v155, s86
	ds_write2_b32 v82, v80, v81 offset0:204 offset1:238
	v_add_u32_e32 v80, 0x8000, v242
	s_waitcnt lgkmcnt(0)
	s_barrier
	ds_read_b128 v[96:99], v80
	ds_read_b128 v[100:103], v80 offset:0x1200
	ds_read_b128 v[104:107], v80 offset:32
	ds_read_b128 v[108:111], v80 offset:0x1220
	ds_read_b128 v[112:115], v80 offset:64
	ds_read_b128 v[116:119], v80 offset:0x1240
	ds_read_b128 v[144:147], v80 offset:96
	ds_read_b128 v[120:123], v80 offset:0x1260
	s_waitcnt lgkmcnt(0)
	s_nop 0
	v_mfma_f32_32x32x16_bf16 v[80:95], v[96:99], v[140:143], v[64:79]
	v_mfma_f32_32x32x16_bf16 v[64:79], v[100:103], v[140:143], v[64:79]
	v_mfma_f32_32x32x16_bf16 v[80:95], v[104:107], v[136:139], v[80:95]
	v_mfma_f32_32x32x16_bf16 v[64:79], v[108:111], v[136:139], v[64:79]
	v_mfma_f32_32x32x16_bf16 v[80:95], v[112:115], v[132:135], v[80:95]
	v_mfma_f32_32x32x16_bf16 v[64:79], v[116:119], v[132:135], v[64:79]
	v_add_u32_e32 v132, 0xb400, v243
	v_mfma_f32_32x32x16_bf16 v[64:79], v[120:123], v[128:131], v[64:79]
	ds_read_b64 v[124:125], v132
	ds_read_b64 v[126:127], v132 offset:16
	ds_read_b64 v[120:121], v132 offset:32
	ds_read_b64 v[122:123], v132 offset:48
	ds_read_b64 v[116:117], v132 offset:64
	ds_read_b64 v[118:119], v132 offset:80
	ds_read_b64 v[112:113], v132 offset:96
	ds_read_b64 v[114:115], v132 offset:112
	ds_read_b64 v[108:109], v132 offset:0x1100
	ds_read_b64 v[110:111], v132 offset:0x1110
	ds_read_b64 v[104:105], v132 offset:0x1120
	ds_read_b64 v[106:107], v132 offset:0x1130
	ds_read_b64 v[100:101], v132 offset:0x1140
	ds_read_b64 v[102:103], v132 offset:0x1150
	ds_read_b64 v[96:97], v132 offset:0x1160
	ds_read_b64 v[98:99], v132 offset:0x1170
	v_mfma_f32_32x32x16_bf16 v[80:95], v[144:147], v[128:131], v[80:95]
	s_nop 10
	v_max_f32_e32 v133, v64, v64
	v_max_f32_e32 v129, v81, v65
	v_max_f32_e32 v130, v83, v67
	v_max_f32_e32 v128, v80, v133
	v_max3_f32 v130, v82, v66, v130
	v_max3_f32 v128, v128, v129, v130
	v_max_f32_e32 v129, v85, v69
	v_max_f32_e32 v130, v87, v71
	v_max3_f32 v129, v84, v68, v129
	v_max3_f32 v130, v86, v70, v130
	v_max3_f32 v128, v128, v129, v130
	v_max_f32_e32 v129, v89, v73
	v_max_f32_e32 v130, v91, v75
	v_max3_f32 v129, v88, v72, v129
	v_max3_f32 v130, v90, v74, v130
	v_max3_f32 v128, v128, v129, v130
	v_max_f32_e32 v129, v93, v77
	v_max_f32_e32 v131, v95, v95
	v_max_f32_e32 v130, v131, v79
	v_max3_f32 v129, v92, v76, v129
	v_max3_f32 v130, v94, v78, v130
	v_max3_f32 v128, v128, v129, v130
	v_mov_b32_e32 v129, v128
	s_nop 1
	v_permlane32_swap_b32_e32 v128, v129
	v_max_f32_e32 v128, v128, v129
	v_cmp_lt_f32_e32 vcc, s80, v128
	s_cbranch_vccz .LBB0_968
	v_max_f32_e32 v128, 0, v128
	v_exp_f32_e64 v130, -v128
	v_pk_add_f32 v[80:81], v[80:81], v[128:129] op_sel_hi:[1,0] neg_lo:[0,1] neg_hi:[0,1]
	v_pk_add_f32 v[64:65], v[64:65], v[128:129] op_sel_hi:[1,0] neg_lo:[0,1] neg_hi:[0,1]
	v_pk_add_f32 v[82:83], v[82:83], v[128:129] op_sel_hi:[1,0] neg_lo:[0,1] neg_hi:[0,1]
	v_pk_mul_f32 v[14:15], v[14:15], v[130:131] op_sel_hi:[1,0]
	v_pk_mul_f32 v[12:13], v[12:13], v[130:131] op_sel_hi:[1,0]
	v_pk_mul_f32 v[10:11], v[10:11], v[130:131] op_sel_hi:[1,0]
	v_pk_mul_f32 v[8:9], v[8:9], v[130:131] op_sel_hi:[1,0]
	v_pk_mul_f32 v[6:7], v[6:7], v[130:131] op_sel_hi:[1,0]
	v_pk_mul_f32 v[4:5], v[4:5], v[130:131] op_sel_hi:[1,0]
	v_pk_mul_f32 v[2:3], v[2:3], v[130:131] op_sel_hi:[1,0]
	v_pk_mul_f32 v[0:1], v[0:1], v[130:131] op_sel_hi:[1,0]
	v_pk_mul_f32 v[30:31], v[30:31], v[130:131] op_sel_hi:[1,0]
	v_pk_mul_f32 v[28:29], v[28:29], v[130:131] op_sel_hi:[1,0]
	v_pk_mul_f32 v[26:27], v[26:27], v[130:131] op_sel_hi:[1,0]
	v_pk_mul_f32 v[24:25], v[24:25], v[130:131] op_sel_hi:[1,0]
	v_pk_mul_f32 v[22:23], v[22:23], v[130:131] op_sel_hi:[1,0]
	v_pk_mul_f32 v[20:21], v[20:21], v[130:131] op_sel_hi:[1,0]
	v_pk_mul_f32 v[18:19], v[18:19], v[130:131] op_sel_hi:[1,0]
	v_pk_mul_f32 v[16:17], v[16:17], v[130:131] op_sel_hi:[1,0]
	v_pk_mul_f32 v[62:63], v[62:63], v[130:131] op_sel_hi:[1,0]
	v_pk_mul_f32 v[60:61], v[60:61], v[130:131] op_sel_hi:[1,0]
	v_pk_mul_f32 v[58:59], v[58:59], v[130:131] op_sel_hi:[1,0]
	v_pk_mul_f32 v[56:57], v[56:57], v[130:131] op_sel_hi:[1,0]
	v_pk_mul_f32 v[54:55], v[54:55], v[130:131] op_sel_hi:[1,0]
	v_pk_mul_f32 v[52:53], v[52:53], v[130:131] op_sel_hi:[1,0]
	v_pk_mul_f32 v[50:51], v[50:51], v[130:131] op_sel_hi:[1,0]
	v_pk_mul_f32 v[48:49], v[48:49], v[130:131] op_sel_hi:[1,0]
	v_pk_mul_f32 v[46:47], v[46:47], v[130:131] op_sel_hi:[1,0]
	v_pk_mul_f32 v[44:45], v[44:45], v[130:131] op_sel_hi:[1,0]
	v_pk_mul_f32 v[42:43], v[42:43], v[130:131] op_sel_hi:[1,0]
	v_pk_mul_f32 v[40:41], v[40:41], v[130:131] op_sel_hi:[1,0]
	v_pk_mul_f32 v[38:39], v[38:39], v[130:131] op_sel_hi:[1,0]
	v_pk_mul_f32 v[36:37], v[36:37], v[130:131] op_sel_hi:[1,0]
	v_pk_mul_f32 v[34:35], v[34:35], v[130:131] op_sel_hi:[1,0]
	v_pk_mul_f32 v[32:33], v[32:33], v[130:131] op_sel_hi:[1,0]
	v_mul_f32_e32 v160, v160, v130
	v_pk_add_f32 v[66:67], v[66:67], v[128:129] op_sel_hi:[1,0] neg_lo:[0,1] neg_hi:[0,1]
	v_pk_add_f32 v[84:85], v[84:85], v[128:129] op_sel_hi:[1,0] neg_lo:[0,1] neg_hi:[0,1]
	v_pk_add_f32 v[68:69], v[68:69], v[128:129] op_sel_hi:[1,0] neg_lo:[0,1] neg_hi:[0,1]
	v_pk_add_f32 v[86:87], v[86:87], v[128:129] op_sel_hi:[1,0] neg_lo:[0,1] neg_hi:[0,1]
	v_pk_add_f32 v[70:71], v[70:71], v[128:129] op_sel_hi:[1,0] neg_lo:[0,1] neg_hi:[0,1]
	v_pk_add_f32 v[88:89], v[88:89], v[128:129] op_sel_hi:[1,0] neg_lo:[0,1] neg_hi:[0,1]
	v_pk_add_f32 v[72:73], v[72:73], v[128:129] op_sel_hi:[1,0] neg_lo:[0,1] neg_hi:[0,1]
	v_pk_add_f32 v[90:91], v[90:91], v[128:129] op_sel_hi:[1,0] neg_lo:[0,1] neg_hi:[0,1]
	v_pk_add_f32 v[74:75], v[74:75], v[128:129] op_sel_hi:[1,0] neg_lo:[0,1] neg_hi:[0,1]
	v_pk_add_f32 v[92:93], v[92:93], v[128:129] op_sel_hi:[1,0] neg_lo:[0,1] neg_hi:[0,1]
	v_pk_add_f32 v[76:77], v[76:77], v[128:129] op_sel_hi:[1,0] neg_lo:[0,1] neg_hi:[0,1]
	v_pk_add_f32 v[94:95], v[94:95], v[128:129] op_sel_hi:[1,0] neg_lo:[0,1] neg_hi:[0,1]
	v_pk_add_f32 v[78:79], v[78:79], v[128:129] op_sel_hi:[1,0] neg_lo:[0,1] neg_hi:[0,1]

.LBB0_974:
	s_or_b64 exec, exec, s[0:1]
	v_add_co_u32_e32 v0, vcc, 0x4000, v16
	v_mad_u32_u24 v33, v32, s22, 0
	s_nop 0
	v_addc_co_u32_e32 v1, vcc, 0, v17, vcc
	v_lshlrev_b32_e32 v244, 3, v19
	v_and_b32_e32 v91, 15, v18
	global_load_dwordx4 v[152:155], v[0:1], off
	global_load_dwordx4 v[156:159], v[0:1], off offset:256
	v_add_u32_e32 v245, v33, v192
	ds_read_b128 v[0:3], v245
	ds_read_b128 v[16:19], v245 offset:0x1200
	ds_read_b128 v[34:37], v245 offset:32
	ds_read_b128 v[38:41], v245 offset:0x1220
	ds_read_b128 v[42:45], v245 offset:64
	ds_read_b128 v[46:49], v245 offset:0x1240
	ds_read_b128 v[50:53], v245 offset:96
	ds_read_b128 v[54:57], v245 offset:0x1260
	s_waitcnt lgkmcnt(0)
	v_mul_u32_u24_e32 v246, 0x90, v32
	v_mfma_f32_32x32x16_bf16 v[0:15], v[0:3], v[140:143], 0
	v_mul_u32_u24_e32 v247, 0x88, v32
	v_lshlrev_b32_e32 v32, 3, v32
	v_sub_u32_e32 v32, v33, v32
	v_add_u32_e32 v248, v32, v244
	v_add_u32_e32 v64, 0x3400, v248
	s_movk_i32 s0, 0xffe0
	v_mfma_f32_32x32x16_bf16 v[16:31], v[16:19], v[140:143], 0
	v_mfma_f32_32x32x16_bf16 v[0:15], v[34:37], v[136:139], v[0:15]
	v_mfma_f32_32x32x16_bf16 v[16:31], v[38:41], v[136:139], v[16:31]
	v_mfma_f32_32x32x16_bf16 v[0:15], v[42:45], v[132:135], v[0:15]
	v_mfma_f32_32x32x16_bf16 v[16:31], v[46:49], v[132:135], v[16:31]
	v_mfma_f32_32x32x16_bf16 v[0:15], v[50:53], v[128:131], v[0:15]
	v_mfma_f32_32x32x16_bf16 v[16:31], v[54:57], v[128:131], v[16:31]
	ds_read_b64 v[60:61], v64
	ds_read_b64 v[62:63], v64 offset:16
	ds_read_b64 v[56:57], v64 offset:32
	ds_read_b64 v[58:59], v64 offset:48
	ds_read_b64 v[52:53], v64 offset:64
	ds_read_b64 v[54:55], v64 offset:80
	ds_read_b64 v[48:49], v64 offset:96
	ds_read_b64 v[50:51], v64 offset:112
	ds_read_b64 v[44:45], v64 offset:0x1100
	ds_read_b64 v[46:47], v64 offset:0x1110
	ds_read_b64 v[40:41], v64 offset:0x1120
	ds_read_b64 v[42:43], v64 offset:0x1130
	ds_read_b64 v[36:37], v64 offset:0x1140
	ds_read_b64 v[38:39], v64 offset:0x1150
	ds_read_b64 v[32:33], v64 offset:0x1160
	ds_read_b64 v[34:35], v64 offset:0x1170
	s_nop 10
	s_waitcnt lgkmcnt(0)
	v_max_f32_e32 v64, v0, v16
	v_max_f32_e32 v65, v1, v17
	v_max_f32_e32 v66, v3, v19
	v_max3_f32 v66, v2, v18, v66
	v_max3_f32 v64, v64, v65, v66
	v_max_f32_e32 v65, v5, v21
	v_max_f32_e32 v66, v7, v23
	v_max3_f32 v65, v4, v20, v65
	v_max3_f32 v66, v6, v22, v66
	v_max3_f32 v64, v64, v65, v66
	v_max_f32_e32 v65, v9, v25
	v_max_f32_e32 v66, v11, v27
	v_max3_f32 v65, v8, v24, v65
	v_max3_f32 v66, v10, v26, v66
	v_max3_f32 v64, v64, v65, v66
	v_max_f32_e32 v65, v13, v29
	v_max_f32_e32 v66, v15, v31
	v_max3_f32 v65, v12, v28, v65
	v_max3_f32 v66, v14, v30, v66
	v_max3_f32 v64, v64, v65, v66
	v_mov_b32_e32 v65, v64
	s_nop 1
	v_permlane32_swap_b32_e32 v64, v65
	v_max_f32_e32 v80, v64, v65
	v_sub_f32_e32 v0, v0, v80
	v_sub_f32_e32 v1, v1, v80
	v_sub_f32_e32 v16, v16, v80
	v_sub_f32_e32 v17, v17, v80
	v_exp_f32_e32 v0, v0
	v_exp_f32_e32 v1, v1
	v_sub_f32_e32 v64, v26, v80
	v_sub_f32_e32 v65, v27, v80
	v_sub_f32_e32 v26, v2, v80
	v_sub_f32_e32 v27, v3, v80
	v_exp_f32_e32 v2, v16
	v_exp_f32_e32 v3, v17
	v_sub_f32_e32 v18, v18, v80
	v_sub_f32_e32 v19, v19, v80
	v_sub_f32_e32 v68, v30, v80
	v_sub_f32_e32 v69, v31, v80
	v_sub_f32_e32 v30, v6, v80
	v_sub_f32_e32 v31, v7, v80
	v_exp_f32_e32 v6, v26
	v_exp_f32_e32 v7, v27
	v_sub_f32_e32 v66, v28, v80
	v_sub_f32_e32 v67, v29, v80
	v_sub_f32_e32 v28, v4, v80
	v_sub_f32_e32 v29, v5, v80
	v_sub_f32_e32 v70, v8, v80
	v_sub_f32_e32 v71, v9, v80
	v_exp_f32_e32 v8, v18
	v_exp_f32_e32 v9, v19
	v_sub_f32_e32 v20, v20, v80
	v_sub_f32_e32 v21, v21, v80
	v_sub_f32_e32 v72, v10, v80
	v_sub_f32_e32 v73, v11, v80
	v_pk_add_f32 v[4:5], v[0:1], 0 op_sel_hi:[1,0]
	v_exp_f32_e32 v10, v28
	v_exp_f32_e32 v11, v29
	v_sub_f32_e32 v74, v12, v80
	v_sub_f32_e32 v75, v13, v80
	v_pk_add_f32 v[4:5], v[2:3], v[4:5]
	v_exp_f32_e32 v12, v20
	v_exp_f32_e32 v13, v21
	v_sub_f32_e32 v22, v22, v80
	v_sub_f32_e32 v23, v23, v80
	v_sub_f32_e32 v81, v14, v80
	v_sub_f32_e32 v86, v15, v80
	v_pk_add_f32 v[4:5], v[6:7], v[4:5]
	v_exp_f32_e32 v14, v30
	v_exp_f32_e32 v15, v31
	v_pk_add_f32 v[4:5], v[8:9], v[4:5]
	v_exp_f32_e32 v20, v22
	v_exp_f32_e32 v21, v23
	v_sub_f32_e32 v24, v24, v80
	v_sub_f32_e32 v25, v25, v80
	v_pk_add_f32 v[4:5], v[10:11], v[4:5]
	v_exp_f32_e32 v22, v70
	v_exp_f32_e32 v23, v71
	v_pk_add_f32 v[4:5], v[12:13], v[4:5]
	v_exp_f32_e32 v24, v24
	v_exp_f32_e32 v25, v25
	v_pk_add_f32 v[4:5], v[14:15], v[4:5]
	v_exp_f32_e32 v26, v72
	v_exp_f32_e32 v27, v73
	v_pk_add_f32 v[4:5], v[20:21], v[4:5]
	v_exp_f32_e32 v28, v64
	v_exp_f32_e32 v29, v65
	v_pk_add_f32 v[4:5], v[22:23], v[4:5]
	v_exp_f32_e32 v30, v74
	v_exp_f32_e32 v31, v75
	v_pk_add_f32 v[4:5], v[24:25], v[4:5]
	v_exp_f32_e32 v70, v66
	v_exp_f32_e32 v71, v67
	v_pk_add_f32 v[4:5], v[26:27], v[4:5]
	v_exp_f32_e32 v64, v81
	v_exp_f32_e32 v65, v86
	v_pk_add_f32 v[4:5], v[28:29], v[4:5]
	v_exp_f32_e32 v92, v68
	v_exp_f32_e32 v93, v69
	v_pk_add_f32 v[4:5], v[30:31], v[4:5]
	v_cvt_pk_bf16_f32 v16, v0, v1
	v_pk_add_f32 v[4:5], v[70:71], v[4:5]
	v_cvt_pk_bf16_f32 v17, v6, v7
	v_pk_add_f32 v[4:5], v[64:65], v[4:5]
	v_cvt_pk_bf16_f32 v18, v10, v11
	v_pk_add_f32 v[4:5], v[92:93], v[4:5]
	v_cvt_pk_bf16_f32 v19, v14, v15
	v_pk_add_f32 v[86:87], v[4:5], v[4:5] op_sel_hi:[0,1]
	v_cvt_pk_bf16_f32 v75, v64, v65
	v_cvt_pk_bf16_f32 v64, v2, v3
	v_cvt_pk_bf16_f32 v65, v8, v9
	v_cvt_pk_bf16_f32 v66, v12, v13
	v_mfma_f32_32x32x16_bf16 v[0:15], v[60:63], v[16:19], 0
	v_cvt_pk_bf16_f32 v72, v22, v23
	v_cvt_pk_bf16_f32 v73, v26, v27
	v_cvt_pk_bf16_f32 v74, v30, v31
	v_cvt_pk_bf16_f32 v67, v20, v21
	v_cvt_pk_bf16_f32 v68, v24, v25
	v_cvt_pk_bf16_f32 v69, v28, v29
	v_cvt_pk_bf16_f32 v70, v70, v71
	v_mfma_f32_32x32x16_bf16 v[0:15], v[56:59], v[72:75], v[0:15]
	v_cvt_pk_bf16_f32 v71, v92, v93
	v_mov_b32_e32 v81, v87
	v_add_f32_e64 v210, v80, 0
	v_add_f32_e64 v211, v81, 0
	v_add_f32_e64 v80, -v210, neg(0)
	v_add_f32_e64 v81, -v211, neg(0)
	v_mov_b32_e32 v81, v80
	v_mfma_f32_32x32x16_bf16 v[0:15], v[52:55], v[64:67], v[0:15]
	v_mov_b32_e32 v86, v80
	v_mov_b32_e32 v87, v80
	v_mfma_f32_32x32x16_bf16 v[0:15], v[48:51], v[68:71], v[0:15]
	v_mfma_f32_32x32x16_bf16 v[48:63], v[44:47], v[16:19], 0
	v_mfma_f32_32x32x16_bf16 v[48:63], v[40:43], v[72:75], v[48:63]
	v_mfma_f32_32x32x16_bf16 v[48:63], v[36:39], v[64:67], v[48:63]
	v_add_u32_e32 v36, 0x5600, v248
	v_mfma_f32_32x32x16_bf16 v[48:63], v[32:35], v[68:71], v[48:63]
	ds_read_b64 v[32:33], v36
	ds_read_b64 v[34:35], v36 offset:16
	ds_read_b64 v[104:105], v36 offset:32
	ds_read_b64 v[106:107], v36 offset:48
	ds_read_b64 v[28:29], v36 offset:64
	ds_read_b64 v[30:31], v36 offset:80
	ds_read_b64 v[24:25], v36 offset:96
	ds_read_b64 v[26:27], v36 offset:112
	ds_read_b64 v[20:21], v36 offset:0x1100
	ds_read_b64 v[22:23], v36 offset:0x1110
	ds_read_b64 v[100:101], v36 offset:0x1120
	ds_read_b64 v[102:103], v36 offset:0x1130
	ds_read_b64 v[96:97], v36 offset:0x1140
	ds_read_b64 v[98:99], v36 offset:0x1150
	ds_read_b64 v[92:93], v36 offset:0x1160
	ds_read_b64 v[94:95], v36 offset:0x1170
	s_nop 0
	s_waitcnt lgkmcnt(0)
	s_nop 0
	v_mfma_f32_32x32x16_bf16 v[32:47], v[32:35], v[16:19], 0
	v_mfma_f32_32x32x16_bf16 v[32:47], v[104:107], v[72:75], v[32:47]
	v_mfma_f32_32x32x16_bf16 v[32:47], v[28:31], v[64:67], v[32:47]
	v_mfma_f32_32x32x16_bf16 v[32:47], v[24:27], v[68:71], v[32:47]
	v_mfma_f32_32x32x16_bf16 v[16:31], v[20:23], v[16:19], 0
	v_mfma_f32_32x32x16_bf16 v[16:31], v[100:103], v[72:75], v[16:31]
	v_mfma_f32_32x32x16_bf16 v[16:31], v[96:99], v[64:67], v[16:31]
	v_lshlrev_b32_e32 v64, 1, v90
	v_lshlrev_b32_e32 v65, 1, v91
	v_and_or_b32 v64, v64, s0, v65
	v_ashrrev_i32_e32 v65, 31, v64
	v_lshlrev_b64 v[64:65], 8, v[64:65]
	v_lshlrev_b32_e32 v66, 4, v89
	s_add_u32 s0, s21, 0x964c000
	v_mfma_f32_32x32x16_bf16 v[16:31], v[92:95], v[68:71], v[16:31]
	v_lshl_add_u64 v[64:65], s[8:9], 0, v[64:65]
	v_and_or_b32 v66, v88, s69, v66
	v_mov_b32_e32 v67, v193
	s_addc_u32 s1, s20, 0
	v_lshl_add_u64 v[204:205], v[64:65], 0, v[66:67]
	v_lshl_add_u64 v[64:65], v[82:83], 1, s[0:1]
	v_lshl_add_u64 v[206:207], v[84:85], 1, v[64:65]
	v_lshl_add_u64 v[64:65], v[76:77], 1, s[0:1]
	v_lshl_add_u64 v[208:209], v[78:79], 1, v[64:65]
	s_mov_b32 s8, 0x8000
	v_mov_b32_e32 v82, v80
	v_mov_b32_e32 v83, v80
	v_mov_b32_e32 v84, v80
	v_mov_b32_e32 v85, v80
	v_mov_b32_e32 v88, v80
	v_mov_b32_e32 v89, v80
	v_mov_b32_e32 v90, v80
	v_mov_b32_e32 v91, v80
	v_mov_b32_e32 v92, v80
	v_mov_b32_e32 v93, v80
	v_mov_b32_e32 v94, v80
	v_mov_b32_e32 v95, v80

.LBB0_979:
	s_or_b64 exec, exec, s[0:1]
	v_lshl_add_u64 v[64:65], s[4:5], 0, v[204:205]
	v_add_co_u32_e32 v64, vcc, 0xa808000, v64
	v_add3_u32 v96, s9, v246, v192
	s_nop 0
	v_addc_co_u32_e32 v65, vcc, 0, v65, vcc
	global_load_dwordx4 v[152:155], v[64:65], off
	global_load_dwordx4 v[156:159], v[64:65], off offset:256
	ds_read_b128 v[64:67], v96
	ds_read_b128 v[68:71], v96 offset:0x1200
	ds_read_b128 v[72:75], v96 offset:32
	ds_read_b128 v[76:79], v96 offset:0x1220
	ds_read_b128 v[160:163], v96 offset:64
	ds_read_b128 v[164:167], v96 offset:0x1240
	ds_read_b128 v[168:171], v96 offset:96
	ds_read_b128 v[172:175], v96 offset:0x1260
	s_waitcnt lgkmcnt(0)
	v_mov_b32_e32 v254, 0xc00
	v_mfma_f32_32x32x16_bf16 v[112:127], v[64:67], v[140:143], v[80:95]
	v_add_u32_e32 v64, s9, v247
	v_add3_u32 v249, v64, v244, s87
	v_mfma_f32_32x32x16_bf16 v[96:111], v[68:71], v[140:143], v[80:95]
	v_mfma_f32_32x32x16_bf16 v[112:127], v[72:75], v[136:139], v[112:127]
	v_mfma_f32_32x32x16_bf16 v[96:111], v[76:79], v[136:139], v[96:111]
	v_mfma_f32_32x32x16_bf16 v[112:127], v[160:163], v[132:135], v[112:127]
	v_mfma_f32_32x32x16_bf16 v[96:111], v[164:167], v[132:135], v[96:111]
	v_mfma_f32_32x32x16_bf16 v[112:127], v[168:171], v[128:131], v[112:127]
	v_mfma_f32_32x32x16_bf16 v[96:111], v[172:175], v[128:131], v[96:111]
	s_nop 10
	ds_read_b64 v[188:189], v249
	ds_read_b64 v[190:191], v249 offset:16
	ds_read_b64 v[184:185], v249 offset:32
	ds_read_b64 v[186:187], v249 offset:48
	ds_read_b64 v[180:181], v249 offset:64
	ds_read_b64 v[182:183], v249 offset:80
	ds_read_b64 v[176:177], v249 offset:96
	ds_read_b64 v[178:179], v249 offset:112
	ds_read_b64 v[172:173], v249 offset:0x1100
	ds_read_b64 v[174:175], v249 offset:0x1110
	ds_read_b64 v[168:169], v249 offset:0x1120
	ds_read_b64 v[170:171], v249 offset:0x1130
	ds_read_b64 v[164:165], v249 offset:0x1140
	ds_read_b64 v[166:167], v249 offset:0x1150
	ds_read_b64 v[160:161], v249 offset:0x1160
	ds_read_b64 v[162:163], v249 offset:0x1170
	v_max_f32_e32 v64, v112, v96
	v_max_f32_e32 v65, v113, v97
	v_max_f32_e32 v66, v115, v99
	v_max3_f32 v66, v114, v98, v66
	v_max3_f32 v64, v64, v65, v66
	v_max_f32_e32 v65, v117, v101
	v_max_f32_e32 v66, v119, v103
	v_max3_f32 v65, v116, v100, v65
	v_max3_f32 v66, v118, v102, v66
	v_max3_f32 v64, v64, v65, v66
	v_max_f32_e32 v65, v121, v105
	v_max_f32_e32 v66, v123, v107
	v_max3_f32 v65, v120, v104, v65
	v_max3_f32 v66, v122, v106, v66
	v_max3_f32 v64, v64, v65, v66
	v_max_f32_e32 v65, v125, v109
	v_max_f32_e32 v67, v127, v127
	v_max_f32_e32 v66, v67, v111
	v_max3_f32 v65, v124, v108, v65
	v_max3_f32 v66, v126, v110, v66
	v_max3_f32 v64, v64, v65, v66
	v_mov_b32_e32 v65, v64
	s_nop 1
	v_permlane32_swap_b32_e32 v64, v65
	v_max_f32_e32 v64, v64, v65
	v_cmp_lt_f32_e32 vcc, s80, v64
	s_cbranch_vccz .LBB0_981
	v_max_f32_e32 v80, 0, v64
	v_exp_f32_e64 v64, -v80
	s_nop 0
	v_mov_b32_e32 v81, v64
	v_pk_mul_f32 v[14:15], v[14:15], v[64:65] op_sel_hi:[1,0]
	v_pk_mul_f32 v[12:13], v[12:13], v[64:65] op_sel_hi:[1,0]
	v_pk_mul_f32 v[10:11], v[10:11], v[64:65] op_sel_hi:[1,0]
	v_pk_mul_f32 v[8:9], v[8:9], v[64:65] op_sel_hi:[1,0]
	v_pk_mul_f32 v[6:7], v[6:7], v[64:65] op_sel_hi:[1,0]
	v_pk_mul_f32 v[4:5], v[4:5], v[64:65] op_sel_hi:[1,0]
	v_pk_mul_f32 v[2:3], v[2:3], v[64:65] op_sel_hi:[1,0]
	v_pk_mul_f32 v[0:1], v[0:1], v[64:65] op_sel_hi:[1,0]
	v_pk_mul_f32 v[62:63], v[62:63], v[64:65] op_sel_hi:[1,0]
	v_pk_mul_f32 v[60:61], v[60:61], v[64:65] op_sel_hi:[1,0]
	v_pk_mul_f32 v[58:59], v[58:59], v[64:65] op_sel_hi:[1,0]
	v_pk_mul_f32 v[56:57], v[56:57], v[64:65] op_sel_hi:[1,0]
	v_pk_mul_f32 v[54:55], v[54:55], v[64:65] op_sel_hi:[1,0]
	v_pk_mul_f32 v[52:53], v[52:53], v[64:65] op_sel_hi:[1,0]
	v_pk_mul_f32 v[50:51], v[50:51], v[64:65] op_sel_hi:[1,0]
	v_pk_mul_f32 v[48:49], v[48:49], v[64:65] op_sel_hi:[1,0]
	v_pk_mul_f32 v[46:47], v[46:47], v[64:65] op_sel_hi:[1,0]
	v_pk_mul_f32 v[44:45], v[44:45], v[64:65] op_sel_hi:[1,0]
	v_pk_mul_f32 v[42:43], v[42:43], v[64:65] op_sel_hi:[1,0]
	v_pk_mul_f32 v[40:41], v[40:41], v[64:65] op_sel_hi:[1,0]
	v_pk_mul_f32 v[38:39], v[38:39], v[64:65] op_sel_hi:[1,0]
	v_pk_mul_f32 v[36:37], v[36:37], v[64:65] op_sel_hi:[1,0]
	v_pk_mul_f32 v[34:35], v[34:35], v[64:65] op_sel_hi:[1,0]
	v_pk_mul_f32 v[32:33], v[32:33], v[64:65] op_sel_hi:[1,0]
	v_pk_mul_f32 v[30:31], v[30:31], v[64:65] op_sel_hi:[1,0]
	v_pk_mul_f32 v[28:29], v[28:29], v[64:65] op_sel_hi:[1,0]
	v_pk_mul_f32 v[26:27], v[26:27], v[64:65] op_sel_hi:[1,0]
	v_pk_mul_f32 v[24:25], v[24:25], v[64:65] op_sel_hi:[1,0]
	v_pk_mul_f32 v[22:23], v[22:23], v[64:65] op_sel_hi:[1,0]
	v_pk_mul_f32 v[20:21], v[20:21], v[64:65] op_sel_hi:[1,0]
	v_pk_mul_f32 v[18:19], v[18:19], v[64:65] op_sel_hi:[1,0]
	v_pk_mul_f32 v[16:17], v[16:17], v[64:65] op_sel_hi:[1,0]
	v_pk_add_f32 v[212:213], v[210:211], v[80:81]
	v_pk_mul_f32 v[64:65], v[210:211], v[80:81]
	v_pk_add_f32 v[112:113], v[112:113], v[80:81] op_sel_hi:[1,0] neg_lo:[0,1] neg_hi:[0,1]
	v_mov_b32_e32 v213, v65
	v_pk_add_f32 v[64:65], v[212:213], 0 neg_lo:[1,1] neg_hi:[1,1]
	v_pk_add_f32 v[96:97], v[96:97], v[80:81] op_sel_hi:[1,0] neg_lo:[0,1] neg_hi:[0,1]
	v_pk_add_f32 v[114:115], v[114:115], v[80:81] op_sel_hi:[1,0] neg_lo:[0,1] neg_hi:[0,1]
	v_pk_add_f32 v[98:99], v[98:99], v[80:81] op_sel_hi:[1,0] neg_lo:[0,1] neg_hi:[0,1]
	v_pk_add_f32 v[116:117], v[116:117], v[80:81] op_sel_hi:[1,0] neg_lo:[0,1] neg_hi:[0,1]
	v_pk_add_f32 v[100:101], v[100:101], v[80:81] op_sel_hi:[1,0] neg_lo:[0,1] neg_hi:[0,1]
	v_pk_add_f32 v[118:119], v[118:119], v[80:81] op_sel_hi:[1,0] neg_lo:[0,1] neg_hi:[0,1]
	v_pk_add_f32 v[102:103], v[102:103], v[80:81] op_sel_hi:[1,0] neg_lo:[0,1] neg_hi:[0,1]
	v_pk_add_f32 v[120:121], v[120:121], v[80:81] op_sel_hi:[1,0] neg_lo:[0,1] neg_hi:[0,1]
	v_pk_add_f32 v[104:105], v[104:105], v[80:81] op_sel_hi:[1,0] neg_lo:[0,1] neg_hi:[0,1]
	v_pk_add_f32 v[122:123], v[122:123], v[80:81] op_sel_hi:[1,0] neg_lo:[0,1] neg_hi:[0,1]
	v_pk_add_f32 v[106:107], v[106:107], v[80:81] op_sel_hi:[1,0] neg_lo:[0,1] neg_hi:[0,1]
	v_pk_add_f32 v[124:125], v[124:125], v[80:81] op_sel_hi:[1,0] neg_lo:[0,1] neg_hi:[0,1]
	v_pk_add_f32 v[108:109], v[108:109], v[80:81] op_sel_hi:[1,0] neg_lo:[0,1] neg_hi:[0,1]
	v_mov_b32_e32 v65, v64
	v_mov_b32_e32 v66, v64
	v_mov_b32_e32 v67, v64
	v_mov_b32_e32 v68, v64
	v_mov_b32_e32 v69, v64
	v_mov_b32_e32 v70, v64
	v_mov_b32_e32 v71, v64
	v_mov_b32_e32 v72, v64
	v_mov_b32_e32 v73, v64
	v_mov_b32_e32 v74, v64
	v_mov_b32_e32 v75, v64
	v_mov_b32_e32 v76, v64
	v_mov_b32_e32 v77, v64
	v_mov_b32_e32 v78, v64
	v_mov_b32_e32 v79, v64
	v_pk_add_f32 v[126:127], v[126:127], v[80:81] op_sel_hi:[1,0] neg_lo:[0,1] neg_hi:[0,1]
	v_pk_add_f32 v[110:111], v[110:111], v[80:81] op_sel_hi:[1,0] neg_lo:[0,1] neg_hi:[0,1]
	v_mov_b32_e32 v80, v64
	v_mov_b32_e32 v81, v64
	v_mov_b32_e32 v82, v64
	v_mov_b32_e32 v83, v64
	v_mov_b32_e32 v84, v64
	v_mov_b32_e32 v85, v64
	v_mov_b32_e32 v86, v64
	v_mov_b32_e32 v87, v64
	v_mov_b32_e32 v88, v64
	v_mov_b32_e32 v89, v64
	v_mov_b32_e32 v90, v64
	v_mov_b32_e32 v91, v64
	v_mov_b32_e32 v92, v64
	v_mov_b32_e32 v93, v64
	v_mov_b32_e32 v94, v64
	v_mov_b32_e32 v95, v64
	v_mov_b32_e32 v210, v212
	s_branch .LBB0_982

.LBB0_984:
	s_waitcnt vmcnt(2)
	ds_write_b128 v240, v[148:151] offset:32768
	s_and_saveexec_b64 s[0:1], s[2:3]
	ds_write_b128 v219, v[144:147] offset:32768
	s_or_b64 exec, exec, s[0:1]
	s_waitcnt vmcnt(0)
	v_perm_b32 v80, v156, v152, s85
	v_perm_b32 v81, v156, v152, s86
	v_add_u32_e32 v82, 0xb400, v241
	ds_write2_b32 v82, v80, v81 offset1:34
	v_perm_b32 v80, v157, v153, s85
	v_perm_b32 v81, v157, v153, s86
	ds_write2_b32 v82, v80, v81 offset0:68 offset1:102
	v_perm_b32 v80, v158, v154, s85
	v_perm_b32 v81, v158, v154, s86
	ds_write2_b32 v82, v80, v81 offset0:136 offset1:170
	v_perm_b32 v80, v159, v155, s85
	v_perm_b32 v81, v159, v155, s86
	ds_write2_b32 v82, v80, v81 offset0:204 offset1:238
	v_add_u32_e32 v80, 0x8000, v245
	s_waitcnt lgkmcnt(0)
	s_barrier
	ds_read_b128 v[96:99], v80
	ds_read_b128 v[100:103], v80 offset:0x1200
	ds_read_b128 v[104:107], v80 offset:32
	ds_read_b128 v[108:111], v80 offset:0x1220
	ds_read_b128 v[112:115], v80 offset:64
	ds_read_b128 v[116:119], v80 offset:0x1240
	ds_read_b128 v[144:147], v80 offset:96
	ds_read_b128 v[120:123], v80 offset:0x1260
	s_waitcnt lgkmcnt(0)
	s_nop 0
	v_mfma_f32_32x32x16_bf16 v[80:95], v[96:99], v[140:143], v[64:79]
	v_mfma_f32_32x32x16_bf16 v[64:79], v[100:103], v[140:143], v[64:79]
	v_mfma_f32_32x32x16_bf16 v[80:95], v[104:107], v[136:139], v[80:95]
	v_mfma_f32_32x32x16_bf16 v[64:79], v[108:111], v[136:139], v[64:79]
	v_mfma_f32_32x32x16_bf16 v[80:95], v[112:115], v[132:135], v[80:95]
	v_mfma_f32_32x32x16_bf16 v[64:79], v[116:119], v[132:135], v[64:79]
	v_add_u32_e32 v132, 0xb400, v248
	v_mfma_f32_32x32x16_bf16 v[64:79], v[120:123], v[128:131], v[64:79]
	ds_read_b64 v[124:125], v132
	ds_read_b64 v[126:127], v132 offset:16
	ds_read_b64 v[120:121], v132 offset:32
	ds_read_b64 v[122:123], v132 offset:48
	ds_read_b64 v[116:117], v132 offset:64
	ds_read_b64 v[118:119], v132 offset:80
	ds_read_b64 v[112:113], v132 offset:96
	ds_read_b64 v[114:115], v132 offset:112
	ds_read_b64 v[108:109], v132 offset:0x1100
	ds_read_b64 v[110:111], v132 offset:0x1110
	ds_read_b64 v[104:105], v132 offset:0x1120
	ds_read_b64 v[106:107], v132 offset:0x1130
	ds_read_b64 v[100:101], v132 offset:0x1140
	ds_read_b64 v[102:103], v132 offset:0x1150
	ds_read_b64 v[96:97], v132 offset:0x1160
	ds_read_b64 v[98:99], v132 offset:0x1170
	v_mfma_f32_32x32x16_bf16 v[80:95], v[144:147], v[128:131], v[80:95]
	s_nop 10
	v_max_f32_e32 v133, v64, v64
	v_max_f32_e32 v129, v81, v65
	v_max_f32_e32 v130, v83, v67
	v_max_f32_e32 v128, v80, v133
	v_max3_f32 v130, v82, v66, v130
	v_max3_f32 v128, v128, v129, v130
	v_max_f32_e32 v129, v85, v69
	v_max_f32_e32 v130, v87, v71
	v_max3_f32 v129, v84, v68, v129
	v_max3_f32 v130, v86, v70, v130
	v_max3_f32 v128, v128, v129, v130
	v_max_f32_e32 v129, v89, v73
	v_max_f32_e32 v130, v91, v75
	v_max3_f32 v129, v88, v72, v129
	v_max3_f32 v130, v90, v74, v130
	v_max3_f32 v128, v128, v129, v130
	v_max_f32_e32 v129, v93, v77
	v_max_f32_e32 v131, v95, v95
	v_max_f32_e32 v130, v131, v79
	v_max3_f32 v129, v92, v76, v129
	v_max3_f32 v130, v94, v78, v130
	v_max3_f32 v128, v128, v129, v130
	v_mov_b32_e32 v129, v128
	s_nop 1
	v_permlane32_swap_b32_e32 v128, v129
	v_max_f32_e32 v128, v128, v129
	v_cmp_lt_f32_e32 vcc, s80, v128
	s_cbranch_vccz .LBB0_822
	v_max_f32_e32 v128, 0, v128
	v_exp_f32_e64 v130, -v128
	v_pk_add_f32 v[80:81], v[80:81], v[128:129] op_sel_hi:[1,0] neg_lo:[0,1] neg_hi:[0,1]
	v_pk_add_f32 v[64:65], v[64:65], v[128:129] op_sel_hi:[1,0] neg_lo:[0,1] neg_hi:[0,1]
	v_pk_add_f32 v[82:83], v[82:83], v[128:129] op_sel_hi:[1,0] neg_lo:[0,1] neg_hi:[0,1]
	v_pk_mul_f32 v[14:15], v[14:15], v[130:131] op_sel_hi:[1,0]
	v_pk_mul_f32 v[12:13], v[12:13], v[130:131] op_sel_hi:[1,0]
	v_pk_mul_f32 v[10:11], v[10:11], v[130:131] op_sel_hi:[1,0]
	v_pk_mul_f32 v[8:9], v[8:9], v[130:131] op_sel_hi:[1,0]
	v_pk_mul_f32 v[6:7], v[6:7], v[130:131] op_sel_hi:[1,0]
	v_pk_mul_f32 v[4:5], v[4:5], v[130:131] op_sel_hi:[1,0]
	v_pk_mul_f32 v[2:3], v[2:3], v[130:131] op_sel_hi:[1,0]
	v_pk_mul_f32 v[0:1], v[0:1], v[130:131] op_sel_hi:[1,0]
	v_pk_mul_f32 v[62:63], v[62:63], v[130:131] op_sel_hi:[1,0]
	v_pk_mul_f32 v[60:61], v[60:61], v[130:131] op_sel_hi:[1,0]
	v_pk_mul_f32 v[58:59], v[58:59], v[130:131] op_sel_hi:[1,0]
	v_pk_mul_f32 v[56:57], v[56:57], v[130:131] op_sel_hi:[1,0]
	v_pk_mul_f32 v[54:55], v[54:55], v[130:131] op_sel_hi:[1,0]
	v_pk_mul_f32 v[52:53], v[52:53], v[130:131] op_sel_hi:[1,0]
	v_pk_mul_f32 v[50:51], v[50:51], v[130:131] op_sel_hi:[1,0]
	v_pk_mul_f32 v[48:49], v[48:49], v[130:131] op_sel_hi:[1,0]
	v_pk_mul_f32 v[46:47], v[46:47], v[130:131] op_sel_hi:[1,0]
	v_pk_mul_f32 v[44:45], v[44:45], v[130:131] op_sel_hi:[1,0]
	v_pk_mul_f32 v[42:43], v[42:43], v[130:131] op_sel_hi:[1,0]
	v_pk_mul_f32 v[40:41], v[40:41], v[130:131] op_sel_hi:[1,0]
	v_pk_mul_f32 v[38:39], v[38:39], v[130:131] op_sel_hi:[1,0]
	v_pk_mul_f32 v[36:37], v[36:37], v[130:131] op_sel_hi:[1,0]
	v_pk_mul_f32 v[34:35], v[34:35], v[130:131] op_sel_hi:[1,0]
	v_pk_mul_f32 v[32:33], v[32:33], v[130:131] op_sel_hi:[1,0]
	v_pk_mul_f32 v[30:31], v[30:31], v[130:131] op_sel_hi:[1,0]
	v_pk_mul_f32 v[28:29], v[28:29], v[130:131] op_sel_hi:[1,0]
	v_pk_mul_f32 v[26:27], v[26:27], v[130:131] op_sel_hi:[1,0]
	v_pk_mul_f32 v[24:25], v[24:25], v[130:131] op_sel_hi:[1,0]
	v_pk_mul_f32 v[22:23], v[22:23], v[130:131] op_sel_hi:[1,0]
	v_pk_mul_f32 v[20:21], v[20:21], v[130:131] op_sel_hi:[1,0]
	v_pk_mul_f32 v[18:19], v[18:19], v[130:131] op_sel_hi:[1,0]
	v_pk_mul_f32 v[16:17], v[16:17], v[130:131] op_sel_hi:[1,0]
	v_mul_f32_e32 v160, v160, v130
	v_pk_add_f32 v[66:67], v[66:67], v[128:129] op_sel_hi:[1,0] neg_lo:[0,1] neg_hi:[0,1]
	v_pk_add_f32 v[84:85], v[84:85], v[128:129] op_sel_hi:[1,0] neg_lo:[0,1] neg_hi:[0,1]
	v_pk_add_f32 v[68:69], v[68:69], v[128:129] op_sel_hi:[1,0] neg_lo:[0,1] neg_hi:[0,1]
	v_pk_add_f32 v[86:87], v[86:87], v[128:129] op_sel_hi:[1,0] neg_lo:[0,1] neg_hi:[0,1]
	v_pk_add_f32 v[70:71], v[70:71], v[128:129] op_sel_hi:[1,0] neg_lo:[0,1] neg_hi:[0,1]
	v_pk_add_f32 v[88:89], v[88:89], v[128:129] op_sel_hi:[1,0] neg_lo:[0,1] neg_hi:[0,1]
	v_pk_add_f32 v[72:73], v[72:73], v[128:129] op_sel_hi:[1,0] neg_lo:[0,1] neg_hi:[0,1]
	v_pk_add_f32 v[90:91], v[90:91], v[128:129] op_sel_hi:[1,0] neg_lo:[0,1] neg_hi:[0,1]
	v_pk_add_f32 v[74:75], v[74:75], v[128:129] op_sel_hi:[1,0] neg_lo:[0,1] neg_hi:[0,1]
	v_pk_add_f32 v[92:93], v[92:93], v[128:129] op_sel_hi:[1,0] neg_lo:[0,1] neg_hi:[0,1]
	v_pk_add_f32 v[76:77], v[76:77], v[128:129] op_sel_hi:[1,0] neg_lo:[0,1] neg_hi:[0,1]
	v_pk_add_f32 v[94:95], v[94:95], v[128:129] op_sel_hi:[1,0] neg_lo:[0,1] neg_hi:[0,1]
	v_pk_add_f32 v[78:79], v[78:79], v[128:129] op_sel_hi:[1,0] neg_lo:[0,1] neg_hi:[0,1]
	s_branch .LBB0_822
